# MFMA order: Gray-code walk over (n,m,k) in every 16-MFMA block of all GEMM K-loops
# speedup vs baseline: 1.0054x; 1.0054x over previous
; #define PG8_STAGE(bufoff, gbase, voff) do { _Pragma("unroll") for (int _i = 0; _i < 2; ++_i) \
;         __builtin_amdgcn_global_load_lds((const unsigned*)((const char*)(gbase) + (voff)[_i]), (PG8_LAS unsigned*)(lds + (bufoff) + ldsw + _i * 8192), 16, 0, 0); } while (0)
; #define PG8_LDA(dst, b, h) do { _Pragma("unroll") for (int m = 0; m < 4; ++m) _Pragma("unroll") for (int k = 0; k < 2; ++k) dst[m][k] = *(const PG8_LAS bf16x8*)(lds + PG8_SA(b, h) + aoff + m * 2048 + k * 1024); } while (0)
; #define PG8_LDB(dst, b, h) do { _Pragma("unroll") for (int n = 0; n < 2; ++n) _Pragma("unroll") for (int k = 0; k < 2; ++k) dst[n][k] = *(const PG8_LAS bf16x8*)(lds + PG8_SB(b, h) + boff + n * 2048 + k * 1024); } while (0)
; #define PG8_MMA(ai, bj, At, Bt) do { __builtin_amdgcn_s_setprio(1); _Pragma("unroll") for (int m = 0; m < 4; ++m) _Pragma("unroll") for (int n = 0; n < 2; ++n) _Pragma("unroll") for (int k = 0; k < 2; ++k) \
;         acc[ai][bj][m][n] = mma16(Bt[n][k], At[m][k], acc[ai][bj][m][n]); __builtin_amdgcn_s_setprio(0); } while (0)
; #define PG8_WAIT_V(n) asm volatile("s_waitcnt vmcnt(" #n ")" ::: "memory")
; #define PG8_WAIT_L(n) asm volatile("s_waitcnt lgkmcnt(" #n ")" ::: "memory")
; template <class Epi, class Sched, bool ALIGN_EPI = false, bool SP2 = false>
; __device__ __forceinline__ void gemm_phase(PG8_LAS unsigned char* lds, const Gemm g, const Sched& S, const Epi& E) {
;     ...
;         for (int t = 0; t < nt; t += 2) {
;             const bool last = (t == nt - 2);
;             const char* a1 = cA + (size_t)(t + 1) * kstep;
;             const char* a2 = last ? nA : cA + (size_t)(t + 2) * kstep; const char* b2 = last ? nB : cB + (size_t)(t + 2) * kstep;
;             const char* a3 = a2 + kstep; const char* b3 = b2 + kstep;
;             if (last && has_next) S.a_ready(nxt);
;             if constexpr (SP2) {
;             PG8_LDB(B0, 0, 0); PG8_LDB(B1, 0, 1); PG8_SCHED; PG8_LDA(At, 0, 0); PG8_STAGE(PG8_SA(1, 1), a1 + hstepA, voffA);
;             PG8_WAIT_V(8); PG8_WAIT_L(0); PG8_BAR; PG8_MMA(0, 0, At, B0); PG8_MMA(0, 1, At, B1); PG8_BAR; PG8_SCHED;
;             PG8_LDA(At, 0, 1); PG8_STAGE(PG8_SB(0, 0), b2, voffB); PG8_STAGE(PG8_SB(0, 1), b2 + hstepB, voffB); PG8_STAGE(PG8_SA(0, 0), a2, voffA);
;             PG8_WAIT_V(8); PG8_WAIT_L(0); PG8_BAR; PG8_MMA(1, 0, At, B0); PG8_MMA(1, 1, At, B1); PG8_BAR; PG8_SCHED;
.LBB0_231:
	ds_read_b128 v[146:149], v158
	ds_read_b128 v[162:165], v158 offset:1024
	ds_read_b128 v[182:185], v158 offset:2048
	ds_read_b128 v[186:189], v158 offset:3072
	ds_read_b128 v[190:193], v159
	ds_read_b128 v[194:197], v159 offset:1024
	ds_read_b128 v[198:201], v159 offset:2048
	ds_read_b128 v[202:205], v159 offset:3072
	s_add_u32 s45, s0, 0xfff00080
	s_addc_u32 s46, s1, -1
	s_cmp_eq_u32 s37, 60
	s_cselect_b32 s67, s55, s46
	s_cselect_b32 s66, s54, s45
	s_cselect_b32 s65, s29, s36
	s_cselect_b32 s64, s33, s35
	v_lshl_add_u64 v[166:167], s[0:1], 0, v[138:139]
	s_add_i32 m0, s13, 0xc000
	ds_read_b128 v[206:209], v160
	ds_read_b128 v[212:215], v160 offset:1024
	ds_read_b128 v[216:219], v160 offset:2048
	ds_read_b128 v[220:223], v160 offset:3072
	ds_read_b128 v[224:227], v160 offset:4096
	ds_read_b128 v[228:231], v160 offset:5120
	ds_read_b128 v[232:235], v160 offset:6144
	ds_read_b128 v[236:239], v160 offset:7168
	global_load_lds_dwordx4 v[166:167], off
	v_lshl_add_u64 v[166:167], s[0:1], 0, v[140:141]
	s_add_i32 m0, s13, 0xe000
	s_nop 0
	global_load_lds_dwordx4 v[166:167], off
	s_waitcnt vmcnt(8)
	s_waitcnt lgkmcnt(0)
	s_barrier
	s_setprio 1
	s_waitcnt lgkmcnt(0)
	v_mfma_f32_16x16x32_bf16 v[126:129], v[146:149], v[206:209], v[126:129]
	v_mfma_f32_16x16x32_bf16 v[126:129], v[162:165], v[212:215], v[126:129]
	v_mfma_f32_16x16x32_bf16 v[122:125], v[186:189], v[212:215], v[122:125]
	v_mfma_f32_16x16x32_bf16 v[122:125], v[182:185], v[206:209], v[122:125]
	v_mfma_f32_16x16x32_bf16 v[110:113], v[182:185], v[216:219], v[110:113]
	v_mfma_f32_16x16x32_bf16 v[110:113], v[186:189], v[220:223], v[110:113]
	v_mfma_f32_16x16x32_bf16 v[118:121], v[162:165], v[220:223], v[118:121]
	v_mfma_f32_16x16x32_bf16 v[118:121], v[146:149], v[216:219], v[118:121]
	v_mfma_f32_16x16x32_bf16 v[102:105], v[146:149], v[224:227], v[102:105]
	v_mfma_f32_16x16x32_bf16 v[102:105], v[162:165], v[228:231], v[102:105]
	v_mfma_f32_16x16x32_bf16 v[94:97], v[186:189], v[228:231], v[94:97]
	v_mfma_f32_16x16x32_bf16 v[94:97], v[182:185], v[224:227], v[94:97]
	v_mfma_f32_16x16x32_bf16 v[78:81], v[182:185], v[232:235], v[78:81]
	v_mfma_f32_16x16x32_bf16 v[78:81], v[186:189], v[236:239], v[78:81]
	v_mfma_f32_16x16x32_bf16 v[86:89], v[162:165], v[236:239], v[86:89]
	v_mfma_f32_16x16x32_bf16 v[86:89], v[146:149], v[232:235], v[86:89]
	s_setprio 0
	s_setprio 1
	v_mfma_f32_16x16x32_bf16 v[114:117], v[190:193], v[206:209], v[114:117]
	v_mfma_f32_16x16x32_bf16 v[114:117], v[194:197], v[212:215], v[114:117]
	v_mfma_f32_16x16x32_bf16 v[106:109], v[202:205], v[212:215], v[106:109]
	v_mfma_f32_16x16x32_bf16 v[106:109], v[198:201], v[206:209], v[106:109]
	v_mfma_f32_16x16x32_bf16 v[90:93], v[198:201], v[216:219], v[90:93]
	v_mfma_f32_16x16x32_bf16 v[90:93], v[202:205], v[220:223], v[90:93]
	v_mfma_f32_16x16x32_bf16 v[98:101], v[194:197], v[220:223], v[98:101]
	v_mfma_f32_16x16x32_bf16 v[98:101], v[190:193], v[216:219], v[98:101]
	v_mfma_f32_16x16x32_bf16 v[82:85], v[190:193], v[224:227], v[82:85]
	v_mfma_f32_16x16x32_bf16 v[82:85], v[194:197], v[228:231], v[82:85]
	v_mfma_f32_16x16x32_bf16 v[74:77], v[202:205], v[228:231], v[74:77]
	v_mfma_f32_16x16x32_bf16 v[74:77], v[198:201], v[224:227], v[74:77]
	v_mfma_f32_16x16x32_bf16 v[66:69], v[198:201], v[232:235], v[66:69]
	v_mfma_f32_16x16x32_bf16 v[66:69], v[202:205], v[236:239], v[66:69]
	v_mfma_f32_16x16x32_bf16 v[70:73], v[194:197], v[236:239], v[70:73]
	v_mfma_f32_16x16x32_bf16 v[70:73], v[190:193], v[232:235], v[70:73]
	s_setprio 0
	s_barrier
	s_add_i32 s45, s26, s12
	v_lshl_add_u64 v[166:167], s[64:65], 0, v[132:133]
	s_mov_b32 m0, s45
	ds_read_b128 v[206:209], v160 offset:16384
	ds_read_b128 v[212:215], v160 offset:17408
	ds_read_b128 v[216:219], v160 offset:18432
	ds_read_b128 v[220:223], v160 offset:19456
	ds_read_b128 v[224:227], v160 offset:20480
	ds_read_b128 v[228:231], v160 offset:21504
	ds_read_b128 v[232:235], v160 offset:22528
	ds_read_b128 v[236:239], v160 offset:23552
	global_load_lds_dwordx4 v[166:167], off
	s_add_i32 m0, s45, 0x2000
	s_add_u32 s46, s64, 0x100000
	v_lshl_add_u64 v[176:177], s[64:65], 0, v[136:137]
	s_addc_u32 s47, s65, 0
	s_add_i32 s45, s27, s12
	global_load_lds_dwordx4 v[176:177], off
	v_lshl_add_u64 v[240:241], s[46:47], 0, v[132:133]
	s_mov_b32 m0, s45
	v_lshl_add_u64 v[242:243], s[66:67], 0, v[134:135]
	global_load_lds_dwordx4 v[240:241], off
	v_lshl_add_u64 v[240:241], s[46:47], 0, v[136:137]
	s_add_i32 m0, s45, 0x2000
	s_nop 0
	global_load_lds_dwordx4 v[240:241], off
	v_lshl_add_u64 v[240:241], s[66:67], 0, v[130:131]
	s_mov_b32 m0, s13
	s_nop 0
	global_load_lds_dwordx4 v[240:241], off
	s_mov_b32 m0, s18
	s_nop 0
	global_load_lds_dwordx4 v[242:243], off
	s_waitcnt vmcnt(8)
	s_waitcnt lgkmcnt(0)
	s_barrier
; #define PG8_STAGE(bufoff, gbase, voff) do { _Pragma("unroll") for (int _i = 0; _i < 2; ++_i) \
;         __builtin_amdgcn_global_load_lds((const unsigned*)((const char*)(gbase) + (voff)[_i]), (PG8_LAS unsigned*)(lds + (bufoff) + ldsw + _i * 8192), 16, 0, 0); } while (0)
; #define PG8_LDA(dst, b, h) do { _Pragma("unroll") for (int m = 0; m < 4; ++m) _Pragma("unroll") for (int k = 0; k < 2; ++k) dst[m][k] = *(const PG8_LAS bf16x8*)(lds + PG8_SA(b, h) + aoff + m * 2048 + k * 1024); } while (0)
; #define PG8_LDB(dst, b, h) do { _Pragma("unroll") for (int n = 0; n < 2; ++n) _Pragma("unroll") for (int k = 0; k < 2; ++k) dst[n][k] = *(const PG8_LAS bf16x8*)(lds + PG8_SB(b, h) + boff + n * 2048 + k * 1024); } while (0)
; #define PG8_MMA(ai, bj, At, Bt) do { __builtin_amdgcn_s_setprio(1); _Pragma("unroll") for (int m = 0; m < 4; ++m) _Pragma("unroll") for (int n = 0; n < 2; ++n) _Pragma("unroll") for (int k = 0; k < 2; ++k) \
;         acc[ai][bj][m][n] = mma16(Bt[n][k], At[m][k], acc[ai][bj][m][n]); __builtin_amdgcn_s_setprio(0); } while (0)
; #define PG8_WAIT_V(n) asm volatile("s_waitcnt vmcnt(" #n ")" ::: "memory")
; #define PG8_WAIT_L(n) asm volatile("s_waitcnt lgkmcnt(" #n ")" ::: "memory")
; #define PG8_BAR __builtin_amdgcn_s_barrier()
; #define PG8_SCHED __builtin_amdgcn_sched_barrier(0)
; template <class Epi, class Sched, bool ALIGN_EPI = false, bool SP2 = false>
; __device__ __forceinline__ void gemm_phase(PG8_LAS unsigned char* lds, const Gemm g, const Sched& S, const Epi& E) {
;     ...
;             PG8_WAIT_V(8); PG8_WAIT_L(0); PG8_BAR; PG8_MMA(1, 0, At, B0); PG8_MMA(1, 1, At, B1); PG8_BAR; PG8_SCHED;
;             PG8_LDB(B0, 1, 0); PG8_LDB(B1, 1, 1); PG8_SCHED; PG8_LDA(At, 1, 0); PG8_STAGE(PG8_SA(0, 1), a2 + hstepA, voffA);
;             PG8_WAIT_V(8); PG8_WAIT_L(0); PG8_BAR; PG8_MMA(0, 0, At, B0); PG8_MMA(0, 1, At, B1); PG8_BAR; PG8_SCHED;
	s_setprio 1
	s_waitcnt lgkmcnt(0)
	v_mfma_f32_16x16x32_bf16 v[62:65], v[146:149], v[206:209], v[62:65]
	v_mfma_f32_16x16x32_bf16 v[62:65], v[162:165], v[212:215], v[62:65]
	v_mfma_f32_16x16x32_bf16 v[58:61], v[186:189], v[212:215], v[58:61]
	v_mfma_f32_16x16x32_bf16 v[58:61], v[182:185], v[206:209], v[58:61]
	v_mfma_f32_16x16x32_bf16 v[46:49], v[182:185], v[216:219], v[46:49]
	v_mfma_f32_16x16x32_bf16 v[46:49], v[186:189], v[220:223], v[46:49]
	v_mfma_f32_16x16x32_bf16 v[54:57], v[162:165], v[220:223], v[54:57]
	v_mfma_f32_16x16x32_bf16 v[54:57], v[146:149], v[216:219], v[54:57]
	v_mfma_f32_16x16x32_bf16 v[38:41], v[146:149], v[224:227], v[38:41]
	v_mfma_f32_16x16x32_bf16 v[38:41], v[162:165], v[228:231], v[38:41]
	v_mfma_f32_16x16x32_bf16 v[30:33], v[186:189], v[228:231], v[30:33]
	v_mfma_f32_16x16x32_bf16 v[30:33], v[182:185], v[224:227], v[30:33]
	v_mfma_f32_16x16x32_bf16 v[14:17], v[182:185], v[232:235], v[14:17]
	v_mfma_f32_16x16x32_bf16 v[14:17], v[186:189], v[236:239], v[14:17]
	v_mfma_f32_16x16x32_bf16 v[22:25], v[162:165], v[236:239], v[22:25]
	v_mfma_f32_16x16x32_bf16 v[22:25], v[146:149], v[232:235], v[22:25]
	s_setprio 0
	s_setprio 1
	v_mfma_f32_16x16x32_bf16 v[50:53], v[190:193], v[206:209], v[50:53]
	v_mfma_f32_16x16x32_bf16 v[50:53], v[194:197], v[212:215], v[50:53]
	v_mfma_f32_16x16x32_bf16 v[42:45], v[202:205], v[212:215], v[42:45]
	v_mfma_f32_16x16x32_bf16 v[42:45], v[198:201], v[206:209], v[42:45]
	v_mfma_f32_16x16x32_bf16 v[26:29], v[198:201], v[216:219], v[26:29]
	v_mfma_f32_16x16x32_bf16 v[26:29], v[202:205], v[220:223], v[26:29]
	v_mfma_f32_16x16x32_bf16 v[34:37], v[194:197], v[220:223], v[34:37]
	v_mfma_f32_16x16x32_bf16 v[34:37], v[190:193], v[216:219], v[34:37]
	v_mfma_f32_16x16x32_bf16 v[18:21], v[190:193], v[224:227], v[18:21]
	v_mfma_f32_16x16x32_bf16 v[18:21], v[194:197], v[228:231], v[18:21]
	v_mfma_f32_16x16x32_bf16 v[10:13], v[202:205], v[228:231], v[10:13]
	v_mfma_f32_16x16x32_bf16 v[10:13], v[198:201], v[224:227], v[10:13]
	v_mfma_f32_16x16x32_bf16 v[2:5], v[198:201], v[232:235], v[2:5]
	v_mfma_f32_16x16x32_bf16 v[2:5], v[202:205], v[236:239], v[2:5]
	v_mfma_f32_16x16x32_bf16 v[6:9], v[194:197], v[236:239], v[6:9]
	v_mfma_f32_16x16x32_bf16 v[6:9], v[190:193], v[232:235], v[6:9]
	s_setprio 0
	s_barrier
	s_add_i32 s45, 0, 0x18000
	v_add_u32_e32 v161, s45, v156
	s_add_i32 s49, 0, 0x1c000
	ds_read_b128 v[146:149], v161
	ds_read_b128 v[162:165], v161 offset:1024
	ds_read_b128 v[182:185], v161 offset:2048
	ds_read_b128 v[186:189], v161 offset:3072
	v_add_u32_e32 v161, s49, v156
	ds_read_b128 v[190:193], v161
	ds_read_b128 v[194:197], v161 offset:1024
	ds_read_b128 v[198:201], v161 offset:2048
	ds_read_b128 v[202:205], v161 offset:3072
	s_add_u32 s46, s66, 0x100000
	s_addc_u32 s47, s67, 0
	s_mov_b32 m0, s19
	v_lshl_add_u64 v[244:245], s[46:47], 0, v[130:131]
	ds_read_b128 v[206:209], v160 offset:32768
	ds_read_b128 v[212:215], v160 offset:33792
	ds_read_b128 v[216:219], v160 offset:34816
	ds_read_b128 v[220:223], v160 offset:35840
	ds_read_b128 v[224:227], v160 offset:36864
	ds_read_b128 v[228:231], v160 offset:37888
	ds_read_b128 v[232:235], v160 offset:38912
	ds_read_b128 v[236:239], v160 offset:39936
	global_load_lds_dwordx4 v[244:245], off
	v_lshl_add_u64 v[244:245], s[46:47], 0, v[134:135]
	s_mov_b32 m0, s20
	s_nop 0
	global_load_lds_dwordx4 v[244:245], off
	s_waitcnt vmcnt(8)
	s_waitcnt lgkmcnt(0)
	s_barrier
	s_setprio 1
	s_waitcnt lgkmcnt(0)
	v_mfma_f32_16x16x32_bf16 v[126:129], v[146:149], v[206:209], v[126:129]
	v_mfma_f32_16x16x32_bf16 v[126:129], v[162:165], v[212:215], v[126:129]
	v_mfma_f32_16x16x32_bf16 v[122:125], v[186:189], v[212:215], v[122:125]
	v_mfma_f32_16x16x32_bf16 v[122:125], v[182:185], v[206:209], v[122:125]
	v_mfma_f32_16x16x32_bf16 v[110:113], v[182:185], v[216:219], v[110:113]
	v_mfma_f32_16x16x32_bf16 v[110:113], v[186:189], v[220:223], v[110:113]
	v_mfma_f32_16x16x32_bf16 v[118:121], v[162:165], v[220:223], v[118:121]
	v_mfma_f32_16x16x32_bf16 v[118:121], v[146:149], v[216:219], v[118:121]
	v_mfma_f32_16x16x32_bf16 v[102:105], v[146:149], v[224:227], v[102:105]
	v_mfma_f32_16x16x32_bf16 v[102:105], v[162:165], v[228:231], v[102:105]
	v_mfma_f32_16x16x32_bf16 v[94:97], v[186:189], v[228:231], v[94:97]
	v_mfma_f32_16x16x32_bf16 v[94:97], v[182:185], v[224:227], v[94:97]
	v_mfma_f32_16x16x32_bf16 v[78:81], v[182:185], v[232:235], v[78:81]
	v_mfma_f32_16x16x32_bf16 v[78:81], v[186:189], v[236:239], v[78:81]
	v_mfma_f32_16x16x32_bf16 v[86:89], v[162:165], v[236:239], v[86:89]
	v_mfma_f32_16x16x32_bf16 v[86:89], v[146:149], v[232:235], v[86:89]
	s_setprio 0
	s_setprio 1
	v_mfma_f32_16x16x32_bf16 v[114:117], v[190:193], v[206:209], v[114:117]
	v_mfma_f32_16x16x32_bf16 v[114:117], v[194:197], v[212:215], v[114:117]
	v_mfma_f32_16x16x32_bf16 v[106:109], v[202:205], v[212:215], v[106:109]
	v_mfma_f32_16x16x32_bf16 v[106:109], v[198:201], v[206:209], v[106:109]
	v_mfma_f32_16x16x32_bf16 v[90:93], v[198:201], v[216:219], v[90:93]
	v_mfma_f32_16x16x32_bf16 v[90:93], v[202:205], v[220:223], v[90:93]
	v_mfma_f32_16x16x32_bf16 v[98:101], v[194:197], v[220:223], v[98:101]
	v_mfma_f32_16x16x32_bf16 v[98:101], v[190:193], v[216:219], v[98:101]
	v_mfma_f32_16x16x32_bf16 v[82:85], v[190:193], v[224:227], v[82:85]
	v_mfma_f32_16x16x32_bf16 v[82:85], v[194:197], v[228:231], v[82:85]
	v_mfma_f32_16x16x32_bf16 v[74:77], v[202:205], v[228:231], v[74:77]
	v_mfma_f32_16x16x32_bf16 v[74:77], v[198:201], v[224:227], v[74:77]
	v_mfma_f32_16x16x32_bf16 v[66:69], v[198:201], v[232:235], v[66:69]
	v_mfma_f32_16x16x32_bf16 v[66:69], v[202:205], v[236:239], v[66:69]
	v_mfma_f32_16x16x32_bf16 v[70:73], v[194:197], v[236:239], v[70:73]
	v_mfma_f32_16x16x32_bf16 v[70:73], v[190:193], v[232:235], v[70:73]
	s_setprio 0
	s_barrier
; #define PG8_STAGE(bufoff, gbase, voff) do { _Pragma("unroll") for (int _i = 0; _i < 2; ++_i) \
;         __builtin_amdgcn_global_load_lds((const unsigned*)((const char*)(gbase) + (voff)[_i]), (PG8_LAS unsigned*)(lds + (bufoff) + ldsw + _i * 8192), 16, 0, 0); } while (0)
; #define PG8_LDA(dst, b, h) do { _Pragma("unroll") for (int m = 0; m < 4; ++m) _Pragma("unroll") for (int k = 0; k < 2; ++k) dst[m][k] = *(const PG8_LAS bf16x8*)(lds + PG8_SA(b, h) + aoff + m * 2048 + k * 1024); } while (0)
; #define PG8_MMA(ai, bj, At, Bt) do { __builtin_amdgcn_s_setprio(1); _Pragma("unroll") for (int m = 0; m < 4; ++m) _Pragma("unroll") for (int n = 0; n < 2; ++n) _Pragma("unroll") for (int k = 0; k < 2; ++k) \
;         acc[ai][bj][m][n] = mma16(Bt[n][k], At[m][k], acc[ai][bj][m][n]); __builtin_amdgcn_s_setprio(0); } while (0)
; #define PG8_WAIT_V(n) asm volatile("s_waitcnt vmcnt(" #n ")" ::: "memory")
; #define PG8_WAIT_L(n) asm volatile("s_waitcnt lgkmcnt(" #n ")" ::: "memory")
; #define PG8_BAR __builtin_amdgcn_s_barrier()
; #define PG8_SCHED __builtin_amdgcn_sched_barrier(0)
; template <class Epi, class Sched, bool ALIGN_EPI = false, bool SP2 = false>
; __device__ __forceinline__ void gemm_phase(PG8_LAS unsigned char* lds, const Gemm g, const Sched& S, const Epi& E) {
;     ...
;         for (int t = 0; t < nt; t += 2) {
;     ...
;             PG8_LDA(At, 1, 1); PG8_STAGE(PG8_SB(1, 0), b3, voffB); PG8_STAGE(PG8_SB(1, 1), b3 + hstepB, voffB); PG8_STAGE(PG8_SA(1, 0), a3, voffA);
;             PG8_WAIT_V(8); PG8_WAIT_L(0); PG8_BAR; PG8_MMA(1, 0, At, B0); PG8_MMA(1, 1, At, B1); PG8_BAR; PG8_SCHED;
;     ...
;         if constexpr (ALIGN_EPI) { if (wr == 0) PG8_BAR; }
	s_add_i32 s45, s45, s12
	v_lshl_add_u64 v[166:167], v[166:167], 0, s[40:41]
	s_mov_b32 m0, s45
	ds_read_b128 v[206:209], v160 offset:49152
	ds_read_b128 v[212:215], v160 offset:50176
	ds_read_b128 v[216:219], v160 offset:51200
	ds_read_b128 v[220:223], v160 offset:52224
	ds_read_b128 v[224:227], v160 offset:53248
	ds_read_b128 v[228:231], v160 offset:54272
	ds_read_b128 v[232:235], v160 offset:55296
	ds_read_b128 v[236:239], v160 offset:56320
	global_load_lds_dwordx4 v[166:167], off
	s_add_i32 m0, s45, 0x2000
	s_add_u32 s46, s64, 0x100080
	v_lshl_add_u64 v[166:167], v[176:177], 0, s[40:41]
	s_addc_u32 s47, s65, 0
	s_add_i32 s45, s49, s12
	global_load_lds_dwordx4 v[166:167], off
	v_lshl_add_u64 v[166:167], s[46:47], 0, v[132:133]
	s_mov_b32 m0, s45
	s_nop 0
	global_load_lds_dwordx4 v[166:167], off
	v_lshl_add_u64 v[166:167], s[46:47], 0, v[136:137]
	s_add_i32 m0, s45, 0x2000
	s_nop 0
	global_load_lds_dwordx4 v[166:167], off
	v_lshl_add_u64 v[166:167], v[240:241], 0, s[40:41]
	s_mov_b32 m0, s22
	s_nop 0
	global_load_lds_dwordx4 v[166:167], off
	v_lshl_add_u64 v[166:167], v[242:243], 0, s[40:41]
	s_mov_b32 m0, s23
	s_nop 0
	global_load_lds_dwordx4 v[166:167], off
	s_waitcnt vmcnt(8)
	s_waitcnt lgkmcnt(0)
	s_barrier
	s_setprio 1
	s_waitcnt lgkmcnt(0)
	v_mfma_f32_16x16x32_bf16 v[62:65], v[146:149], v[206:209], v[62:65]
	v_mfma_f32_16x16x32_bf16 v[62:65], v[162:165], v[212:215], v[62:65]
	v_mfma_f32_16x16x32_bf16 v[58:61], v[186:189], v[212:215], v[58:61]
	v_mfma_f32_16x16x32_bf16 v[58:61], v[182:185], v[206:209], v[58:61]
	v_mfma_f32_16x16x32_bf16 v[46:49], v[182:185], v[216:219], v[46:49]
	v_mfma_f32_16x16x32_bf16 v[46:49], v[186:189], v[220:223], v[46:49]
	v_mfma_f32_16x16x32_bf16 v[54:57], v[162:165], v[220:223], v[54:57]
	v_mfma_f32_16x16x32_bf16 v[54:57], v[146:149], v[216:219], v[54:57]
	v_mfma_f32_16x16x32_bf16 v[38:41], v[146:149], v[224:227], v[38:41]
	v_mfma_f32_16x16x32_bf16 v[38:41], v[162:165], v[228:231], v[38:41]
	v_mfma_f32_16x16x32_bf16 v[30:33], v[186:189], v[228:231], v[30:33]
	v_mfma_f32_16x16x32_bf16 v[30:33], v[182:185], v[224:227], v[30:33]
	v_mfma_f32_16x16x32_bf16 v[14:17], v[182:185], v[232:235], v[14:17]
	v_mfma_f32_16x16x32_bf16 v[14:17], v[186:189], v[236:239], v[14:17]
	v_mfma_f32_16x16x32_bf16 v[22:25], v[162:165], v[236:239], v[22:25]
	v_mfma_f32_16x16x32_bf16 v[22:25], v[146:149], v[232:235], v[22:25]
	s_setprio 0
	s_setprio 1
	v_mfma_f32_16x16x32_bf16 v[50:53], v[190:193], v[206:209], v[50:53]
	v_mfma_f32_16x16x32_bf16 v[50:53], v[194:197], v[212:215], v[50:53]
	v_mfma_f32_16x16x32_bf16 v[42:45], v[202:205], v[212:215], v[42:45]
	v_mfma_f32_16x16x32_bf16 v[42:45], v[198:201], v[206:209], v[42:45]
	v_mfma_f32_16x16x32_bf16 v[26:29], v[198:201], v[216:219], v[26:29]
	v_mfma_f32_16x16x32_bf16 v[26:29], v[202:205], v[220:223], v[26:29]
	v_mfma_f32_16x16x32_bf16 v[34:37], v[194:197], v[220:223], v[34:37]
	v_mfma_f32_16x16x32_bf16 v[34:37], v[190:193], v[216:219], v[34:37]
	v_mfma_f32_16x16x32_bf16 v[18:21], v[190:193], v[224:227], v[18:21]
	v_mfma_f32_16x16x32_bf16 v[18:21], v[194:197], v[228:231], v[18:21]
	v_mfma_f32_16x16x32_bf16 v[10:13], v[202:205], v[228:231], v[10:13]
	v_mfma_f32_16x16x32_bf16 v[10:13], v[198:201], v[224:227], v[10:13]
	v_mfma_f32_16x16x32_bf16 v[2:5], v[198:201], v[232:235], v[2:5]
	v_mfma_f32_16x16x32_bf16 v[2:5], v[202:205], v[236:239], v[2:5]
	v_mfma_f32_16x16x32_bf16 v[6:9], v[194:197], v[236:239], v[6:9]
	v_mfma_f32_16x16x32_bf16 v[6:9], v[190:193], v[232:235], v[6:9]
	s_setprio 0
	s_barrier
	s_add_i32 s37, s37, 2
	s_add_u32 s0, s0, 0x100
	s_addc_u32 s1, s1, 0
	s_add_u32 s35, s35, 0x100
	s_addc_u32 s36, s36, 0
	s_cmp_gt_u32 s37, 61
	s_cbranch_scc0 .LBB0_231
	s_and_b64 vcc, exec, s[42:43]
	s_cbranch_vccz .LBB0_234
	s_barrier

; #define PG8_STAGE(bufoff, gbase, voff) do { _Pragma("unroll") for (int _i = 0; _i < 2; ++_i) \
;         __builtin_amdgcn_global_load_lds((const unsigned*)((const char*)(gbase) + (voff)[_i]), (PG8_LAS unsigned*)(lds + (bufoff) + ldsw + _i * 8192), 16, 0, 0); } while (0)
; #define PG8_LDA(dst, b, h) do { _Pragma("unroll") for (int m = 0; m < 4; ++m) _Pragma("unroll") for (int k = 0; k < 2; ++k) dst[m][k] = *(const PG8_LAS bf16x8*)(lds + PG8_SA(b, h) + aoff + m * 2048 + k * 1024); } while (0)
; #define PG8_LDB(dst, b, h) do { _Pragma("unroll") for (int n = 0; n < 2; ++n) _Pragma("unroll") for (int k = 0; k < 2; ++k) dst[n][k] = *(const PG8_LAS bf16x8*)(lds + PG8_SB(b, h) + boff + n * 2048 + k * 1024); } while (0)
; #define PG8_MMA(ai, bj, At, Bt) do { __builtin_amdgcn_s_setprio(1); _Pragma("unroll") for (int m = 0; m < 4; ++m) _Pragma("unroll") for (int n = 0; n < 2; ++n) _Pragma("unroll") for (int k = 0; k < 2; ++k) \
;         acc[ai][bj][m][n] = mma16(Bt[n][k], At[m][k], acc[ai][bj][m][n]); __builtin_amdgcn_s_setprio(0); } while (0)
; #define PG8_WAIT_V(n) asm volatile("s_waitcnt vmcnt(" #n ")" ::: "memory")
; #define PG8_WAIT_L(n) asm volatile("s_waitcnt lgkmcnt(" #n ")" ::: "memory")
; template <class Epi, class Sched, bool ALIGN_EPI = false, bool SP2 = false>
; __device__ __forceinline__ void gemm_phase(PG8_LAS unsigned char* lds, const Gemm g, const Sched& S, const Epi& E) {
;     ...
;         for (int t = 0; t < nt; t += 2) {
;             const bool last = (t == nt - 2);
;             const char* a1 = cA + (size_t)(t + 1) * kstep;
;             const char* a2 = last ? nA : cA + (size_t)(t + 2) * kstep; const char* b2 = last ? nB : cB + (size_t)(t + 2) * kstep;
;             const char* a3 = a2 + kstep; const char* b3 = b2 + kstep;
;             if (last && has_next) S.a_ready(nxt);
;             if constexpr (SP2) {
;             PG8_LDB(B0, 0, 0); PG8_LDB(B1, 0, 1); PG8_SCHED; PG8_LDA(At, 0, 0); PG8_STAGE(PG8_SA(1, 1), a1 + hstepA, voffA);
;             PG8_WAIT_V(8); PG8_WAIT_L(0); PG8_BAR; PG8_MMA(0, 0, At, B0); PG8_MMA(0, 1, At, B1); PG8_BAR; PG8_SCHED;
;             PG8_LDA(At, 0, 1); PG8_STAGE(PG8_SB(0, 0), b2, voffB); PG8_STAGE(PG8_SB(0, 1), b2 + hstepB, voffB); PG8_STAGE(PG8_SA(0, 0), a2, voffA);
;             PG8_WAIT_V(8); PG8_WAIT_L(0); PG8_BAR; PG8_MMA(1, 0, At, B0); PG8_MMA(1, 1, At, B1); PG8_BAR; PG8_SCHED;
.LBB0_249:
	ds_read_b128 v[122:125], v181
	ds_read_b128 v[126:129], v181 offset:1024
	ds_read_b128 v[134:137], v181 offset:2048
	ds_read_b128 v[142:145], v181 offset:3072
	ds_read_b128 v[184:187], v182
	ds_read_b128 v[188:191], v182 offset:1024
	ds_read_b128 v[192:195], v182 offset:2048
	ds_read_b128 v[196:199], v182 offset:3072
	s_add_u32 s51, s0, 0xfff80080
	s_addc_u32 s63, s1, -1
	s_cmp_eq_u32 s50, 28
	s_cselect_b32 s95, s65, s63
	s_cselect_b32 s94, s64, s51
	s_cselect_b32 s91, s36, s47
	s_cselect_b32 s90, s37, s46
	v_lshl_add_u64 v[166:167], s[0:1], 0, v[158:159]
	s_add_i32 m0, s13, 0xc000
	ds_read_b128 v[200:203], v183
	ds_read_b128 v[204:207], v183 offset:1024
	ds_read_b128 v[212:215], v183 offset:2048
	ds_read_b128 v[216:219], v183 offset:3072
	ds_read_b128 v[220:223], v183 offset:4096
	ds_read_b128 v[224:227], v183 offset:5120
	ds_read_b128 v[228:231], v183 offset:6144
	ds_read_b128 v[232:235], v183 offset:7168
	global_load_lds_dwordx4 v[166:167], off
	v_lshl_add_u64 v[166:167], s[0:1], 0, v[160:161]
	s_add_i32 m0, s13, 0xe000
	s_nop 0
	global_load_lds_dwordx4 v[166:167], off
	s_waitcnt vmcnt(8)
	s_waitcnt lgkmcnt(0)
	s_barrier
	s_setprio 1
	s_waitcnt lgkmcnt(0)
	v_mfma_i32_16x16x64_i8 v[138:141], v[122:125], v[200:203], v[138:141]
	v_mfma_i32_16x16x64_i8 v[138:141], v[126:129], v[204:207], v[138:141]
	v_mfma_i32_16x16x64_i8 v[130:133], v[142:145], v[204:207], v[130:133]
	v_mfma_i32_16x16x64_i8 v[130:133], v[134:137], v[200:203], v[130:133]
	v_mfma_i32_16x16x64_i8 v[106:109], v[134:137], v[212:215], v[106:109]
	v_mfma_i32_16x16x64_i8 v[106:109], v[142:145], v[216:219], v[106:109]
	v_mfma_i32_16x16x64_i8 v[110:113], v[126:129], v[216:219], v[110:113]
	v_mfma_i32_16x16x64_i8 v[110:113], v[122:125], v[212:215], v[110:113]
	v_mfma_i32_16x16x64_i8 v[94:97], v[122:125], v[220:223], v[94:97]
	v_mfma_i32_16x16x64_i8 v[94:97], v[126:129], v[224:227], v[94:97]
	v_mfma_i32_16x16x64_i8 v[90:93], v[142:145], v[224:227], v[90:93]
	v_mfma_i32_16x16x64_i8 v[90:93], v[134:137], v[220:223], v[90:93]
	v_mfma_i32_16x16x64_i8 v[74:77], v[134:137], v[228:231], v[74:77]
	v_mfma_i32_16x16x64_i8 v[74:77], v[142:145], v[232:235], v[74:77]
	v_mfma_i32_16x16x64_i8 v[78:81], v[126:129], v[232:235], v[78:81]
	v_mfma_i32_16x16x64_i8 v[78:81], v[122:125], v[228:231], v[78:81]
	s_setprio 0
	s_setprio 1
	v_mfma_i32_16x16x64_i8 v[118:121], v[184:187], v[200:203], v[118:121]
	v_mfma_i32_16x16x64_i8 v[118:121], v[188:191], v[204:207], v[118:121]
	v_mfma_i32_16x16x64_i8 v[114:117], v[196:199], v[204:207], v[114:117]
	v_mfma_i32_16x16x64_i8 v[114:117], v[192:195], v[200:203], v[114:117]
	v_mfma_i32_16x16x64_i8 v[98:101], v[192:195], v[212:215], v[98:101]
	v_mfma_i32_16x16x64_i8 v[98:101], v[196:199], v[216:219], v[98:101]
	v_mfma_i32_16x16x64_i8 v[102:105], v[188:191], v[216:219], v[102:105]
	v_mfma_i32_16x16x64_i8 v[102:105], v[184:187], v[212:215], v[102:105]
	v_mfma_i32_16x16x64_i8 v[86:89], v[184:187], v[220:223], v[86:89]
	v_mfma_i32_16x16x64_i8 v[86:89], v[188:191], v[224:227], v[86:89]
	v_mfma_i32_16x16x64_i8 v[82:85], v[196:199], v[224:227], v[82:85]
	v_mfma_i32_16x16x64_i8 v[82:85], v[192:195], v[220:223], v[82:85]
	v_mfma_i32_16x16x64_i8 v[66:69], v[192:195], v[228:231], v[66:69]
	v_mfma_i32_16x16x64_i8 v[66:69], v[196:199], v[232:235], v[66:69]
	v_mfma_i32_16x16x64_i8 v[70:73], v[188:191], v[232:235], v[70:73]
	v_mfma_i32_16x16x64_i8 v[70:73], v[184:187], v[228:231], v[70:73]
	s_setprio 0
	s_barrier
	s_add_i32 s51, s27, s7
	v_lshl_add_u64 v[166:167], s[90:91], 0, v[148:149]
	s_mov_b32 m0, s51
	ds_read_b128 v[200:203], v183 offset:16384
	ds_read_b128 v[204:207], v183 offset:17408
	ds_read_b128 v[212:215], v183 offset:18432
	ds_read_b128 v[216:219], v183 offset:19456
	ds_read_b128 v[220:223], v183 offset:20480
	ds_read_b128 v[224:227], v183 offset:21504
	ds_read_b128 v[228:231], v183 offset:22528
	ds_read_b128 v[232:235], v183 offset:23552
	global_load_lds_dwordx4 v[166:167], off
	s_add_i32 m0, s51, 0x2000
	s_add_u32 s68, s90, 0x80000
	v_lshl_add_u64 v[208:209], s[90:91], 0, v[152:153]
	s_addc_u32 s69, s91, 0
	s_add_i32 s51, s28, s7
	global_load_lds_dwordx4 v[208:209], off
	v_lshl_add_u64 v[236:237], s[68:69], 0, v[148:149]
	s_mov_b32 m0, s51
	v_lshl_add_u64 v[238:239], s[94:95], 0, v[150:151]
	global_load_lds_dwordx4 v[236:237], off
	v_lshl_add_u64 v[236:237], s[68:69], 0, v[152:153]
	s_add_i32 m0, s51, 0x2000
	s_nop 0
	global_load_lds_dwordx4 v[236:237], off
	v_lshl_add_u64 v[236:237], s[94:95], 0, v[146:147]
	s_mov_b32 m0, s13
	s_nop 0
	global_load_lds_dwordx4 v[236:237], off
	s_mov_b32 m0, s18
	s_nop 0
	global_load_lds_dwordx4 v[238:239], off
	s_waitcnt vmcnt(8)
	s_waitcnt lgkmcnt(0)
	s_barrier
; #define PG8_STAGE(bufoff, gbase, voff) do { _Pragma("unroll") for (int _i = 0; _i < 2; ++_i) \
;         __builtin_amdgcn_global_load_lds((const unsigned*)((const char*)(gbase) + (voff)[_i]), (PG8_LAS unsigned*)(lds + (bufoff) + ldsw + _i * 8192), 16, 0, 0); } while (0)
; #define PG8_LDA(dst, b, h) do { _Pragma("unroll") for (int m = 0; m < 4; ++m) _Pragma("unroll") for (int k = 0; k < 2; ++k) dst[m][k] = *(const PG8_LAS bf16x8*)(lds + PG8_SA(b, h) + aoff + m * 2048 + k * 1024); } while (0)
; #define PG8_LDB(dst, b, h) do { _Pragma("unroll") for (int n = 0; n < 2; ++n) _Pragma("unroll") for (int k = 0; k < 2; ++k) dst[n][k] = *(const PG8_LAS bf16x8*)(lds + PG8_SB(b, h) + boff + n * 2048 + k * 1024); } while (0)
; #define PG8_MMA(ai, bj, At, Bt) do { __builtin_amdgcn_s_setprio(1); _Pragma("unroll") for (int m = 0; m < 4; ++m) _Pragma("unroll") for (int n = 0; n < 2; ++n) _Pragma("unroll") for (int k = 0; k < 2; ++k) \
;         acc[ai][bj][m][n] = mma16(Bt[n][k], At[m][k], acc[ai][bj][m][n]); __builtin_amdgcn_s_setprio(0); } while (0)
; #define PG8_WAIT_V(n) asm volatile("s_waitcnt vmcnt(" #n ")" ::: "memory")
; #define PG8_WAIT_L(n) asm volatile("s_waitcnt lgkmcnt(" #n ")" ::: "memory")
; #define PG8_BAR __builtin_amdgcn_s_barrier()
; #define PG8_SCHED __builtin_amdgcn_sched_barrier(0)
; template <class Epi, class Sched, bool ALIGN_EPI = false, bool SP2 = false>
; __device__ __forceinline__ void gemm_phase(PG8_LAS unsigned char* lds, const Gemm g, const Sched& S, const Epi& E) {
;     ...
;             PG8_WAIT_V(8); PG8_WAIT_L(0); PG8_BAR; PG8_MMA(1, 0, At, B0); PG8_MMA(1, 1, At, B1); PG8_BAR; PG8_SCHED;
;             PG8_LDB(B0, 1, 0); PG8_LDB(B1, 1, 1); PG8_SCHED; PG8_LDA(At, 1, 0); PG8_STAGE(PG8_SA(0, 1), a2 + hstepA, voffA);
;             PG8_WAIT_V(8); PG8_WAIT_L(0); PG8_BAR; PG8_MMA(0, 0, At, B0); PG8_MMA(0, 1, At, B1); PG8_BAR; PG8_SCHED;
	s_setprio 1
	s_waitcnt lgkmcnt(0)
	v_mfma_i32_16x16x64_i8 v[62:65], v[122:125], v[200:203], v[62:65]
	v_mfma_i32_16x16x64_i8 v[62:65], v[126:129], v[204:207], v[62:65]
	v_mfma_i32_16x16x64_i8 v[58:61], v[142:145], v[204:207], v[58:61]
	v_mfma_i32_16x16x64_i8 v[58:61], v[134:137], v[200:203], v[58:61]
	v_mfma_i32_16x16x64_i8 v[42:45], v[134:137], v[212:215], v[42:45]
	v_mfma_i32_16x16x64_i8 v[42:45], v[142:145], v[216:219], v[42:45]
	v_mfma_i32_16x16x64_i8 v[46:49], v[126:129], v[216:219], v[46:49]
	v_mfma_i32_16x16x64_i8 v[46:49], v[122:125], v[212:215], v[46:49]
	v_mfma_i32_16x16x64_i8 v[30:33], v[122:125], v[220:223], v[30:33]
	v_mfma_i32_16x16x64_i8 v[30:33], v[126:129], v[224:227], v[30:33]
	v_mfma_i32_16x16x64_i8 v[26:29], v[142:145], v[224:227], v[26:29]
	v_mfma_i32_16x16x64_i8 v[26:29], v[134:137], v[220:223], v[26:29]
	v_mfma_i32_16x16x64_i8 v[10:13], v[134:137], v[228:231], v[10:13]
	v_mfma_i32_16x16x64_i8 v[10:13], v[142:145], v[232:235], v[10:13]
	v_mfma_i32_16x16x64_i8 v[14:17], v[126:129], v[232:235], v[14:17]
	v_mfma_i32_16x16x64_i8 v[14:17], v[122:125], v[228:231], v[14:17]
	s_setprio 0
	s_setprio 1
	v_mfma_i32_16x16x64_i8 v[54:57], v[184:187], v[200:203], v[54:57]
	v_mfma_i32_16x16x64_i8 v[54:57], v[188:191], v[204:207], v[54:57]
	v_mfma_i32_16x16x64_i8 v[50:53], v[196:199], v[204:207], v[50:53]
	v_mfma_i32_16x16x64_i8 v[50:53], v[192:195], v[200:203], v[50:53]
	v_mfma_i32_16x16x64_i8 v[34:37], v[192:195], v[212:215], v[34:37]
	v_mfma_i32_16x16x64_i8 v[34:37], v[196:199], v[216:219], v[34:37]
	v_mfma_i32_16x16x64_i8 v[38:41], v[188:191], v[216:219], v[38:41]
	v_mfma_i32_16x16x64_i8 v[38:41], v[184:187], v[212:215], v[38:41]
	v_mfma_i32_16x16x64_i8 v[22:25], v[184:187], v[220:223], v[22:25]
	v_mfma_i32_16x16x64_i8 v[22:25], v[188:191], v[224:227], v[22:25]
	v_mfma_i32_16x16x64_i8 v[18:21], v[196:199], v[224:227], v[18:21]
	v_mfma_i32_16x16x64_i8 v[18:21], v[192:195], v[220:223], v[18:21]
	v_mfma_i32_16x16x64_i8 v[2:5], v[192:195], v[228:231], v[2:5]
	v_mfma_i32_16x16x64_i8 v[2:5], v[196:199], v[232:235], v[2:5]
	v_mfma_i32_16x16x64_i8 v[6:9], v[188:191], v[232:235], v[6:9]
	v_mfma_i32_16x16x64_i8 v[6:9], v[184:187], v[228:231], v[6:9]
	s_setprio 0
	s_barrier
	s_add_i32 s51, 0, 0x18000
	s_add_i32 s63, 0, 0x1c000
	v_add_u32_e32 v142, s51, v176
	v_add_u32_e32 v196, s63, v176
	ds_read_b128 v[122:125], v142
	ds_read_b128 v[126:129], v142 offset:1024
	ds_read_b128 v[134:137], v142 offset:2048
	ds_read_b128 v[142:145], v142 offset:3072
	ds_read_b128 v[184:187], v196
	ds_read_b128 v[188:191], v196 offset:1024
	ds_read_b128 v[192:195], v196 offset:2048
	ds_read_b128 v[196:199], v196 offset:3072
	s_add_u32 s68, s94, 0x80000
	s_addc_u32 s69, s95, 0
	s_mov_b32 m0, s19
	v_lshl_add_u64 v[240:241], s[68:69], 0, v[146:147]
	ds_read_b128 v[200:203], v183 offset:32768
	ds_read_b128 v[204:207], v183 offset:33792
	ds_read_b128 v[212:215], v183 offset:34816
	ds_read_b128 v[216:219], v183 offset:35840
	ds_read_b128 v[220:223], v183 offset:36864
	ds_read_b128 v[224:227], v183 offset:37888
	ds_read_b128 v[228:231], v183 offset:38912
	ds_read_b128 v[232:235], v183 offset:39936
	global_load_lds_dwordx4 v[240:241], off
	v_lshl_add_u64 v[240:241], s[68:69], 0, v[150:151]
	s_mov_b32 m0, s20
	s_nop 0
	global_load_lds_dwordx4 v[240:241], off
	s_waitcnt vmcnt(8)
	s_waitcnt lgkmcnt(0)
	s_barrier
	s_setprio 1
	s_waitcnt lgkmcnt(0)
	v_mfma_i32_16x16x64_i8 v[138:141], v[122:125], v[200:203], v[138:141]
	v_mfma_i32_16x16x64_i8 v[138:141], v[126:129], v[204:207], v[138:141]
	v_mfma_i32_16x16x64_i8 v[130:133], v[142:145], v[204:207], v[130:133]
	v_mfma_i32_16x16x64_i8 v[130:133], v[134:137], v[200:203], v[130:133]
	v_mfma_i32_16x16x64_i8 v[106:109], v[134:137], v[212:215], v[106:109]
	v_mfma_i32_16x16x64_i8 v[106:109], v[142:145], v[216:219], v[106:109]
	v_mfma_i32_16x16x64_i8 v[110:113], v[126:129], v[216:219], v[110:113]
	v_mfma_i32_16x16x64_i8 v[110:113], v[122:125], v[212:215], v[110:113]
	v_mfma_i32_16x16x64_i8 v[94:97], v[122:125], v[220:223], v[94:97]
	v_mfma_i32_16x16x64_i8 v[94:97], v[126:129], v[224:227], v[94:97]
	v_mfma_i32_16x16x64_i8 v[90:93], v[142:145], v[224:227], v[90:93]
	v_mfma_i32_16x16x64_i8 v[90:93], v[134:137], v[220:223], v[90:93]
	v_mfma_i32_16x16x64_i8 v[74:77], v[134:137], v[228:231], v[74:77]
	v_mfma_i32_16x16x64_i8 v[74:77], v[142:145], v[232:235], v[74:77]
	v_mfma_i32_16x16x64_i8 v[78:81], v[126:129], v[232:235], v[78:81]
	v_mfma_i32_16x16x64_i8 v[78:81], v[122:125], v[228:231], v[78:81]
	s_setprio 0
	s_setprio 1
	v_mfma_i32_16x16x64_i8 v[118:121], v[184:187], v[200:203], v[118:121]
	v_mfma_i32_16x16x64_i8 v[118:121], v[188:191], v[204:207], v[118:121]
	v_mfma_i32_16x16x64_i8 v[114:117], v[196:199], v[204:207], v[114:117]
	v_mfma_i32_16x16x64_i8 v[114:117], v[192:195], v[200:203], v[114:117]
	v_mfma_i32_16x16x64_i8 v[98:101], v[192:195], v[212:215], v[98:101]
	v_mfma_i32_16x16x64_i8 v[98:101], v[196:199], v[216:219], v[98:101]
	v_mfma_i32_16x16x64_i8 v[102:105], v[188:191], v[216:219], v[102:105]
	v_mfma_i32_16x16x64_i8 v[102:105], v[184:187], v[212:215], v[102:105]
	v_mfma_i32_16x16x64_i8 v[86:89], v[184:187], v[220:223], v[86:89]
	v_mfma_i32_16x16x64_i8 v[86:89], v[188:191], v[224:227], v[86:89]
	v_mfma_i32_16x16x64_i8 v[82:85], v[196:199], v[224:227], v[82:85]
	v_mfma_i32_16x16x64_i8 v[82:85], v[192:195], v[220:223], v[82:85]
	v_mfma_i32_16x16x64_i8 v[66:69], v[192:195], v[228:231], v[66:69]
	v_mfma_i32_16x16x64_i8 v[66:69], v[196:199], v[232:235], v[66:69]
	v_mfma_i32_16x16x64_i8 v[70:73], v[188:191], v[232:235], v[70:73]
	v_mfma_i32_16x16x64_i8 v[70:73], v[184:187], v[228:231], v[70:73]
	s_setprio 0
	s_barrier
; #define PG8_STAGE(bufoff, gbase, voff) do { _Pragma("unroll") for (int _i = 0; _i < 2; ++_i) \
;         __builtin_amdgcn_global_load_lds((const unsigned*)((const char*)(gbase) + (voff)[_i]), (PG8_LAS unsigned*)(lds + (bufoff) + ldsw + _i * 8192), 16, 0, 0); } while (0)
; #define PG8_LDA(dst, b, h) do { _Pragma("unroll") for (int m = 0; m < 4; ++m) _Pragma("unroll") for (int k = 0; k < 2; ++k) dst[m][k] = *(const PG8_LAS bf16x8*)(lds + PG8_SA(b, h) + aoff + m * 2048 + k * 1024); } while (0)
; #define PG8_MMA(ai, bj, At, Bt) do { __builtin_amdgcn_s_setprio(1); _Pragma("unroll") for (int m = 0; m < 4; ++m) _Pragma("unroll") for (int n = 0; n < 2; ++n) _Pragma("unroll") for (int k = 0; k < 2; ++k) \
;         acc[ai][bj][m][n] = mma16(Bt[n][k], At[m][k], acc[ai][bj][m][n]); __builtin_amdgcn_s_setprio(0); } while (0)
; #define PG8_WAIT_V(n) asm volatile("s_waitcnt vmcnt(" #n ")" ::: "memory")
; #define PG8_WAIT_L(n) asm volatile("s_waitcnt lgkmcnt(" #n ")" ::: "memory")
; #define PG8_BAR __builtin_amdgcn_s_barrier()
; #define PG8_SCHED __builtin_amdgcn_sched_barrier(0)
; template <class Epi, class Sched, bool ALIGN_EPI = false, bool SP2 = false>
; __device__ __forceinline__ void gemm_phase(PG8_LAS unsigned char* lds, const Gemm g, const Sched& S, const Epi& E) {
;     ...
;         for (int t = 0; t < nt; t += 2) {
;     ...
;             PG8_LDA(At, 1, 1); PG8_STAGE(PG8_SB(1, 0), b3, voffB); PG8_STAGE(PG8_SB(1, 1), b3 + hstepB, voffB); PG8_STAGE(PG8_SA(1, 0), a3, voffA);
;             PG8_WAIT_V(8); PG8_WAIT_L(0); PG8_BAR; PG8_MMA(1, 0, At, B0); PG8_MMA(1, 1, At, B1); PG8_BAR; PG8_SCHED;
;     ...
;         if constexpr (ALIGN_EPI) { if (wr == 0) PG8_BAR; }
	s_add_i32 s51, s51, s7
	v_lshl_add_u64 v[166:167], v[166:167], 0, s[48:49]
	s_mov_b32 m0, s51
	ds_read_b128 v[200:203], v183 offset:49152
	ds_read_b128 v[204:207], v183 offset:50176
	ds_read_b128 v[212:215], v183 offset:51200
	ds_read_b128 v[216:219], v183 offset:52224
	ds_read_b128 v[220:223], v183 offset:53248
	ds_read_b128 v[224:227], v183 offset:54272
	ds_read_b128 v[228:231], v183 offset:55296
	ds_read_b128 v[232:235], v183 offset:56320
	global_load_lds_dwordx4 v[166:167], off
	s_add_i32 m0, s51, 0x2000
	s_add_u32 s68, s90, 0x80080
	v_lshl_add_u64 v[166:167], v[208:209], 0, s[48:49]
	s_addc_u32 s69, s91, 0
	s_add_i32 s51, s63, s7
	global_load_lds_dwordx4 v[166:167], off
	v_lshl_add_u64 v[166:167], s[68:69], 0, v[148:149]
	s_mov_b32 m0, s51
	s_nop 0
	global_load_lds_dwordx4 v[166:167], off
	v_lshl_add_u64 v[166:167], s[68:69], 0, v[152:153]
	s_add_i32 m0, s51, 0x2000
	s_nop 0
	global_load_lds_dwordx4 v[166:167], off
	v_lshl_add_u64 v[166:167], v[236:237], 0, s[48:49]
	s_mov_b32 m0, s23
	s_nop 0
	global_load_lds_dwordx4 v[166:167], off
	v_lshl_add_u64 v[166:167], v[238:239], 0, s[48:49]
	s_mov_b32 m0, s24
	s_nop 0
	global_load_lds_dwordx4 v[166:167], off
	s_waitcnt vmcnt(8)
	s_waitcnt lgkmcnt(0)
	s_barrier
	s_setprio 1
	s_waitcnt lgkmcnt(0)
	v_mfma_i32_16x16x64_i8 v[62:65], v[122:125], v[200:203], v[62:65]
	v_mfma_i32_16x16x64_i8 v[62:65], v[126:129], v[204:207], v[62:65]
	v_mfma_i32_16x16x64_i8 v[58:61], v[142:145], v[204:207], v[58:61]
	v_mfma_i32_16x16x64_i8 v[58:61], v[134:137], v[200:203], v[58:61]
	v_mfma_i32_16x16x64_i8 v[42:45], v[134:137], v[212:215], v[42:45]
	v_mfma_i32_16x16x64_i8 v[42:45], v[142:145], v[216:219], v[42:45]
	v_mfma_i32_16x16x64_i8 v[46:49], v[126:129], v[216:219], v[46:49]
	v_mfma_i32_16x16x64_i8 v[46:49], v[122:125], v[212:215], v[46:49]
	v_mfma_i32_16x16x64_i8 v[30:33], v[122:125], v[220:223], v[30:33]
	v_mfma_i32_16x16x64_i8 v[30:33], v[126:129], v[224:227], v[30:33]
	v_mfma_i32_16x16x64_i8 v[26:29], v[142:145], v[224:227], v[26:29]
	v_mfma_i32_16x16x64_i8 v[26:29], v[134:137], v[220:223], v[26:29]
	v_mfma_i32_16x16x64_i8 v[10:13], v[134:137], v[228:231], v[10:13]
	v_mfma_i32_16x16x64_i8 v[10:13], v[142:145], v[232:235], v[10:13]
	v_mfma_i32_16x16x64_i8 v[14:17], v[126:129], v[232:235], v[14:17]
	v_mfma_i32_16x16x64_i8 v[14:17], v[122:125], v[228:231], v[14:17]
	s_setprio 0
	s_setprio 1
	v_mfma_i32_16x16x64_i8 v[54:57], v[184:187], v[200:203], v[54:57]
	v_mfma_i32_16x16x64_i8 v[54:57], v[188:191], v[204:207], v[54:57]
	v_mfma_i32_16x16x64_i8 v[50:53], v[196:199], v[204:207], v[50:53]
	v_mfma_i32_16x16x64_i8 v[50:53], v[192:195], v[200:203], v[50:53]
	v_mfma_i32_16x16x64_i8 v[34:37], v[192:195], v[212:215], v[34:37]
	v_mfma_i32_16x16x64_i8 v[34:37], v[196:199], v[216:219], v[34:37]
	v_mfma_i32_16x16x64_i8 v[38:41], v[188:191], v[216:219], v[38:41]
	v_mfma_i32_16x16x64_i8 v[38:41], v[184:187], v[212:215], v[38:41]
	v_mfma_i32_16x16x64_i8 v[22:25], v[184:187], v[220:223], v[22:25]
	v_mfma_i32_16x16x64_i8 v[22:25], v[188:191], v[224:227], v[22:25]
	v_mfma_i32_16x16x64_i8 v[18:21], v[196:199], v[224:227], v[18:21]
	v_mfma_i32_16x16x64_i8 v[18:21], v[192:195], v[220:223], v[18:21]
	v_mfma_i32_16x16x64_i8 v[2:5], v[192:195], v[228:231], v[2:5]
	v_mfma_i32_16x16x64_i8 v[2:5], v[196:199], v[232:235], v[2:5]
	v_mfma_i32_16x16x64_i8 v[6:9], v[188:191], v[232:235], v[6:9]
	v_mfma_i32_16x16x64_i8 v[6:9], v[184:187], v[228:231], v[6:9]
	s_setprio 0
	s_barrier
	s_add_i32 s50, s50, 2
	s_add_u32 s0, s0, 0x100
	s_addc_u32 s1, s1, 0
	s_add_u32 s46, s46, 0x100
	s_addc_u32 s47, s47, 0
	s_cmp_gt_u32 s50, 29
	s_cbranch_scc0 .LBB0_249
	s_and_b64 vcc, exec, s[54:55]
	s_cbranch_vccz .LBB0_252
	s_barrier

; #define PG8_STAGE(bufoff, gbase, voff) do { _Pragma("unroll") for (int _i = 0; _i < 2; ++_i) \
;         __builtin_amdgcn_global_load_lds((const unsigned*)((const char*)(gbase) + (voff)[_i]), (PG8_LAS unsigned*)(lds + (bufoff) + ldsw + _i * 8192), 16, 0, 0); } while (0)
; #define PG8_LDA(dst, b, h) do { _Pragma("unroll") for (int m = 0; m < 4; ++m) _Pragma("unroll") for (int k = 0; k < 2; ++k) dst[m][k] = *(const PG8_LAS bf16x8*)(lds + PG8_SA(b, h) + aoff + m * 2048 + k * 1024); } while (0)
; #define PG8_LDB(dst, b, h) do { _Pragma("unroll") for (int n = 0; n < 2; ++n) _Pragma("unroll") for (int k = 0; k < 2; ++k) dst[n][k] = *(const PG8_LAS bf16x8*)(lds + PG8_SB(b, h) + boff + n * 2048 + k * 1024); } while (0)
; #define PG8_MMA(ai, bj, At, Bt) do { __builtin_amdgcn_s_setprio(1); _Pragma("unroll") for (int m = 0; m < 4; ++m) _Pragma("unroll") for (int n = 0; n < 2; ++n) _Pragma("unroll") for (int k = 0; k < 2; ++k) \
;         acc[ai][bj][m][n] = mma16(Bt[n][k], At[m][k], acc[ai][bj][m][n]); __builtin_amdgcn_s_setprio(0); } while (0)
; #define PG8_WAIT_V(n) asm volatile("s_waitcnt vmcnt(" #n ")" ::: "memory")
; #define PG8_WAIT_L(n) asm volatile("s_waitcnt lgkmcnt(" #n ")" ::: "memory")
; template <class Epi, class Sched, bool ALIGN_EPI = false, bool SP2 = false>
; __device__ __forceinline__ void gemm_phase(PG8_LAS unsigned char* lds, const Gemm g, const Sched& S, const Epi& E) {
;     ...
;         for (int t = 0; t < nt; t += 2) {
;             const bool last = (t == nt - 2);
;             const char* a1 = cA + (size_t)(t + 1) * kstep;
;             const char* a2 = last ? nA : cA + (size_t)(t + 2) * kstep; const char* b2 = last ? nB : cB + (size_t)(t + 2) * kstep;
;             const char* a3 = a2 + kstep; const char* b3 = b2 + kstep;
;             if (last && has_next) S.a_ready(nxt);
;             if constexpr (SP2) {
;             PG8_LDB(B0, 0, 0); PG8_LDB(B1, 0, 1); PG8_SCHED; PG8_LDA(At, 0, 0); PG8_STAGE(PG8_SA(1, 1), a1 + hstepA, voffA);
;             PG8_WAIT_V(8); PG8_WAIT_L(0); PG8_BAR; PG8_MMA(0, 0, At, B0); PG8_MMA(0, 1, At, B1); PG8_BAR; PG8_SCHED;
;             PG8_LDA(At, 0, 1); PG8_STAGE(PG8_SB(0, 0), b2, voffB); PG8_STAGE(PG8_SB(0, 1), b2 + hstepB, voffB); PG8_STAGE(PG8_SA(0, 0), a2, voffA);
;             PG8_WAIT_V(8); PG8_WAIT_L(0); PG8_BAR; PG8_MMA(1, 0, At, B0); PG8_MMA(1, 1, At, B1); PG8_BAR; PG8_SCHED;
.LBB0_275:
	ds_read_b128 v[122:125], v169
	ds_read_b128 v[126:129], v169 offset:1024
	ds_read_b128 v[134:137], v169 offset:2048
	ds_read_b128 v[142:145], v169 offset:3072
	ds_read_b128 v[182:185], v170
	ds_read_b128 v[186:189], v170 offset:1024
	ds_read_b128 v[190:193], v170 offset:2048
	ds_read_b128 v[194:197], v170 offset:3072
	s_add_u32 s51, s0, 0xfff80080
	s_addc_u32 s63, s1, -1
	s_cmp_eq_u32 s50, 28
	s_cselect_b32 s67, s55, s63
	s_cselect_b32 s66, s54, s51
	s_cselect_b32 s65, s37, s49
	s_cselect_b32 s64, s46, s47
	v_lshl_add_u64 v[166:167], s[0:1], 0, v[158:159]
	s_add_i32 m0, s18, 0xc000
	ds_read_b128 v[198:201], v171
	ds_read_b128 v[202:205], v171 offset:1024
	ds_read_b128 v[206:209], v171 offset:2048
	ds_read_b128 v[212:215], v171 offset:3072
	ds_read_b128 v[216:219], v171 offset:4096
	ds_read_b128 v[220:223], v171 offset:5120
	ds_read_b128 v[224:227], v171 offset:6144
	ds_read_b128 v[228:231], v171 offset:7168
	global_load_lds_dwordx4 v[166:167], off
	v_lshl_add_u64 v[166:167], s[0:1], 0, v[160:161]
	s_add_i32 m0, s18, 0xe000
	s_nop 0
	global_load_lds_dwordx4 v[166:167], off
	s_waitcnt vmcnt(8)
	s_waitcnt lgkmcnt(0)
	s_barrier
	s_setprio 1
	s_waitcnt lgkmcnt(0)
	v_mfma_i32_16x16x64_i8 v[138:141], v[122:125], v[198:201], v[138:141]
	v_mfma_i32_16x16x64_i8 v[138:141], v[126:129], v[202:205], v[138:141]
	v_mfma_i32_16x16x64_i8 v[130:133], v[142:145], v[202:205], v[130:133]
	v_mfma_i32_16x16x64_i8 v[130:133], v[134:137], v[198:201], v[130:133]
	v_mfma_i32_16x16x64_i8 v[106:109], v[134:137], v[206:209], v[106:109]
	v_mfma_i32_16x16x64_i8 v[106:109], v[142:145], v[212:215], v[106:109]
	v_mfma_i32_16x16x64_i8 v[110:113], v[126:129], v[212:215], v[110:113]
	v_mfma_i32_16x16x64_i8 v[110:113], v[122:125], v[206:209], v[110:113]
	v_mfma_i32_16x16x64_i8 v[94:97], v[122:125], v[216:219], v[94:97]
	v_mfma_i32_16x16x64_i8 v[94:97], v[126:129], v[220:223], v[94:97]
	v_mfma_i32_16x16x64_i8 v[90:93], v[142:145], v[220:223], v[90:93]
	v_mfma_i32_16x16x64_i8 v[90:93], v[134:137], v[216:219], v[90:93]
	v_mfma_i32_16x16x64_i8 v[74:77], v[134:137], v[224:227], v[74:77]
	v_mfma_i32_16x16x64_i8 v[74:77], v[142:145], v[228:231], v[74:77]
	v_mfma_i32_16x16x64_i8 v[78:81], v[126:129], v[228:231], v[78:81]
	v_mfma_i32_16x16x64_i8 v[78:81], v[122:125], v[224:227], v[78:81]
	s_setprio 0
	s_setprio 1
	v_mfma_i32_16x16x64_i8 v[118:121], v[182:185], v[198:201], v[118:121]
	v_mfma_i32_16x16x64_i8 v[118:121], v[186:189], v[202:205], v[118:121]
	v_mfma_i32_16x16x64_i8 v[114:117], v[194:197], v[202:205], v[114:117]
	v_mfma_i32_16x16x64_i8 v[114:117], v[190:193], v[198:201], v[114:117]
	v_mfma_i32_16x16x64_i8 v[98:101], v[190:193], v[206:209], v[98:101]
	v_mfma_i32_16x16x64_i8 v[98:101], v[194:197], v[212:215], v[98:101]
	v_mfma_i32_16x16x64_i8 v[102:105], v[186:189], v[212:215], v[102:105]
	v_mfma_i32_16x16x64_i8 v[102:105], v[182:185], v[206:209], v[102:105]
	v_mfma_i32_16x16x64_i8 v[86:89], v[182:185], v[216:219], v[86:89]
	v_mfma_i32_16x16x64_i8 v[86:89], v[186:189], v[220:223], v[86:89]
	v_mfma_i32_16x16x64_i8 v[82:85], v[194:197], v[220:223], v[82:85]
	v_mfma_i32_16x16x64_i8 v[82:85], v[190:193], v[216:219], v[82:85]
	v_mfma_i32_16x16x64_i8 v[66:69], v[190:193], v[224:227], v[66:69]
	v_mfma_i32_16x16x64_i8 v[66:69], v[194:197], v[228:231], v[66:69]
	v_mfma_i32_16x16x64_i8 v[70:73], v[186:189], v[228:231], v[70:73]
	v_mfma_i32_16x16x64_i8 v[70:73], v[182:185], v[224:227], v[70:73]
	s_setprio 0
	s_barrier
	s_add_i32 s51, s28, s12
	v_lshl_add_u64 v[166:167], s[64:65], 0, v[148:149]
	s_mov_b32 m0, s51
	ds_read_b128 v[198:201], v171 offset:16384
	ds_read_b128 v[202:205], v171 offset:17408
	ds_read_b128 v[206:209], v171 offset:18432
	ds_read_b128 v[212:215], v171 offset:19456
	ds_read_b128 v[216:219], v171 offset:20480
	ds_read_b128 v[220:223], v171 offset:21504
	ds_read_b128 v[224:227], v171 offset:22528
	ds_read_b128 v[228:231], v171 offset:23552
	global_load_lds_dwordx4 v[166:167], off
	s_add_i32 m0, s51, 0x2000
	s_add_u32 s68, s64, 0x80000
	v_lshl_add_u64 v[176:177], s[64:65], 0, v[152:153]
	s_addc_u32 s69, s65, 0
	s_add_i32 s51, s29, s12
	global_load_lds_dwordx4 v[176:177], off
	v_lshl_add_u64 v[232:233], s[68:69], 0, v[148:149]
	s_mov_b32 m0, s51
	v_lshl_add_u64 v[234:235], s[66:67], 0, v[150:151]
	global_load_lds_dwordx4 v[232:233], off
	v_lshl_add_u64 v[232:233], s[68:69], 0, v[152:153]
	s_add_i32 m0, s51, 0x2000
	s_nop 0
	global_load_lds_dwordx4 v[232:233], off
	v_lshl_add_u64 v[232:233], s[66:67], 0, v[146:147]
	s_mov_b32 m0, s18
	s_nop 0
	global_load_lds_dwordx4 v[232:233], off
	s_mov_b32 m0, s19
	s_nop 0
	global_load_lds_dwordx4 v[234:235], off
	s_waitcnt vmcnt(8)
	s_waitcnt lgkmcnt(0)
	s_barrier
; #define PG8_STAGE(bufoff, gbase, voff) do { _Pragma("unroll") for (int _i = 0; _i < 2; ++_i) \
;         __builtin_amdgcn_global_load_lds((const unsigned*)((const char*)(gbase) + (voff)[_i]), (PG8_LAS unsigned*)(lds + (bufoff) + ldsw + _i * 8192), 16, 0, 0); } while (0)
; #define PG8_LDA(dst, b, h) do { _Pragma("unroll") for (int m = 0; m < 4; ++m) _Pragma("unroll") for (int k = 0; k < 2; ++k) dst[m][k] = *(const PG8_LAS bf16x8*)(lds + PG8_SA(b, h) + aoff + m * 2048 + k * 1024); } while (0)
; #define PG8_LDB(dst, b, h) do { _Pragma("unroll") for (int n = 0; n < 2; ++n) _Pragma("unroll") for (int k = 0; k < 2; ++k) dst[n][k] = *(const PG8_LAS bf16x8*)(lds + PG8_SB(b, h) + boff + n * 2048 + k * 1024); } while (0)
; #define PG8_MMA(ai, bj, At, Bt) do { __builtin_amdgcn_s_setprio(1); _Pragma("unroll") for (int m = 0; m < 4; ++m) _Pragma("unroll") for (int n = 0; n < 2; ++n) _Pragma("unroll") for (int k = 0; k < 2; ++k) \
;         acc[ai][bj][m][n] = mma16(Bt[n][k], At[m][k], acc[ai][bj][m][n]); __builtin_amdgcn_s_setprio(0); } while (0)
; #define PG8_WAIT_V(n) asm volatile("s_waitcnt vmcnt(" #n ")" ::: "memory")
; #define PG8_WAIT_L(n) asm volatile("s_waitcnt lgkmcnt(" #n ")" ::: "memory")
; #define PG8_BAR __builtin_amdgcn_s_barrier()
; #define PG8_SCHED __builtin_amdgcn_sched_barrier(0)
; template <class Epi, class Sched, bool ALIGN_EPI = false, bool SP2 = false>
; __device__ __forceinline__ void gemm_phase(PG8_LAS unsigned char* lds, const Gemm g, const Sched& S, const Epi& E) {
;     ...
;             PG8_WAIT_V(8); PG8_WAIT_L(0); PG8_BAR; PG8_MMA(1, 0, At, B0); PG8_MMA(1, 1, At, B1); PG8_BAR; PG8_SCHED;
;             PG8_LDB(B0, 1, 0); PG8_LDB(B1, 1, 1); PG8_SCHED; PG8_LDA(At, 1, 0); PG8_STAGE(PG8_SA(0, 1), a2 + hstepA, voffA);
;             PG8_WAIT_V(8); PG8_WAIT_L(0); PG8_BAR; PG8_MMA(0, 0, At, B0); PG8_MMA(0, 1, At, B1); PG8_BAR; PG8_SCHED;
	s_setprio 1
	s_waitcnt lgkmcnt(0)
	v_mfma_i32_16x16x64_i8 v[62:65], v[122:125], v[198:201], v[62:65]
	v_mfma_i32_16x16x64_i8 v[62:65], v[126:129], v[202:205], v[62:65]
	v_mfma_i32_16x16x64_i8 v[58:61], v[142:145], v[202:205], v[58:61]
	v_mfma_i32_16x16x64_i8 v[58:61], v[134:137], v[198:201], v[58:61]
	v_mfma_i32_16x16x64_i8 v[42:45], v[134:137], v[206:209], v[42:45]
	v_mfma_i32_16x16x64_i8 v[42:45], v[142:145], v[212:215], v[42:45]
	v_mfma_i32_16x16x64_i8 v[46:49], v[126:129], v[212:215], v[46:49]
	v_mfma_i32_16x16x64_i8 v[46:49], v[122:125], v[206:209], v[46:49]
	v_mfma_i32_16x16x64_i8 v[30:33], v[122:125], v[216:219], v[30:33]
	v_mfma_i32_16x16x64_i8 v[30:33], v[126:129], v[220:223], v[30:33]
	v_mfma_i32_16x16x64_i8 v[26:29], v[142:145], v[220:223], v[26:29]
	v_mfma_i32_16x16x64_i8 v[26:29], v[134:137], v[216:219], v[26:29]
	v_mfma_i32_16x16x64_i8 v[10:13], v[134:137], v[224:227], v[10:13]
	v_mfma_i32_16x16x64_i8 v[10:13], v[142:145], v[228:231], v[10:13]
	v_mfma_i32_16x16x64_i8 v[14:17], v[126:129], v[228:231], v[14:17]
	v_mfma_i32_16x16x64_i8 v[14:17], v[122:125], v[224:227], v[14:17]
	s_setprio 0
	s_setprio 1
	v_mfma_i32_16x16x64_i8 v[54:57], v[182:185], v[198:201], v[54:57]
	v_mfma_i32_16x16x64_i8 v[54:57], v[186:189], v[202:205], v[54:57]
	v_mfma_i32_16x16x64_i8 v[50:53], v[194:197], v[202:205], v[50:53]
	v_mfma_i32_16x16x64_i8 v[50:53], v[190:193], v[198:201], v[50:53]
	v_mfma_i32_16x16x64_i8 v[34:37], v[190:193], v[206:209], v[34:37]
	v_mfma_i32_16x16x64_i8 v[34:37], v[194:197], v[212:215], v[34:37]
	v_mfma_i32_16x16x64_i8 v[38:41], v[186:189], v[212:215], v[38:41]
	v_mfma_i32_16x16x64_i8 v[38:41], v[182:185], v[206:209], v[38:41]
	v_mfma_i32_16x16x64_i8 v[22:25], v[182:185], v[216:219], v[22:25]
	v_mfma_i32_16x16x64_i8 v[22:25], v[186:189], v[220:223], v[22:25]
	v_mfma_i32_16x16x64_i8 v[18:21], v[194:197], v[220:223], v[18:21]
	v_mfma_i32_16x16x64_i8 v[18:21], v[190:193], v[216:219], v[18:21]
	v_mfma_i32_16x16x64_i8 v[2:5], v[190:193], v[224:227], v[2:5]
	v_mfma_i32_16x16x64_i8 v[2:5], v[194:197], v[228:231], v[2:5]
	v_mfma_i32_16x16x64_i8 v[6:9], v[186:189], v[228:231], v[6:9]
	v_mfma_i32_16x16x64_i8 v[6:9], v[182:185], v[224:227], v[6:9]
	s_setprio 0
	s_barrier
	s_add_i32 s51, 0, 0x18000
	s_add_i32 s63, 0, 0x1c000
	v_add_u32_e32 v142, s51, v173
	v_add_u32_e32 v172, s63, v173
	ds_read_b128 v[122:125], v142
	ds_read_b128 v[126:129], v142 offset:1024
	ds_read_b128 v[134:137], v142 offset:2048
	ds_read_b128 v[142:145], v142 offset:3072
	ds_read_b128 v[182:185], v172
	ds_read_b128 v[186:189], v172 offset:1024
	ds_read_b128 v[190:193], v172 offset:2048
	ds_read_b128 v[194:197], v172 offset:3072
	s_add_u32 s66, s66, 0x80000
	s_addc_u32 s67, s67, 0
	s_mov_b32 m0, s20
	v_lshl_add_u64 v[236:237], s[66:67], 0, v[146:147]
	ds_read_b128 v[198:201], v171 offset:32768
	ds_read_b128 v[202:205], v171 offset:33792
	ds_read_b128 v[206:209], v171 offset:34816
	ds_read_b128 v[212:215], v171 offset:35840
	ds_read_b128 v[216:219], v171 offset:36864
	ds_read_b128 v[220:223], v171 offset:37888
	ds_read_b128 v[224:227], v171 offset:38912
	ds_read_b128 v[228:231], v171 offset:39936
	global_load_lds_dwordx4 v[236:237], off
	v_lshl_add_u64 v[236:237], s[66:67], 0, v[150:151]
	s_mov_b32 m0, s21
	s_nop 0
	global_load_lds_dwordx4 v[236:237], off
	s_waitcnt vmcnt(8)
	s_waitcnt lgkmcnt(0)
	s_barrier
	s_setprio 1
	s_waitcnt lgkmcnt(0)
	v_mfma_i32_16x16x64_i8 v[138:141], v[122:125], v[198:201], v[138:141]
	v_mfma_i32_16x16x64_i8 v[138:141], v[126:129], v[202:205], v[138:141]
	v_mfma_i32_16x16x64_i8 v[130:133], v[142:145], v[202:205], v[130:133]
	v_mfma_i32_16x16x64_i8 v[130:133], v[134:137], v[198:201], v[130:133]
	v_mfma_i32_16x16x64_i8 v[106:109], v[134:137], v[206:209], v[106:109]
	v_mfma_i32_16x16x64_i8 v[106:109], v[142:145], v[212:215], v[106:109]
	v_mfma_i32_16x16x64_i8 v[110:113], v[126:129], v[212:215], v[110:113]
	v_mfma_i32_16x16x64_i8 v[110:113], v[122:125], v[206:209], v[110:113]
	v_mfma_i32_16x16x64_i8 v[94:97], v[122:125], v[216:219], v[94:97]
	v_mfma_i32_16x16x64_i8 v[94:97], v[126:129], v[220:223], v[94:97]
	v_mfma_i32_16x16x64_i8 v[90:93], v[142:145], v[220:223], v[90:93]
	v_mfma_i32_16x16x64_i8 v[90:93], v[134:137], v[216:219], v[90:93]
	v_mfma_i32_16x16x64_i8 v[74:77], v[134:137], v[224:227], v[74:77]
	v_mfma_i32_16x16x64_i8 v[74:77], v[142:145], v[228:231], v[74:77]
	v_mfma_i32_16x16x64_i8 v[78:81], v[126:129], v[228:231], v[78:81]
	v_mfma_i32_16x16x64_i8 v[78:81], v[122:125], v[224:227], v[78:81]
	s_setprio 0
	s_setprio 1
	v_mfma_i32_16x16x64_i8 v[118:121], v[182:185], v[198:201], v[118:121]
	v_mfma_i32_16x16x64_i8 v[118:121], v[186:189], v[202:205], v[118:121]
	v_mfma_i32_16x16x64_i8 v[114:117], v[194:197], v[202:205], v[114:117]
	v_mfma_i32_16x16x64_i8 v[114:117], v[190:193], v[198:201], v[114:117]
	v_mfma_i32_16x16x64_i8 v[98:101], v[190:193], v[206:209], v[98:101]
	v_mfma_i32_16x16x64_i8 v[98:101], v[194:197], v[212:215], v[98:101]
	v_mfma_i32_16x16x64_i8 v[102:105], v[186:189], v[212:215], v[102:105]
	v_mfma_i32_16x16x64_i8 v[102:105], v[182:185], v[206:209], v[102:105]
	v_mfma_i32_16x16x64_i8 v[86:89], v[182:185], v[216:219], v[86:89]
	v_mfma_i32_16x16x64_i8 v[86:89], v[186:189], v[220:223], v[86:89]
	v_mfma_i32_16x16x64_i8 v[82:85], v[194:197], v[220:223], v[82:85]
	v_mfma_i32_16x16x64_i8 v[82:85], v[190:193], v[216:219], v[82:85]
	v_mfma_i32_16x16x64_i8 v[66:69], v[190:193], v[224:227], v[66:69]
	v_mfma_i32_16x16x64_i8 v[66:69], v[194:197], v[228:231], v[66:69]
	v_mfma_i32_16x16x64_i8 v[70:73], v[186:189], v[228:231], v[70:73]
	v_mfma_i32_16x16x64_i8 v[70:73], v[182:185], v[224:227], v[70:73]
	s_setprio 0
	s_barrier
; #define PG8_STAGE(bufoff, gbase, voff) do { _Pragma("unroll") for (int _i = 0; _i < 2; ++_i) \
;         __builtin_amdgcn_global_load_lds((const unsigned*)((const char*)(gbase) + (voff)[_i]), (PG8_LAS unsigned*)(lds + (bufoff) + ldsw + _i * 8192), 16, 0, 0); } while (0)
; #define PG8_LDA(dst, b, h) do { _Pragma("unroll") for (int m = 0; m < 4; ++m) _Pragma("unroll") for (int k = 0; k < 2; ++k) dst[m][k] = *(const PG8_LAS bf16x8*)(lds + PG8_SA(b, h) + aoff + m * 2048 + k * 1024); } while (0)
; #define PG8_MMA(ai, bj, At, Bt) do { __builtin_amdgcn_s_setprio(1); _Pragma("unroll") for (int m = 0; m < 4; ++m) _Pragma("unroll") for (int n = 0; n < 2; ++n) _Pragma("unroll") for (int k = 0; k < 2; ++k) \
;         acc[ai][bj][m][n] = mma16(Bt[n][k], At[m][k], acc[ai][bj][m][n]); __builtin_amdgcn_s_setprio(0); } while (0)
; #define PG8_WAIT_V(n) asm volatile("s_waitcnt vmcnt(" #n ")" ::: "memory")
; #define PG8_WAIT_L(n) asm volatile("s_waitcnt lgkmcnt(" #n ")" ::: "memory")
; #define PG8_BAR __builtin_amdgcn_s_barrier()
; #define PG8_SCHED __builtin_amdgcn_sched_barrier(0)
; template <class Epi, class Sched, bool ALIGN_EPI = false, bool SP2 = false>
; __device__ __forceinline__ void gemm_phase(PG8_LAS unsigned char* lds, const Gemm g, const Sched& S, const Epi& E) {
;     ...
;         for (int t = 0; t < nt; t += 2) {
;     ...
;             PG8_LDA(At, 1, 1); PG8_STAGE(PG8_SB(1, 0), b3, voffB); PG8_STAGE(PG8_SB(1, 1), b3 + hstepB, voffB); PG8_STAGE(PG8_SA(1, 0), a3, voffA);
;             PG8_WAIT_V(8); PG8_WAIT_L(0); PG8_BAR; PG8_MMA(1, 0, At, B0); PG8_MMA(1, 1, At, B1); PG8_BAR; PG8_SCHED;
;     ...
;         if constexpr (ALIGN_EPI) { if (wr == 0) PG8_BAR; }
	s_add_i32 s51, s51, s12
	v_lshl_add_u64 v[166:167], v[166:167], 0, s[42:43]
	s_mov_b32 m0, s51
	ds_read_b128 v[198:201], v171 offset:49152
	ds_read_b128 v[202:205], v171 offset:50176
	ds_read_b128 v[206:209], v171 offset:51200
	ds_read_b128 v[212:215], v171 offset:52224
	ds_read_b128 v[216:219], v171 offset:53248
	ds_read_b128 v[220:223], v171 offset:54272
	ds_read_b128 v[224:227], v171 offset:55296
	ds_read_b128 v[228:231], v171 offset:56320
	global_load_lds_dwordx4 v[166:167], off
	s_add_i32 m0, s51, 0x2000
	s_add_u32 s64, s64, 0x80080
	v_lshl_add_u64 v[166:167], v[176:177], 0, s[42:43]
	s_addc_u32 s65, s65, 0
	s_add_i32 s51, s63, s12
	global_load_lds_dwordx4 v[166:167], off
	v_lshl_add_u64 v[166:167], s[64:65], 0, v[148:149]
	s_mov_b32 m0, s51
	s_nop 0
	global_load_lds_dwordx4 v[166:167], off
	v_lshl_add_u64 v[166:167], s[64:65], 0, v[152:153]
	s_add_i32 m0, s51, 0x2000
	s_nop 0
	global_load_lds_dwordx4 v[166:167], off
	v_lshl_add_u64 v[166:167], v[232:233], 0, s[42:43]
	s_mov_b32 m0, s24
	s_nop 0
	global_load_lds_dwordx4 v[166:167], off
	v_lshl_add_u64 v[166:167], v[234:235], 0, s[42:43]
	s_mov_b32 m0, s25
	s_nop 0
	global_load_lds_dwordx4 v[166:167], off
	s_waitcnt vmcnt(8)
	s_waitcnt lgkmcnt(0)
	s_barrier
	s_setprio 1
	s_waitcnt lgkmcnt(0)
	v_mfma_i32_16x16x64_i8 v[62:65], v[122:125], v[198:201], v[62:65]
	v_mfma_i32_16x16x64_i8 v[62:65], v[126:129], v[202:205], v[62:65]
	v_mfma_i32_16x16x64_i8 v[58:61], v[142:145], v[202:205], v[58:61]
	v_mfma_i32_16x16x64_i8 v[58:61], v[134:137], v[198:201], v[58:61]
	v_mfma_i32_16x16x64_i8 v[42:45], v[134:137], v[206:209], v[42:45]
	v_mfma_i32_16x16x64_i8 v[42:45], v[142:145], v[212:215], v[42:45]
	v_mfma_i32_16x16x64_i8 v[46:49], v[126:129], v[212:215], v[46:49]
	v_mfma_i32_16x16x64_i8 v[46:49], v[122:125], v[206:209], v[46:49]
	v_mfma_i32_16x16x64_i8 v[30:33], v[122:125], v[216:219], v[30:33]
	v_mfma_i32_16x16x64_i8 v[30:33], v[126:129], v[220:223], v[30:33]
	v_mfma_i32_16x16x64_i8 v[26:29], v[142:145], v[220:223], v[26:29]
	v_mfma_i32_16x16x64_i8 v[26:29], v[134:137], v[216:219], v[26:29]
	v_mfma_i32_16x16x64_i8 v[10:13], v[134:137], v[224:227], v[10:13]
	v_mfma_i32_16x16x64_i8 v[10:13], v[142:145], v[228:231], v[10:13]
	v_mfma_i32_16x16x64_i8 v[14:17], v[126:129], v[228:231], v[14:17]
	v_mfma_i32_16x16x64_i8 v[14:17], v[122:125], v[224:227], v[14:17]
	s_setprio 0
	s_setprio 1
	v_mfma_i32_16x16x64_i8 v[54:57], v[182:185], v[198:201], v[54:57]
	v_mfma_i32_16x16x64_i8 v[54:57], v[186:189], v[202:205], v[54:57]
	v_mfma_i32_16x16x64_i8 v[50:53], v[194:197], v[202:205], v[50:53]
	v_mfma_i32_16x16x64_i8 v[50:53], v[190:193], v[198:201], v[50:53]
	v_mfma_i32_16x16x64_i8 v[34:37], v[190:193], v[206:209], v[34:37]
	v_mfma_i32_16x16x64_i8 v[34:37], v[194:197], v[212:215], v[34:37]
	v_mfma_i32_16x16x64_i8 v[38:41], v[186:189], v[212:215], v[38:41]
	v_mfma_i32_16x16x64_i8 v[38:41], v[182:185], v[206:209], v[38:41]
	v_mfma_i32_16x16x64_i8 v[22:25], v[182:185], v[216:219], v[22:25]
	v_mfma_i32_16x16x64_i8 v[22:25], v[186:189], v[220:223], v[22:25]
	v_mfma_i32_16x16x64_i8 v[18:21], v[194:197], v[220:223], v[18:21]
	v_mfma_i32_16x16x64_i8 v[18:21], v[190:193], v[216:219], v[18:21]
	v_mfma_i32_16x16x64_i8 v[2:5], v[190:193], v[224:227], v[2:5]
	v_mfma_i32_16x16x64_i8 v[2:5], v[194:197], v[228:231], v[2:5]
	v_mfma_i32_16x16x64_i8 v[6:9], v[186:189], v[228:231], v[6:9]
	v_mfma_i32_16x16x64_i8 v[6:9], v[182:185], v[224:227], v[6:9]
	s_setprio 0
	s_barrier
	s_add_i32 s50, s50, 2
	s_add_u32 s0, s0, 0x100
	s_addc_u32 s1, s1, 0
	s_add_u32 s47, s47, 0x100
	s_addc_u32 s49, s49, 0
	s_cmp_gt_u32 s50, 29
	s_cbranch_scc0 .LBB0_275
	s_and_b64 vcc, exec, s[44:45]
	s_cbranch_vccz .LBB0_278
	s_barrier

; #define PG8_STAGE(bufoff, gbase, voff) do { _Pragma("unroll") for (int _i = 0; _i < 2; ++_i) \
;         __builtin_amdgcn_global_load_lds((const unsigned*)((const char*)(gbase) + (voff)[_i]), (PG8_LAS unsigned*)(lds + (bufoff) + ldsw + _i * 8192), 16, 0, 0); } while (0)
; #define PG8_LDA(dst, b, h) do { _Pragma("unroll") for (int m = 0; m < 4; ++m) _Pragma("unroll") for (int k = 0; k < 2; ++k) dst[m][k] = *(const PG8_LAS bf16x8*)(lds + PG8_SA(b, h) + aoff + m * 2048 + k * 1024); } while (0)
; #define PG8_LDB(dst, b, h) do { _Pragma("unroll") for (int n = 0; n < 2; ++n) _Pragma("unroll") for (int k = 0; k < 2; ++k) dst[n][k] = *(const PG8_LAS bf16x8*)(lds + PG8_SB(b, h) + boff + n * 2048 + k * 1024); } while (0)
; #define PG8_MMA(ai, bj, At, Bt) do { __builtin_amdgcn_s_setprio(1); _Pragma("unroll") for (int m = 0; m < 4; ++m) _Pragma("unroll") for (int n = 0; n < 2; ++n) _Pragma("unroll") for (int k = 0; k < 2; ++k) \
;         acc[ai][bj][m][n] = mma16(Bt[n][k], At[m][k], acc[ai][bj][m][n]); __builtin_amdgcn_s_setprio(0); } while (0)
; #define PG8_WAIT_V(n) asm volatile("s_waitcnt vmcnt(" #n ")" ::: "memory")
; #define PG8_WAIT_L(n) asm volatile("s_waitcnt lgkmcnt(" #n ")" ::: "memory")
; template <class Epi, class Sched, bool ALIGN_EPI = false, bool SP2 = false>
; __device__ __forceinline__ void gemm_phase(PG8_LAS unsigned char* lds, const Gemm g, const Sched& S, const Epi& E) {
;     ...
;         for (int t = 0; t < nt; t += 2) {
;             const bool last = (t == nt - 2);
;             const char* a1 = cA + (size_t)(t + 1) * kstep;
;             const char* a2 = last ? nA : cA + (size_t)(t + 2) * kstep; const char* b2 = last ? nB : cB + (size_t)(t + 2) * kstep;
;             const char* a3 = a2 + kstep; const char* b3 = b2 + kstep;
;             if (last && has_next) S.a_ready(nxt);
;             if constexpr (SP2) {
;             PG8_LDB(B0, 0, 0); PG8_LDB(B1, 0, 1); PG8_SCHED; PG8_LDA(At, 0, 0); PG8_STAGE(PG8_SA(1, 1), a1 + hstepA, voffA);
;             PG8_WAIT_V(8); PG8_WAIT_L(0); PG8_BAR; PG8_MMA(0, 0, At, B0); PG8_MMA(0, 1, At, B1); PG8_BAR; PG8_SCHED;
;             PG8_LDA(At, 0, 1); PG8_STAGE(PG8_SB(0, 0), b2, voffB); PG8_STAGE(PG8_SB(0, 1), b2 + hstepB, voffB); PG8_STAGE(PG8_SA(0, 0), a2, voffA);
;             PG8_WAIT_V(8); PG8_WAIT_L(0); PG8_BAR; PG8_MMA(1, 0, At, B0); PG8_MMA(1, 1, At, B1); PG8_BAR; PG8_SCHED;
.LBB0_389:
	ds_read_b128 v[154:157], v150
	ds_read_b128 v[158:161], v150 offset:1024
	ds_read_b128 v[162:165], v150 offset:2048
	ds_read_b128 v[166:169], v150 offset:3072
	ds_read_b128 v[170:173], v151
	ds_read_b128 v[174:177], v151 offset:1024
	ds_read_b128 v[182:185], v151 offset:2048
	ds_read_b128 v[186:189], v151 offset:3072
	s_add_u32 s33, s0, 0xfff00080
	s_addc_u32 s35, s1, -1
	s_cmp_eq_u32 s29, 12
	s_cselect_b32 s59, s49, s35
	s_cselect_b32 s58, s48, s33
	s_cselect_b32 s55, s25, s28
	s_cselect_b32 s54, s26, s27
	v_lshl_add_u64 v[146:147], s[0:1], 0, v[138:139]
	s_add_i32 m0, s12, 0xc000
	ds_read_b128 v[190:193], v152
	ds_read_b128 v[194:197], v152 offset:1024
	ds_read_b128 v[198:201], v152 offset:2048
	ds_read_b128 v[202:205], v152 offset:3072
	ds_read_b128 v[206:209], v152 offset:4096
	ds_read_b128 v[212:215], v152 offset:5120
	ds_read_b128 v[216:219], v152 offset:6144
	ds_read_b128 v[220:223], v152 offset:7168
	global_load_lds_dwordx4 v[146:147], off
	v_lshl_add_u64 v[146:147], s[0:1], 0, v[140:141]
	s_add_i32 m0, s12, 0xe000
	s_nop 0
	global_load_lds_dwordx4 v[146:147], off
	s_waitcnt vmcnt(8)
	s_waitcnt lgkmcnt(0)
	s_barrier
	s_setprio 1
	s_waitcnt lgkmcnt(0)
	v_mfma_f32_16x16x32_bf16 v[126:129], v[154:157], v[190:193], v[126:129]
	v_mfma_f32_16x16x32_bf16 v[126:129], v[158:161], v[194:197], v[126:129]
	v_mfma_f32_16x16x32_bf16 v[122:125], v[166:169], v[194:197], v[122:125]
	v_mfma_f32_16x16x32_bf16 v[122:125], v[162:165], v[190:193], v[122:125]
	v_mfma_f32_16x16x32_bf16 v[110:113], v[162:165], v[198:201], v[110:113]
	v_mfma_f32_16x16x32_bf16 v[110:113], v[166:169], v[202:205], v[110:113]
	v_mfma_f32_16x16x32_bf16 v[118:121], v[158:161], v[202:205], v[118:121]
	v_mfma_f32_16x16x32_bf16 v[118:121], v[154:157], v[198:201], v[118:121]
	v_mfma_f32_16x16x32_bf16 v[102:105], v[154:157], v[206:209], v[102:105]
	v_mfma_f32_16x16x32_bf16 v[102:105], v[158:161], v[212:215], v[102:105]
	v_mfma_f32_16x16x32_bf16 v[94:97], v[166:169], v[212:215], v[94:97]
	v_mfma_f32_16x16x32_bf16 v[94:97], v[162:165], v[206:209], v[94:97]
	v_mfma_f32_16x16x32_bf16 v[78:81], v[162:165], v[216:219], v[78:81]
	v_mfma_f32_16x16x32_bf16 v[78:81], v[166:169], v[220:223], v[78:81]
	v_mfma_f32_16x16x32_bf16 v[86:89], v[158:161], v[220:223], v[86:89]
	v_mfma_f32_16x16x32_bf16 v[86:89], v[154:157], v[216:219], v[86:89]
	s_setprio 0
	s_setprio 1
	v_mfma_f32_16x16x32_bf16 v[114:117], v[170:173], v[190:193], v[114:117]
	v_mfma_f32_16x16x32_bf16 v[114:117], v[174:177], v[194:197], v[114:117]
	v_mfma_f32_16x16x32_bf16 v[106:109], v[186:189], v[194:197], v[106:109]
	v_mfma_f32_16x16x32_bf16 v[106:109], v[182:185], v[190:193], v[106:109]
	v_mfma_f32_16x16x32_bf16 v[90:93], v[182:185], v[198:201], v[90:93]
	v_mfma_f32_16x16x32_bf16 v[90:93], v[186:189], v[202:205], v[90:93]
	v_mfma_f32_16x16x32_bf16 v[98:101], v[174:177], v[202:205], v[98:101]
	v_mfma_f32_16x16x32_bf16 v[98:101], v[170:173], v[198:201], v[98:101]
	v_mfma_f32_16x16x32_bf16 v[82:85], v[170:173], v[206:209], v[82:85]
	v_mfma_f32_16x16x32_bf16 v[82:85], v[174:177], v[212:215], v[82:85]
	v_mfma_f32_16x16x32_bf16 v[74:77], v[186:189], v[212:215], v[74:77]
	v_mfma_f32_16x16x32_bf16 v[74:77], v[182:185], v[206:209], v[74:77]
	v_mfma_f32_16x16x32_bf16 v[66:69], v[182:185], v[216:219], v[66:69]
	v_mfma_f32_16x16x32_bf16 v[66:69], v[186:189], v[220:223], v[66:69]
	v_mfma_f32_16x16x32_bf16 v[70:73], v[174:177], v[220:223], v[70:73]
	v_mfma_f32_16x16x32_bf16 v[70:73], v[170:173], v[216:219], v[70:73]
	s_setprio 0
	s_barrier
	s_add_i32 s33, s22, s7
	v_lshl_add_u64 v[146:147], s[54:55], 0, v[132:133]
	s_mov_b32 m0, s33
	ds_read_b128 v[190:193], v152 offset:16384
	ds_read_b128 v[194:197], v152 offset:17408
	ds_read_b128 v[198:201], v152 offset:18432
	ds_read_b128 v[202:205], v152 offset:19456
	ds_read_b128 v[206:209], v152 offset:20480
	ds_read_b128 v[212:215], v152 offset:21504
	ds_read_b128 v[216:219], v152 offset:22528
	ds_read_b128 v[220:223], v152 offset:23552
	global_load_lds_dwordx4 v[146:147], off
	s_add_i32 m0, s33, 0x2000
	s_add_u32 s36, s54, 0x40000
	v_lshl_add_u64 v[224:225], s[54:55], 0, v[136:137]
	s_addc_u32 s37, s55, 0
	s_add_i32 s33, s23, s7
	global_load_lds_dwordx4 v[224:225], off
	v_lshl_add_u64 v[226:227], s[36:37], 0, v[132:133]
	s_mov_b32 m0, s33
	v_lshl_add_u64 v[228:229], s[58:59], 0, v[134:135]
	global_load_lds_dwordx4 v[226:227], off
	v_lshl_add_u64 v[226:227], s[36:37], 0, v[136:137]
	s_add_i32 m0, s33, 0x2000
	s_nop 0
	global_load_lds_dwordx4 v[226:227], off
	v_lshl_add_u64 v[226:227], s[58:59], 0, v[130:131]
	s_mov_b32 m0, s12
	s_nop 0
	global_load_lds_dwordx4 v[226:227], off
	s_mov_b32 m0, s13
	s_nop 0
	global_load_lds_dwordx4 v[228:229], off
	s_waitcnt vmcnt(8)
	s_waitcnt lgkmcnt(0)
	s_barrier
; #define PG8_STAGE(bufoff, gbase, voff) do { _Pragma("unroll") for (int _i = 0; _i < 2; ++_i) \
;         __builtin_amdgcn_global_load_lds((const unsigned*)((const char*)(gbase) + (voff)[_i]), (PG8_LAS unsigned*)(lds + (bufoff) + ldsw + _i * 8192), 16, 0, 0); } while (0)
; #define PG8_LDA(dst, b, h) do { _Pragma("unroll") for (int m = 0; m < 4; ++m) _Pragma("unroll") for (int k = 0; k < 2; ++k) dst[m][k] = *(const PG8_LAS bf16x8*)(lds + PG8_SA(b, h) + aoff + m * 2048 + k * 1024); } while (0)
; #define PG8_LDB(dst, b, h) do { _Pragma("unroll") for (int n = 0; n < 2; ++n) _Pragma("unroll") for (int k = 0; k < 2; ++k) dst[n][k] = *(const PG8_LAS bf16x8*)(lds + PG8_SB(b, h) + boff + n * 2048 + k * 1024); } while (0)
; #define PG8_MMA(ai, bj, At, Bt) do { __builtin_amdgcn_s_setprio(1); _Pragma("unroll") for (int m = 0; m < 4; ++m) _Pragma("unroll") for (int n = 0; n < 2; ++n) _Pragma("unroll") for (int k = 0; k < 2; ++k) \
;         acc[ai][bj][m][n] = mma16(Bt[n][k], At[m][k], acc[ai][bj][m][n]); __builtin_amdgcn_s_setprio(0); } while (0)
; #define PG8_WAIT_V(n) asm volatile("s_waitcnt vmcnt(" #n ")" ::: "memory")
; #define PG8_WAIT_L(n) asm volatile("s_waitcnt lgkmcnt(" #n ")" ::: "memory")
; #define PG8_BAR __builtin_amdgcn_s_barrier()
; #define PG8_SCHED __builtin_amdgcn_sched_barrier(0)
; template <class Epi, class Sched, bool ALIGN_EPI = false, bool SP2 = false>
; __device__ __forceinline__ void gemm_phase(PG8_LAS unsigned char* lds, const Gemm g, const Sched& S, const Epi& E) {
;     ...
;             PG8_WAIT_V(8); PG8_WAIT_L(0); PG8_BAR; PG8_MMA(1, 0, At, B0); PG8_MMA(1, 1, At, B1); PG8_BAR; PG8_SCHED;
;             PG8_LDB(B0, 1, 0); PG8_LDB(B1, 1, 1); PG8_SCHED; PG8_LDA(At, 1, 0); PG8_STAGE(PG8_SA(0, 1), a2 + hstepA, voffA);
;             PG8_WAIT_V(8); PG8_WAIT_L(0); PG8_BAR; PG8_MMA(0, 0, At, B0); PG8_MMA(0, 1, At, B1); PG8_BAR; PG8_SCHED;
	s_setprio 1
	s_waitcnt lgkmcnt(0)
	v_mfma_f32_16x16x32_bf16 v[62:65], v[154:157], v[190:193], v[62:65]
	v_mfma_f32_16x16x32_bf16 v[62:65], v[158:161], v[194:197], v[62:65]
	v_mfma_f32_16x16x32_bf16 v[58:61], v[166:169], v[194:197], v[58:61]
	v_mfma_f32_16x16x32_bf16 v[58:61], v[162:165], v[190:193], v[58:61]
	v_mfma_f32_16x16x32_bf16 v[46:49], v[162:165], v[198:201], v[46:49]
	v_mfma_f32_16x16x32_bf16 v[46:49], v[166:169], v[202:205], v[46:49]
	v_mfma_f32_16x16x32_bf16 v[54:57], v[158:161], v[202:205], v[54:57]
	v_mfma_f32_16x16x32_bf16 v[54:57], v[154:157], v[198:201], v[54:57]
	v_mfma_f32_16x16x32_bf16 v[38:41], v[154:157], v[206:209], v[38:41]
	v_mfma_f32_16x16x32_bf16 v[38:41], v[158:161], v[212:215], v[38:41]
	v_mfma_f32_16x16x32_bf16 v[30:33], v[166:169], v[212:215], v[30:33]
	v_mfma_f32_16x16x32_bf16 v[30:33], v[162:165], v[206:209], v[30:33]
	v_mfma_f32_16x16x32_bf16 v[14:17], v[162:165], v[216:219], v[14:17]
	v_mfma_f32_16x16x32_bf16 v[14:17], v[166:169], v[220:223], v[14:17]
	v_mfma_f32_16x16x32_bf16 v[22:25], v[158:161], v[220:223], v[22:25]
	v_mfma_f32_16x16x32_bf16 v[22:25], v[154:157], v[216:219], v[22:25]
	s_setprio 0
	s_setprio 1
	v_mfma_f32_16x16x32_bf16 v[50:53], v[170:173], v[190:193], v[50:53]
	v_mfma_f32_16x16x32_bf16 v[50:53], v[174:177], v[194:197], v[50:53]
	v_mfma_f32_16x16x32_bf16 v[42:45], v[186:189], v[194:197], v[42:45]
	v_mfma_f32_16x16x32_bf16 v[42:45], v[182:185], v[190:193], v[42:45]
	v_mfma_f32_16x16x32_bf16 v[26:29], v[182:185], v[198:201], v[26:29]
	v_mfma_f32_16x16x32_bf16 v[26:29], v[186:189], v[202:205], v[26:29]
	v_mfma_f32_16x16x32_bf16 v[34:37], v[174:177], v[202:205], v[34:37]
	v_mfma_f32_16x16x32_bf16 v[34:37], v[170:173], v[198:201], v[34:37]
	v_mfma_f32_16x16x32_bf16 v[18:21], v[170:173], v[206:209], v[18:21]
	v_mfma_f32_16x16x32_bf16 v[18:21], v[174:177], v[212:215], v[18:21]
	v_mfma_f32_16x16x32_bf16 v[10:13], v[186:189], v[212:215], v[10:13]
	v_mfma_f32_16x16x32_bf16 v[10:13], v[182:185], v[206:209], v[10:13]
	v_mfma_f32_16x16x32_bf16 v[2:5], v[182:185], v[216:219], v[2:5]
	v_mfma_f32_16x16x32_bf16 v[2:5], v[186:189], v[220:223], v[2:5]
	v_mfma_f32_16x16x32_bf16 v[6:9], v[174:177], v[220:223], v[6:9]
	v_mfma_f32_16x16x32_bf16 v[6:9], v[170:173], v[216:219], v[6:9]
	s_setprio 0
	s_barrier
	s_add_i32 s33, 0, 0x18000
	v_add_u32_e32 v153, s33, v148
	s_add_i32 s35, 0, 0x1c000
	ds_read_b128 v[154:157], v153
	ds_read_b128 v[158:161], v153 offset:1024
	ds_read_b128 v[162:165], v153 offset:2048
	ds_read_b128 v[166:169], v153 offset:3072
	v_add_u32_e32 v153, s35, v148
	ds_read_b128 v[170:173], v153
	ds_read_b128 v[174:177], v153 offset:1024
	ds_read_b128 v[182:185], v153 offset:2048
	ds_read_b128 v[186:189], v153 offset:3072
	s_add_u32 s36, s58, 0x100000
	s_addc_u32 s37, s59, 0
	s_mov_b32 m0, s16
	v_lshl_add_u64 v[230:231], s[36:37], 0, v[130:131]
	ds_read_b128 v[190:193], v152 offset:32768
	ds_read_b128 v[194:197], v152 offset:33792
	ds_read_b128 v[198:201], v152 offset:34816
	ds_read_b128 v[202:205], v152 offset:35840
	ds_read_b128 v[206:209], v152 offset:36864
	ds_read_b128 v[212:215], v152 offset:37888
	ds_read_b128 v[216:219], v152 offset:38912
	ds_read_b128 v[220:223], v152 offset:39936
	global_load_lds_dwordx4 v[230:231], off
	v_lshl_add_u64 v[230:231], s[36:37], 0, v[134:135]
	s_mov_b32 m0, s17
	s_nop 0
	global_load_lds_dwordx4 v[230:231], off
	s_waitcnt vmcnt(8)
	s_waitcnt lgkmcnt(0)
	s_barrier
	s_setprio 1
	s_waitcnt lgkmcnt(0)
	v_mfma_f32_16x16x32_bf16 v[126:129], v[154:157], v[190:193], v[126:129]
	v_mfma_f32_16x16x32_bf16 v[126:129], v[158:161], v[194:197], v[126:129]
	v_mfma_f32_16x16x32_bf16 v[122:125], v[166:169], v[194:197], v[122:125]
	v_mfma_f32_16x16x32_bf16 v[122:125], v[162:165], v[190:193], v[122:125]
	v_mfma_f32_16x16x32_bf16 v[110:113], v[162:165], v[198:201], v[110:113]
	v_mfma_f32_16x16x32_bf16 v[110:113], v[166:169], v[202:205], v[110:113]
	v_mfma_f32_16x16x32_bf16 v[118:121], v[158:161], v[202:205], v[118:121]
	v_mfma_f32_16x16x32_bf16 v[118:121], v[154:157], v[198:201], v[118:121]
	v_mfma_f32_16x16x32_bf16 v[102:105], v[154:157], v[206:209], v[102:105]
	v_mfma_f32_16x16x32_bf16 v[102:105], v[158:161], v[212:215], v[102:105]
	v_mfma_f32_16x16x32_bf16 v[94:97], v[166:169], v[212:215], v[94:97]
	v_mfma_f32_16x16x32_bf16 v[94:97], v[162:165], v[206:209], v[94:97]
	v_mfma_f32_16x16x32_bf16 v[78:81], v[162:165], v[216:219], v[78:81]
	v_mfma_f32_16x16x32_bf16 v[78:81], v[166:169], v[220:223], v[78:81]
	v_mfma_f32_16x16x32_bf16 v[86:89], v[158:161], v[220:223], v[86:89]
	v_mfma_f32_16x16x32_bf16 v[86:89], v[154:157], v[216:219], v[86:89]
	s_setprio 0
	s_setprio 1
	v_mfma_f32_16x16x32_bf16 v[114:117], v[170:173], v[190:193], v[114:117]
	v_mfma_f32_16x16x32_bf16 v[114:117], v[174:177], v[194:197], v[114:117]
	v_mfma_f32_16x16x32_bf16 v[106:109], v[186:189], v[194:197], v[106:109]
	v_mfma_f32_16x16x32_bf16 v[106:109], v[182:185], v[190:193], v[106:109]
	v_mfma_f32_16x16x32_bf16 v[90:93], v[182:185], v[198:201], v[90:93]
	v_mfma_f32_16x16x32_bf16 v[90:93], v[186:189], v[202:205], v[90:93]
	v_mfma_f32_16x16x32_bf16 v[98:101], v[174:177], v[202:205], v[98:101]
	v_mfma_f32_16x16x32_bf16 v[98:101], v[170:173], v[198:201], v[98:101]
	v_mfma_f32_16x16x32_bf16 v[82:85], v[170:173], v[206:209], v[82:85]
	v_mfma_f32_16x16x32_bf16 v[82:85], v[174:177], v[212:215], v[82:85]
	v_mfma_f32_16x16x32_bf16 v[74:77], v[186:189], v[212:215], v[74:77]
	v_mfma_f32_16x16x32_bf16 v[74:77], v[182:185], v[206:209], v[74:77]
	v_mfma_f32_16x16x32_bf16 v[66:69], v[182:185], v[216:219], v[66:69]
	v_mfma_f32_16x16x32_bf16 v[66:69], v[186:189], v[220:223], v[66:69]
	v_mfma_f32_16x16x32_bf16 v[70:73], v[174:177], v[220:223], v[70:73]
	v_mfma_f32_16x16x32_bf16 v[70:73], v[170:173], v[216:219], v[70:73]
	s_setprio 0
	s_barrier
; #define PG8_STAGE(bufoff, gbase, voff) do { _Pragma("unroll") for (int _i = 0; _i < 2; ++_i) \
;         __builtin_amdgcn_global_load_lds((const unsigned*)((const char*)(gbase) + (voff)[_i]), (PG8_LAS unsigned*)(lds + (bufoff) + ldsw + _i * 8192), 16, 0, 0); } while (0)
; #define PG8_LDA(dst, b, h) do { _Pragma("unroll") for (int m = 0; m < 4; ++m) _Pragma("unroll") for (int k = 0; k < 2; ++k) dst[m][k] = *(const PG8_LAS bf16x8*)(lds + PG8_SA(b, h) + aoff + m * 2048 + k * 1024); } while (0)
; #define PG8_MMA(ai, bj, At, Bt) do { __builtin_amdgcn_s_setprio(1); _Pragma("unroll") for (int m = 0; m < 4; ++m) _Pragma("unroll") for (int n = 0; n < 2; ++n) _Pragma("unroll") for (int k = 0; k < 2; ++k) \
;         acc[ai][bj][m][n] = mma16(Bt[n][k], At[m][k], acc[ai][bj][m][n]); __builtin_amdgcn_s_setprio(0); } while (0)
; #define PG8_WAIT_V(n) asm volatile("s_waitcnt vmcnt(" #n ")" ::: "memory")
; #define PG8_WAIT_L(n) asm volatile("s_waitcnt lgkmcnt(" #n ")" ::: "memory")
; #define PG8_BAR __builtin_amdgcn_s_barrier()
; #define PG8_SCHED __builtin_amdgcn_sched_barrier(0)
; template <class Epi, class Sched, bool ALIGN_EPI = false, bool SP2 = false>
; __device__ __forceinline__ void gemm_phase(PG8_LAS unsigned char* lds, const Gemm g, const Sched& S, const Epi& E) {
;     ...
;         for (int t = 0; t < nt; t += 2) {
;     ...
;             PG8_LDA(At, 1, 1); PG8_STAGE(PG8_SB(1, 0), b3, voffB); PG8_STAGE(PG8_SB(1, 1), b3 + hstepB, voffB); PG8_STAGE(PG8_SA(1, 0), a3, voffA);
;             PG8_WAIT_V(8); PG8_WAIT_L(0); PG8_BAR; PG8_MMA(1, 0, At, B0); PG8_MMA(1, 1, At, B1); PG8_BAR; PG8_SCHED;
;     ...
;         if constexpr (ALIGN_EPI) { if (wr == 0) PG8_BAR; }
	s_add_i32 s33, s33, s7
	v_lshl_add_u64 v[146:147], v[146:147], 0, s[38:39]
	s_mov_b32 m0, s33
	ds_read_b128 v[190:193], v152 offset:49152
	ds_read_b128 v[194:197], v152 offset:50176
	ds_read_b128 v[198:201], v152 offset:51200
	ds_read_b128 v[202:205], v152 offset:52224
	ds_read_b128 v[206:209], v152 offset:53248
	ds_read_b128 v[212:215], v152 offset:54272
	ds_read_b128 v[216:219], v152 offset:55296
	ds_read_b128 v[220:223], v152 offset:56320
	global_load_lds_dwordx4 v[146:147], off
	s_add_i32 m0, s33, 0x2000
	s_add_u32 s36, s54, 0x40080
	v_lshl_add_u64 v[146:147], v[224:225], 0, s[38:39]
	s_addc_u32 s37, s55, 0
	s_add_i32 s33, s35, s7
	global_load_lds_dwordx4 v[146:147], off
	v_lshl_add_u64 v[146:147], s[36:37], 0, v[132:133]
	s_mov_b32 m0, s33
	s_nop 0
	global_load_lds_dwordx4 v[146:147], off
	v_lshl_add_u64 v[146:147], s[36:37], 0, v[136:137]
	s_add_i32 m0, s33, 0x2000
	s_nop 0
	global_load_lds_dwordx4 v[146:147], off
	v_lshl_add_u64 v[146:147], v[226:227], 0, s[38:39]
	s_mov_b32 m0, s19
	s_nop 0
	global_load_lds_dwordx4 v[146:147], off
	v_lshl_add_u64 v[146:147], v[228:229], 0, s[38:39]
	s_mov_b32 m0, s20
	s_nop 0
	global_load_lds_dwordx4 v[146:147], off
	s_waitcnt vmcnt(8)
	s_waitcnt lgkmcnt(0)
	s_barrier
	s_setprio 1
	s_waitcnt lgkmcnt(0)
	v_mfma_f32_16x16x32_bf16 v[62:65], v[154:157], v[190:193], v[62:65]
	v_mfma_f32_16x16x32_bf16 v[62:65], v[158:161], v[194:197], v[62:65]
	v_mfma_f32_16x16x32_bf16 v[58:61], v[166:169], v[194:197], v[58:61]
	v_mfma_f32_16x16x32_bf16 v[58:61], v[162:165], v[190:193], v[58:61]
	v_mfma_f32_16x16x32_bf16 v[46:49], v[162:165], v[198:201], v[46:49]
	v_mfma_f32_16x16x32_bf16 v[46:49], v[166:169], v[202:205], v[46:49]
	v_mfma_f32_16x16x32_bf16 v[54:57], v[158:161], v[202:205], v[54:57]
	v_mfma_f32_16x16x32_bf16 v[54:57], v[154:157], v[198:201], v[54:57]
	v_mfma_f32_16x16x32_bf16 v[38:41], v[154:157], v[206:209], v[38:41]
	v_mfma_f32_16x16x32_bf16 v[38:41], v[158:161], v[212:215], v[38:41]
	v_mfma_f32_16x16x32_bf16 v[30:33], v[166:169], v[212:215], v[30:33]
	v_mfma_f32_16x16x32_bf16 v[30:33], v[162:165], v[206:209], v[30:33]
	v_mfma_f32_16x16x32_bf16 v[14:17], v[162:165], v[216:219], v[14:17]
	v_mfma_f32_16x16x32_bf16 v[14:17], v[166:169], v[220:223], v[14:17]
	v_mfma_f32_16x16x32_bf16 v[22:25], v[158:161], v[220:223], v[22:25]
	v_mfma_f32_16x16x32_bf16 v[22:25], v[154:157], v[216:219], v[22:25]
	s_setprio 0
	s_setprio 1
	v_mfma_f32_16x16x32_bf16 v[50:53], v[170:173], v[190:193], v[50:53]
	v_mfma_f32_16x16x32_bf16 v[50:53], v[174:177], v[194:197], v[50:53]
	v_mfma_f32_16x16x32_bf16 v[42:45], v[186:189], v[194:197], v[42:45]
	v_mfma_f32_16x16x32_bf16 v[42:45], v[182:185], v[190:193], v[42:45]
	v_mfma_f32_16x16x32_bf16 v[26:29], v[182:185], v[198:201], v[26:29]
	v_mfma_f32_16x16x32_bf16 v[26:29], v[186:189], v[202:205], v[26:29]
	v_mfma_f32_16x16x32_bf16 v[34:37], v[174:177], v[202:205], v[34:37]
	v_mfma_f32_16x16x32_bf16 v[34:37], v[170:173], v[198:201], v[34:37]
	v_mfma_f32_16x16x32_bf16 v[18:21], v[170:173], v[206:209], v[18:21]
	v_mfma_f32_16x16x32_bf16 v[18:21], v[174:177], v[212:215], v[18:21]
	v_mfma_f32_16x16x32_bf16 v[10:13], v[186:189], v[212:215], v[10:13]
	v_mfma_f32_16x16x32_bf16 v[10:13], v[182:185], v[206:209], v[10:13]
	v_mfma_f32_16x16x32_bf16 v[2:5], v[182:185], v[216:219], v[2:5]
	v_mfma_f32_16x16x32_bf16 v[2:5], v[186:189], v[220:223], v[2:5]
	v_mfma_f32_16x16x32_bf16 v[6:9], v[174:177], v[220:223], v[6:9]
	v_mfma_f32_16x16x32_bf16 v[6:9], v[170:173], v[216:219], v[6:9]
	s_setprio 0
	s_barrier
	s_add_i32 s29, s29, 2
	s_add_u32 s0, s0, 0x100
	s_addc_u32 s1, s1, 0
	s_add_u32 s27, s27, 0x100
	s_addc_u32 s28, s28, 0
	s_cmp_gt_u32 s29, 13
	s_cbranch_scc0 .LBB0_389
	s_and_b64 vcc, exec, s[40:41]
	s_cbranch_vccz .LBB0_392
	s_barrier

; #define PG8_STAGE(bufoff, gbase, voff) do { _Pragma("unroll") for (int _i = 0; _i < 2; ++_i) \
;         __builtin_amdgcn_global_load_lds((const unsigned*)((const char*)(gbase) + (voff)[_i]), (PG8_LAS unsigned*)(lds + (bufoff) + ldsw + _i * 8192), 16, 0, 0); } while (0)
; #define PG8_LDA(dst, b, h) do { _Pragma("unroll") for (int m = 0; m < 4; ++m) _Pragma("unroll") for (int k = 0; k < 2; ++k) dst[m][k] = *(const PG8_LAS bf16x8*)(lds + PG8_SA(b, h) + aoff + m * 2048 + k * 1024); } while (0)
; #define PG8_LDB(dst, b, h) do { _Pragma("unroll") for (int n = 0; n < 2; ++n) _Pragma("unroll") for (int k = 0; k < 2; ++k) dst[n][k] = *(const PG8_LAS bf16x8*)(lds + PG8_SB(b, h) + boff + n * 2048 + k * 1024); } while (0)
; #define PG8_MMA(ai, bj, At, Bt) do { __builtin_amdgcn_s_setprio(1); _Pragma("unroll") for (int m = 0; m < 4; ++m) _Pragma("unroll") for (int n = 0; n < 2; ++n) _Pragma("unroll") for (int k = 0; k < 2; ++k) \
;         acc[ai][bj][m][n] = mma16(Bt[n][k], At[m][k], acc[ai][bj][m][n]); __builtin_amdgcn_s_setprio(0); } while (0)
; #define PG8_WAIT_V(n) asm volatile("s_waitcnt vmcnt(" #n ")" ::: "memory")
; #define PG8_WAIT_L(n) asm volatile("s_waitcnt lgkmcnt(" #n ")" ::: "memory")
; template <class Epi, class Sched, bool ALIGN_EPI = false, bool SP2 = false>
; __device__ __forceinline__ void gemm_phase(PG8_LAS unsigned char* lds, const Gemm g, const Sched& S, const Epi& E) {
;     ...
;         for (int t = 0; t < nt; t += 2) {
;             const bool last = (t == nt - 2);
;             const char* a1 = cA + (size_t)(t + 1) * kstep;
;             const char* a2 = last ? nA : cA + (size_t)(t + 2) * kstep; const char* b2 = last ? nB : cB + (size_t)(t + 2) * kstep;
;             const char* a3 = a2 + kstep; const char* b3 = b2 + kstep;
;             if (last && has_next) S.a_ready(nxt);
;             if constexpr (SP2) {
;             PG8_LDB(B0, 0, 0); PG8_LDB(B1, 0, 1); PG8_SCHED; PG8_LDA(At, 0, 0); PG8_STAGE(PG8_SA(1, 1), a1 + hstepA, voffA);
;             PG8_WAIT_V(8); PG8_WAIT_L(0); PG8_BAR; PG8_MMA(0, 0, At, B0); PG8_MMA(0, 1, At, B1); PG8_BAR; PG8_SCHED;
;             PG8_LDA(At, 0, 1); PG8_STAGE(PG8_SB(0, 0), b2, voffB); PG8_STAGE(PG8_SB(0, 1), b2 + hstepB, voffB); PG8_STAGE(PG8_SA(0, 0), a2, voffA);
;             PG8_WAIT_V(8); PG8_WAIT_L(0); PG8_BAR; PG8_MMA(1, 0, At, B0); PG8_MMA(1, 1, At, B1); PG8_BAR; PG8_SCHED;
.LBB0_555:
	ds_read_b128 v[82:85], v181
	ds_read_b128 v[86:89], v181 offset:1024
	ds_read_b128 v[138:141], v181 offset:2048
	ds_read_b128 v[142:145], v181 offset:3072
	ds_read_b128 v[146:149], v213
	ds_read_b128 v[150:153], v213 offset:1024
	ds_read_b128 v[154:157], v213 offset:2048
	ds_read_b128 v[158:161], v213 offset:3072
	s_add_u32 s47, s62, 0xfff80080
	s_addc_u32 s61, s63, -1
	s_cmp_eq_u32 s46, 28
	s_cselect_b32 s67, s28, s61
	s_cselect_b32 s66, s29, s47
	s_cselect_b32 s65, s33, s37
	s_cselect_b32 s64, s35, s36
	v_lshl_add_u64 v[194:195], s[62:63], 0, v[174:175]
	s_add_i32 m0, s11, 0xc000
	ds_read_b128 v[186:189], v214
	ds_read_b128 v[190:193], v214 offset:1024
	ds_read_b128 v[216:219], v214 offset:2048
	ds_read_b128 v[220:223], v214 offset:3072
	ds_read_b128 v[224:227], v214 offset:4096
	ds_read_b128 v[228:231], v214 offset:5120
	ds_read_b128 v[232:235], v214 offset:6144
	ds_read_b128 v[236:239], v214 offset:7168
	global_load_lds_dwordx4 v[194:195], off
	v_lshl_add_u64 v[194:195], s[62:63], 0, v[176:177]
	s_add_i32 m0, s11, 0xe000
	s_nop 0
	global_load_lds_dwordx4 v[194:195], off
	s_waitcnt vmcnt(8)
	s_waitcnt lgkmcnt(0)
	s_barrier
	s_setprio 1
	s_waitcnt lgkmcnt(0)
	v_mfma_i32_16x16x64_i8 v[70:73], v[82:85], v[186:189], v[70:73]
	v_mfma_i32_16x16x64_i8 v[70:73], v[86:89], v[190:193], v[70:73]
	v_mfma_i32_16x16x64_i8 v[66:69], v[142:145], v[190:193], v[66:69]
	v_mfma_i32_16x16x64_i8 v[66:69], v[138:141], v[186:189], v[66:69]
	v_mfma_i32_16x16x64_i8 v[122:125], v[138:141], v[216:219], v[122:125]
	v_mfma_i32_16x16x64_i8 v[122:125], v[142:145], v[220:223], v[122:125]
	v_mfma_i32_16x16x64_i8 v[126:129], v[86:89], v[220:223], v[126:129]
	v_mfma_i32_16x16x64_i8 v[126:129], v[82:85], v[216:219], v[126:129]
	v_mfma_i32_16x16x64_i8 v[110:113], v[82:85], v[224:227], v[110:113]
	v_mfma_i32_16x16x64_i8 v[110:113], v[86:89], v[228:231], v[110:113]
	v_mfma_i32_16x16x64_i8 v[106:109], v[142:145], v[228:231], v[106:109]
	v_mfma_i32_16x16x64_i8 v[106:109], v[138:141], v[224:227], v[106:109]
	v_mfma_i32_16x16x64_i8 v[90:93], v[138:141], v[232:235], v[90:93]
	v_mfma_i32_16x16x64_i8 v[90:93], v[142:145], v[236:239], v[90:93]
	v_mfma_i32_16x16x64_i8 v[94:97], v[86:89], v[236:239], v[94:97]
	v_mfma_i32_16x16x64_i8 v[94:97], v[82:85], v[232:235], v[94:97]
	s_setprio 0
	s_setprio 1
	v_mfma_i32_16x16x64_i8 v[134:137], v[146:149], v[186:189], v[134:137]
	v_mfma_i32_16x16x64_i8 v[134:137], v[150:153], v[190:193], v[134:137]
	v_mfma_i32_16x16x64_i8 v[130:133], v[158:161], v[190:193], v[130:133]
	v_mfma_i32_16x16x64_i8 v[130:133], v[154:157], v[186:189], v[130:133]
	v_mfma_i32_16x16x64_i8 v[114:117], v[154:157], v[216:219], v[114:117]
	v_mfma_i32_16x16x64_i8 v[114:117], v[158:161], v[220:223], v[114:117]
	v_mfma_i32_16x16x64_i8 v[118:121], v[150:153], v[220:223], v[118:121]
	v_mfma_i32_16x16x64_i8 v[118:121], v[146:149], v[216:219], v[118:121]
	v_mfma_i32_16x16x64_i8 v[102:105], v[146:149], v[224:227], v[102:105]
	v_mfma_i32_16x16x64_i8 v[102:105], v[150:153], v[228:231], v[102:105]
	v_mfma_i32_16x16x64_i8 v[98:101], v[158:161], v[228:231], v[98:101]
	v_mfma_i32_16x16x64_i8 v[98:101], v[154:157], v[224:227], v[98:101]
	v_mfma_i32_16x16x64_i8 v[74:77], v[154:157], v[232:235], v[74:77]
	v_mfma_i32_16x16x64_i8 v[74:77], v[158:161], v[236:239], v[74:77]
	v_mfma_i32_16x16x64_i8 v[78:81], v[150:153], v[236:239], v[78:81]
	v_mfma_i32_16x16x64_i8 v[78:81], v[146:149], v[232:235], v[78:81]
	s_setprio 0
	s_barrier
	s_add_i32 s47, s23, s7
	v_lshl_add_u64 v[194:195], s[64:65], 0, v[164:165]
	s_mov_b32 m0, s47
	ds_read_b128 v[186:189], v214 offset:16384
	ds_read_b128 v[190:193], v214 offset:17408
	ds_read_b128 v[216:219], v214 offset:18432
	ds_read_b128 v[220:223], v214 offset:19456
	ds_read_b128 v[224:227], v214 offset:20480
	ds_read_b128 v[228:231], v214 offset:21504
	ds_read_b128 v[232:235], v214 offset:22528
	ds_read_b128 v[236:239], v214 offset:23552
	global_load_lds_dwordx4 v[194:195], off
	s_add_i32 m0, s47, 0x2000
	s_add_u32 s68, s64, 0x80000
	v_lshl_add_u64 v[240:241], s[64:65], 0, v[168:169]
	s_addc_u32 s69, s65, 0
	s_add_i32 s47, s24, s7
	global_load_lds_dwordx4 v[240:241], off
	v_lshl_add_u64 v[242:243], s[68:69], 0, v[164:165]
	s_mov_b32 m0, s47
	v_lshl_add_u64 v[244:245], s[66:67], 0, v[166:167]
	global_load_lds_dwordx4 v[242:243], off
	v_lshl_add_u64 v[242:243], s[68:69], 0, v[168:169]
	s_add_i32 m0, s47, 0x2000
	s_nop 0
	global_load_lds_dwordx4 v[242:243], off
	v_lshl_add_u64 v[242:243], s[66:67], 0, v[162:163]
	s_mov_b32 m0, s11
	s_nop 0
	global_load_lds_dwordx4 v[242:243], off
	s_mov_b32 m0, s12
	s_nop 0
	global_load_lds_dwordx4 v[244:245], off
	s_waitcnt vmcnt(8)
	s_waitcnt lgkmcnt(0)
	s_barrier
; #define PG8_STAGE(bufoff, gbase, voff) do { _Pragma("unroll") for (int _i = 0; _i < 2; ++_i) \
;         __builtin_amdgcn_global_load_lds((const unsigned*)((const char*)(gbase) + (voff)[_i]), (PG8_LAS unsigned*)(lds + (bufoff) + ldsw + _i * 8192), 16, 0, 0); } while (0)
; #define PG8_LDA(dst, b, h) do { _Pragma("unroll") for (int m = 0; m < 4; ++m) _Pragma("unroll") for (int k = 0; k < 2; ++k) dst[m][k] = *(const PG8_LAS bf16x8*)(lds + PG8_SA(b, h) + aoff + m * 2048 + k * 1024); } while (0)
; #define PG8_LDB(dst, b, h) do { _Pragma("unroll") for (int n = 0; n < 2; ++n) _Pragma("unroll") for (int k = 0; k < 2; ++k) dst[n][k] = *(const PG8_LAS bf16x8*)(lds + PG8_SB(b, h) + boff + n * 2048 + k * 1024); } while (0)
; #define PG8_MMA(ai, bj, At, Bt) do { __builtin_amdgcn_s_setprio(1); _Pragma("unroll") for (int m = 0; m < 4; ++m) _Pragma("unroll") for (int n = 0; n < 2; ++n) _Pragma("unroll") for (int k = 0; k < 2; ++k) \
;         acc[ai][bj][m][n] = mma16(Bt[n][k], At[m][k], acc[ai][bj][m][n]); __builtin_amdgcn_s_setprio(0); } while (0)
; #define PG8_WAIT_V(n) asm volatile("s_waitcnt vmcnt(" #n ")" ::: "memory")
; #define PG8_WAIT_L(n) asm volatile("s_waitcnt lgkmcnt(" #n ")" ::: "memory")
; #define PG8_BAR __builtin_amdgcn_s_barrier()
; #define PG8_SCHED __builtin_amdgcn_sched_barrier(0)
; template <class Epi, class Sched, bool ALIGN_EPI = false, bool SP2 = false>
; __device__ __forceinline__ void gemm_phase(PG8_LAS unsigned char* lds, const Gemm g, const Sched& S, const Epi& E) {
;     ...
;             PG8_WAIT_V(8); PG8_WAIT_L(0); PG8_BAR; PG8_MMA(1, 0, At, B0); PG8_MMA(1, 1, At, B1); PG8_BAR; PG8_SCHED;
;             PG8_LDB(B0, 1, 0); PG8_LDB(B1, 1, 1); PG8_SCHED; PG8_LDA(At, 1, 0); PG8_STAGE(PG8_SA(0, 1), a2 + hstepA, voffA);
;             PG8_WAIT_V(8); PG8_WAIT_L(0); PG8_BAR; PG8_MMA(0, 0, At, B0); PG8_MMA(0, 1, At, B1); PG8_BAR; PG8_SCHED;
	s_setprio 1
	s_waitcnt lgkmcnt(0)
	v_mfma_i32_16x16x64_i8 v[62:65], v[82:85], v[186:189], v[62:65]
	v_mfma_i32_16x16x64_i8 v[62:65], v[86:89], v[190:193], v[62:65]
	v_mfma_i32_16x16x64_i8 v[58:61], v[142:145], v[190:193], v[58:61]
	v_mfma_i32_16x16x64_i8 v[58:61], v[138:141], v[186:189], v[58:61]
	v_mfma_i32_16x16x64_i8 v[42:45], v[138:141], v[216:219], v[42:45]
	v_mfma_i32_16x16x64_i8 v[42:45], v[142:145], v[220:223], v[42:45]
	v_mfma_i32_16x16x64_i8 v[46:49], v[86:89], v[220:223], v[46:49]
	v_mfma_i32_16x16x64_i8 v[46:49], v[82:85], v[216:219], v[46:49]
	v_mfma_i32_16x16x64_i8 v[30:33], v[82:85], v[224:227], v[30:33]
	v_mfma_i32_16x16x64_i8 v[30:33], v[86:89], v[228:231], v[30:33]
	v_mfma_i32_16x16x64_i8 v[26:29], v[142:145], v[228:231], v[26:29]
	v_mfma_i32_16x16x64_i8 v[26:29], v[138:141], v[224:227], v[26:29]
	v_mfma_i32_16x16x64_i8 v[10:13], v[138:141], v[232:235], v[10:13]
	v_mfma_i32_16x16x64_i8 v[10:13], v[142:145], v[236:239], v[10:13]
	v_mfma_i32_16x16x64_i8 v[14:17], v[86:89], v[236:239], v[14:17]
	v_mfma_i32_16x16x64_i8 v[14:17], v[82:85], v[232:235], v[14:17]
	s_setprio 0
	s_setprio 1
	v_mfma_i32_16x16x64_i8 v[54:57], v[146:149], v[186:189], v[54:57]
	v_mfma_i32_16x16x64_i8 v[54:57], v[150:153], v[190:193], v[54:57]
	v_mfma_i32_16x16x64_i8 v[50:53], v[158:161], v[190:193], v[50:53]
	v_mfma_i32_16x16x64_i8 v[50:53], v[154:157], v[186:189], v[50:53]
	v_mfma_i32_16x16x64_i8 v[34:37], v[154:157], v[216:219], v[34:37]
	v_mfma_i32_16x16x64_i8 v[34:37], v[158:161], v[220:223], v[34:37]
	v_mfma_i32_16x16x64_i8 v[38:41], v[150:153], v[220:223], v[38:41]
	v_mfma_i32_16x16x64_i8 v[38:41], v[146:149], v[216:219], v[38:41]
	v_mfma_i32_16x16x64_i8 v[22:25], v[146:149], v[224:227], v[22:25]
	v_mfma_i32_16x16x64_i8 v[22:25], v[150:153], v[228:231], v[22:25]
	v_mfma_i32_16x16x64_i8 v[18:21], v[158:161], v[228:231], v[18:21]
	v_mfma_i32_16x16x64_i8 v[18:21], v[154:157], v[224:227], v[18:21]
	v_mfma_i32_16x16x64_i8 v[2:5], v[154:157], v[232:235], v[2:5]
	v_mfma_i32_16x16x64_i8 v[2:5], v[158:161], v[236:239], v[2:5]
	v_mfma_i32_16x16x64_i8 v[6:9], v[150:153], v[236:239], v[6:9]
	v_mfma_i32_16x16x64_i8 v[6:9], v[146:149], v[232:235], v[6:9]
	s_setprio 0
	s_barrier
	s_add_i32 s47, 0, 0x18000
	s_add_i32 s61, 0, 0x1c000
	v_add_u32_e32 v142, s47, v209
	v_add_u32_e32 v158, s61, v209
	ds_read_b128 v[82:85], v142
	ds_read_b128 v[86:89], v142 offset:1024
	ds_read_b128 v[138:141], v142 offset:2048
	ds_read_b128 v[142:145], v142 offset:3072
	ds_read_b128 v[146:149], v158
	ds_read_b128 v[150:153], v158 offset:1024
	ds_read_b128 v[154:157], v158 offset:2048
	ds_read_b128 v[158:161], v158 offset:3072
	s_add_u32 s66, s66, 0x80000
	s_addc_u32 s67, s67, 0
	s_mov_b32 m0, s13
	v_lshl_add_u64 v[246:247], s[66:67], 0, v[162:163]
	ds_read_b128 v[186:189], v214 offset:32768
	ds_read_b128 v[190:193], v214 offset:33792
	ds_read_b128 v[216:219], v214 offset:34816
	ds_read_b128 v[220:223], v214 offset:35840
	ds_read_b128 v[224:227], v214 offset:36864
	ds_read_b128 v[228:231], v214 offset:37888
	ds_read_b128 v[232:235], v214 offset:38912
	ds_read_b128 v[236:239], v214 offset:39936
	global_load_lds_dwordx4 v[246:247], off
	v_lshl_add_u64 v[246:247], s[66:67], 0, v[166:167]
	s_mov_b32 m0, s16
	s_nop 0
	global_load_lds_dwordx4 v[246:247], off
	s_waitcnt vmcnt(8)
	s_waitcnt lgkmcnt(0)
	s_barrier
	s_setprio 1
	s_waitcnt lgkmcnt(0)
	v_mfma_i32_16x16x64_i8 v[70:73], v[82:85], v[186:189], v[70:73]
	v_mfma_i32_16x16x64_i8 v[70:73], v[86:89], v[190:193], v[70:73]
	v_mfma_i32_16x16x64_i8 v[66:69], v[142:145], v[190:193], v[66:69]
	v_mfma_i32_16x16x64_i8 v[66:69], v[138:141], v[186:189], v[66:69]
	v_mfma_i32_16x16x64_i8 v[122:125], v[138:141], v[216:219], v[122:125]
	v_mfma_i32_16x16x64_i8 v[122:125], v[142:145], v[220:223], v[122:125]
	v_mfma_i32_16x16x64_i8 v[126:129], v[86:89], v[220:223], v[126:129]
	v_mfma_i32_16x16x64_i8 v[126:129], v[82:85], v[216:219], v[126:129]
	v_mfma_i32_16x16x64_i8 v[110:113], v[82:85], v[224:227], v[110:113]
	v_mfma_i32_16x16x64_i8 v[110:113], v[86:89], v[228:231], v[110:113]
	v_mfma_i32_16x16x64_i8 v[106:109], v[142:145], v[228:231], v[106:109]
	v_mfma_i32_16x16x64_i8 v[106:109], v[138:141], v[224:227], v[106:109]
	v_mfma_i32_16x16x64_i8 v[90:93], v[138:141], v[232:235], v[90:93]
	v_mfma_i32_16x16x64_i8 v[90:93], v[142:145], v[236:239], v[90:93]
	v_mfma_i32_16x16x64_i8 v[94:97], v[86:89], v[236:239], v[94:97]
	v_mfma_i32_16x16x64_i8 v[94:97], v[82:85], v[232:235], v[94:97]
	s_setprio 0
	s_setprio 1
	v_mfma_i32_16x16x64_i8 v[134:137], v[146:149], v[186:189], v[134:137]
	v_mfma_i32_16x16x64_i8 v[134:137], v[150:153], v[190:193], v[134:137]
	v_mfma_i32_16x16x64_i8 v[130:133], v[158:161], v[190:193], v[130:133]
	v_mfma_i32_16x16x64_i8 v[130:133], v[154:157], v[186:189], v[130:133]
	v_mfma_i32_16x16x64_i8 v[114:117], v[154:157], v[216:219], v[114:117]
	v_mfma_i32_16x16x64_i8 v[114:117], v[158:161], v[220:223], v[114:117]
	v_mfma_i32_16x16x64_i8 v[118:121], v[150:153], v[220:223], v[118:121]
	v_mfma_i32_16x16x64_i8 v[118:121], v[146:149], v[216:219], v[118:121]
	v_mfma_i32_16x16x64_i8 v[102:105], v[146:149], v[224:227], v[102:105]
	v_mfma_i32_16x16x64_i8 v[102:105], v[150:153], v[228:231], v[102:105]
	v_mfma_i32_16x16x64_i8 v[98:101], v[158:161], v[228:231], v[98:101]
	v_mfma_i32_16x16x64_i8 v[98:101], v[154:157], v[224:227], v[98:101]
	v_mfma_i32_16x16x64_i8 v[74:77], v[154:157], v[232:235], v[74:77]
	v_mfma_i32_16x16x64_i8 v[74:77], v[158:161], v[236:239], v[74:77]
	v_mfma_i32_16x16x64_i8 v[78:81], v[150:153], v[236:239], v[78:81]
	v_mfma_i32_16x16x64_i8 v[78:81], v[146:149], v[232:235], v[78:81]
	s_setprio 0
	s_barrier
; #define PG8_STAGE(bufoff, gbase, voff) do { _Pragma("unroll") for (int _i = 0; _i < 2; ++_i) \
;         __builtin_amdgcn_global_load_lds((const unsigned*)((const char*)(gbase) + (voff)[_i]), (PG8_LAS unsigned*)(lds + (bufoff) + ldsw + _i * 8192), 16, 0, 0); } while (0)
; #define PG8_LDA(dst, b, h) do { _Pragma("unroll") for (int m = 0; m < 4; ++m) _Pragma("unroll") for (int k = 0; k < 2; ++k) dst[m][k] = *(const PG8_LAS bf16x8*)(lds + PG8_SA(b, h) + aoff + m * 2048 + k * 1024); } while (0)
; #define PG8_MMA(ai, bj, At, Bt) do { __builtin_amdgcn_s_setprio(1); _Pragma("unroll") for (int m = 0; m < 4; ++m) _Pragma("unroll") for (int n = 0; n < 2; ++n) _Pragma("unroll") for (int k = 0; k < 2; ++k) \
;         acc[ai][bj][m][n] = mma16(Bt[n][k], At[m][k], acc[ai][bj][m][n]); __builtin_amdgcn_s_setprio(0); } while (0)
; #define PG8_WAIT_V(n) asm volatile("s_waitcnt vmcnt(" #n ")" ::: "memory")
; #define PG8_WAIT_L(n) asm volatile("s_waitcnt lgkmcnt(" #n ")" ::: "memory")
; #define PG8_BAR __builtin_amdgcn_s_barrier()
; #define PG8_SCHED __builtin_amdgcn_sched_barrier(0)
; template <class Epi, class Sched, bool ALIGN_EPI = false, bool SP2 = false>
; __device__ __forceinline__ void gemm_phase(PG8_LAS unsigned char* lds, const Gemm g, const Sched& S, const Epi& E) {
;     ...
;         for (int t = 0; t < nt; t += 2) {
;     ...
;             PG8_LDA(At, 1, 1); PG8_STAGE(PG8_SB(1, 0), b3, voffB); PG8_STAGE(PG8_SB(1, 1), b3 + hstepB, voffB); PG8_STAGE(PG8_SA(1, 0), a3, voffA);
;             PG8_WAIT_V(8); PG8_WAIT_L(0); PG8_BAR; PG8_MMA(1, 0, At, B0); PG8_MMA(1, 1, At, B1); PG8_BAR; PG8_SCHED;
;     ...
;         if constexpr (ALIGN_EPI) { if (wr == 0) PG8_BAR; }
	s_add_i32 s47, s47, s7
	v_lshl_add_u64 v[194:195], v[194:195], 0, s[50:51]
	s_mov_b32 m0, s47
	ds_read_b128 v[186:189], v214 offset:49152
	ds_read_b128 v[190:193], v214 offset:50176
	ds_read_b128 v[216:219], v214 offset:51200
	ds_read_b128 v[220:223], v214 offset:52224
	ds_read_b128 v[224:227], v214 offset:53248
	ds_read_b128 v[228:231], v214 offset:54272
	ds_read_b128 v[232:235], v214 offset:55296
	ds_read_b128 v[236:239], v214 offset:56320
	global_load_lds_dwordx4 v[194:195], off
	s_add_i32 m0, s47, 0x2000
	s_add_u32 s64, s64, 0x80080
	v_lshl_add_u64 v[194:195], v[240:241], 0, s[50:51]
	s_addc_u32 s65, s65, 0
	s_add_i32 s47, s61, s7
	global_load_lds_dwordx4 v[194:195], off
	v_lshl_add_u64 v[194:195], s[64:65], 0, v[164:165]
	s_mov_b32 m0, s47
	s_nop 0
	global_load_lds_dwordx4 v[194:195], off
	v_lshl_add_u64 v[194:195], s[64:65], 0, v[168:169]
	s_add_i32 m0, s47, 0x2000
	s_nop 0
	global_load_lds_dwordx4 v[194:195], off
	v_lshl_add_u64 v[194:195], v[242:243], 0, s[50:51]
	s_mov_b32 m0, s19
	s_nop 0
	global_load_lds_dwordx4 v[194:195], off
	v_lshl_add_u64 v[194:195], v[244:245], 0, s[50:51]
	s_mov_b32 m0, s20
	s_nop 0
	global_load_lds_dwordx4 v[194:195], off
	s_waitcnt vmcnt(8)
	s_waitcnt lgkmcnt(0)
	s_barrier
	s_setprio 1
	s_waitcnt lgkmcnt(0)
	v_mfma_i32_16x16x64_i8 v[62:65], v[82:85], v[186:189], v[62:65]
	v_mfma_i32_16x16x64_i8 v[62:65], v[86:89], v[190:193], v[62:65]
	v_mfma_i32_16x16x64_i8 v[58:61], v[142:145], v[190:193], v[58:61]
	v_mfma_i32_16x16x64_i8 v[58:61], v[138:141], v[186:189], v[58:61]
	v_mfma_i32_16x16x64_i8 v[42:45], v[138:141], v[216:219], v[42:45]
	v_mfma_i32_16x16x64_i8 v[42:45], v[142:145], v[220:223], v[42:45]
	v_mfma_i32_16x16x64_i8 v[46:49], v[86:89], v[220:223], v[46:49]
	v_mfma_i32_16x16x64_i8 v[46:49], v[82:85], v[216:219], v[46:49]
	v_mfma_i32_16x16x64_i8 v[30:33], v[82:85], v[224:227], v[30:33]
	v_mfma_i32_16x16x64_i8 v[30:33], v[86:89], v[228:231], v[30:33]
	v_mfma_i32_16x16x64_i8 v[26:29], v[142:145], v[228:231], v[26:29]
	v_mfma_i32_16x16x64_i8 v[26:29], v[138:141], v[224:227], v[26:29]
	v_mfma_i32_16x16x64_i8 v[10:13], v[138:141], v[232:235], v[10:13]
	v_mfma_i32_16x16x64_i8 v[10:13], v[142:145], v[236:239], v[10:13]
	v_mfma_i32_16x16x64_i8 v[14:17], v[86:89], v[236:239], v[14:17]
	v_mfma_i32_16x16x64_i8 v[14:17], v[82:85], v[232:235], v[14:17]
	s_setprio 0
	s_setprio 1
	v_mfma_i32_16x16x64_i8 v[54:57], v[146:149], v[186:189], v[54:57]
	v_mfma_i32_16x16x64_i8 v[54:57], v[150:153], v[190:193], v[54:57]
	v_mfma_i32_16x16x64_i8 v[50:53], v[158:161], v[190:193], v[50:53]
	v_mfma_i32_16x16x64_i8 v[50:53], v[154:157], v[186:189], v[50:53]
	v_mfma_i32_16x16x64_i8 v[34:37], v[154:157], v[216:219], v[34:37]
	v_mfma_i32_16x16x64_i8 v[34:37], v[158:161], v[220:223], v[34:37]
	v_mfma_i32_16x16x64_i8 v[38:41], v[150:153], v[220:223], v[38:41]
	v_mfma_i32_16x16x64_i8 v[38:41], v[146:149], v[216:219], v[38:41]
	v_mfma_i32_16x16x64_i8 v[22:25], v[146:149], v[224:227], v[22:25]
	v_mfma_i32_16x16x64_i8 v[22:25], v[150:153], v[228:231], v[22:25]
	v_mfma_i32_16x16x64_i8 v[18:21], v[158:161], v[228:231], v[18:21]
	v_mfma_i32_16x16x64_i8 v[18:21], v[154:157], v[224:227], v[18:21]
	v_mfma_i32_16x16x64_i8 v[2:5], v[154:157], v[232:235], v[2:5]
	v_mfma_i32_16x16x64_i8 v[2:5], v[158:161], v[236:239], v[2:5]
	v_mfma_i32_16x16x64_i8 v[6:9], v[150:153], v[236:239], v[6:9]
	v_mfma_i32_16x16x64_i8 v[6:9], v[146:149], v[232:235], v[6:9]
	s_setprio 0
	s_barrier
	s_add_i32 s46, s46, 2
	s_add_u32 s62, s62, 0x100
	s_addc_u32 s63, s63, 0
	s_add_u32 s36, s36, 0x100
	s_addc_u32 s37, s37, 0
	s_cmp_gt_u32 s46, 29
	s_cbranch_scc0 .LBB0_555
	s_and_b64 vcc, exec, s[52:53]
	s_cbranch_vccz .LBB0_558
	s_barrier

; #define PG8_STAGE(bufoff, gbase, voff) do { _Pragma("unroll") for (int _i = 0; _i < 2; ++_i) \
;         __builtin_amdgcn_global_load_lds((const unsigned*)((const char*)(gbase) + (voff)[_i]), (PG8_LAS unsigned*)(lds + (bufoff) + ldsw + _i * 8192), 16, 0, 0); } while (0)
; #define PG8_LDA(dst, b, h) do { _Pragma("unroll") for (int m = 0; m < 4; ++m) _Pragma("unroll") for (int k = 0; k < 2; ++k) dst[m][k] = *(const PG8_LAS bf16x8*)(lds + PG8_SA(b, h) + aoff + m * 2048 + k * 1024); } while (0)
; #define PG8_LDB(dst, b, h) do { _Pragma("unroll") for (int n = 0; n < 2; ++n) _Pragma("unroll") for (int k = 0; k < 2; ++k) dst[n][k] = *(const PG8_LAS bf16x8*)(lds + PG8_SB(b, h) + boff + n * 2048 + k * 1024); } while (0)
; #define PG8_MMA(ai, bj, At, Bt) do { __builtin_amdgcn_s_setprio(1); _Pragma("unroll") for (int m = 0; m < 4; ++m) _Pragma("unroll") for (int n = 0; n < 2; ++n) _Pragma("unroll") for (int k = 0; k < 2; ++k) \
;         acc[ai][bj][m][n] = mma16(Bt[n][k], At[m][k], acc[ai][bj][m][n]); __builtin_amdgcn_s_setprio(0); } while (0)
; #define PG8_WAIT_V(n) asm volatile("s_waitcnt vmcnt(" #n ")" ::: "memory")
; #define PG8_WAIT_L(n) asm volatile("s_waitcnt lgkmcnt(" #n ")" ::: "memory")
; template <class Epi, class Sched, bool ALIGN_EPI = false, bool SP2 = false>
; __device__ __forceinline__ void gemm_phase(PG8_LAS unsigned char* lds, const Gemm g, const Sched& S, const Epi& E) {
;     ...
;         for (int t = 0; t < nt; t += 2) {
;             const bool last = (t == nt - 2);
;             const char* a1 = cA + (size_t)(t + 1) * kstep;
;             const char* a2 = last ? nA : cA + (size_t)(t + 2) * kstep; const char* b2 = last ? nB : cB + (size_t)(t + 2) * kstep;
;             const char* a3 = a2 + kstep; const char* b3 = b2 + kstep;
;             if (last && has_next) S.a_ready(nxt);
;             if constexpr (SP2) {
;             PG8_LDB(B0, 0, 0); PG8_LDB(B1, 0, 1); PG8_SCHED; PG8_LDA(At, 0, 0); PG8_STAGE(PG8_SA(1, 1), a1 + hstepA, voffA);
;             PG8_WAIT_V(8); PG8_WAIT_L(0); PG8_BAR; PG8_MMA(0, 0, At, B0); PG8_MMA(0, 1, At, B1); PG8_BAR; PG8_SCHED;
;             PG8_LDA(At, 0, 1); PG8_STAGE(PG8_SB(0, 0), b2, voffB); PG8_STAGE(PG8_SB(0, 1), b2 + hstepB, voffB); PG8_STAGE(PG8_SA(0, 0), a2, voffA);
;             PG8_WAIT_V(8); PG8_WAIT_L(0); PG8_BAR; PG8_MMA(1, 0, At, B0); PG8_MMA(1, 1, At, B1); PG8_BAR; PG8_SCHED;
.LBB0_579:
	ds_read_b128 v[130:133], v1
	ds_read_b128 v[134:137], v1 offset:1024
	ds_read_b128 v[138:141], v1 offset:2048
	ds_read_b128 v[142:145], v1 offset:3072
	ds_read_b128 v[146:149], v214
	ds_read_b128 v[150:153], v214 offset:1024
	ds_read_b128 v[154:157], v214 offset:2048
	ds_read_b128 v[158:161], v214 offset:3072
	s_add_u32 s35, s56, 0xfff00080
	s_addc_u32 s36, s57, -1
	s_cmp_eq_u32 s33, 60
	s_cselect_b32 s61, s24, s36
	s_cselect_b32 s60, s25, s35
	s_cselect_b32 s59, s26, s29
	s_cselect_b32 s58, s27, s28
	v_lshl_add_u64 v[220:221], s[56:57], 0, v[190:191]
	s_add_i32 m0, s8, 0xc000
	ds_read_b128 v[162:165], v215
	ds_read_b128 v[166:169], v215 offset:1024
	ds_read_b128 v[170:173], v215 offset:2048
	ds_read_b128 v[174:177], v215 offset:3072
	ds_read_b128 v[198:201], v215 offset:4096
	ds_read_b128 v[202:205], v215 offset:5120
	ds_read_b128 v[206:209], v215 offset:6144
	ds_read_b128 v[216:219], v215 offset:7168
	global_load_lds_dwordx4 v[220:221], off
	v_lshl_add_u64 v[220:221], s[56:57], 0, v[192:193]
	s_add_i32 m0, s8, 0xe000
	s_nop 0
	global_load_lds_dwordx4 v[220:221], off
	s_waitcnt vmcnt(8)
	s_waitcnt lgkmcnt(0)
	s_barrier
	s_setprio 1
	s_waitcnt lgkmcnt(0)
	v_mfma_f32_16x16x32_bf16 v[126:129], v[130:133], v[162:165], v[126:129]
	v_mfma_f32_16x16x32_bf16 v[126:129], v[134:137], v[166:169], v[126:129]
	v_mfma_f32_16x16x32_bf16 v[122:125], v[142:145], v[166:169], v[122:125]
	v_mfma_f32_16x16x32_bf16 v[122:125], v[138:141], v[162:165], v[122:125]
	v_mfma_f32_16x16x32_bf16 v[106:109], v[138:141], v[170:173], v[106:109]
	v_mfma_f32_16x16x32_bf16 v[106:109], v[142:145], v[174:177], v[106:109]
	v_mfma_f32_16x16x32_bf16 v[110:113], v[134:137], v[174:177], v[110:113]
	v_mfma_f32_16x16x32_bf16 v[110:113], v[130:133], v[170:173], v[110:113]
	v_mfma_f32_16x16x32_bf16 v[94:97], v[130:133], v[198:201], v[94:97]
	v_mfma_f32_16x16x32_bf16 v[94:97], v[134:137], v[202:205], v[94:97]
	v_mfma_f32_16x16x32_bf16 v[90:93], v[142:145], v[202:205], v[90:93]
	v_mfma_f32_16x16x32_bf16 v[90:93], v[138:141], v[198:201], v[90:93]
	v_mfma_f32_16x16x32_bf16 v[74:77], v[138:141], v[206:209], v[74:77]
	v_mfma_f32_16x16x32_bf16 v[74:77], v[142:145], v[216:219], v[74:77]
	v_mfma_f32_16x16x32_bf16 v[78:81], v[134:137], v[216:219], v[78:81]
	v_mfma_f32_16x16x32_bf16 v[78:81], v[130:133], v[206:209], v[78:81]
	s_setprio 0
	s_setprio 1
	v_mfma_f32_16x16x32_bf16 v[118:121], v[146:149], v[162:165], v[118:121]
	v_mfma_f32_16x16x32_bf16 v[118:121], v[150:153], v[166:169], v[118:121]
	v_mfma_f32_16x16x32_bf16 v[114:117], v[158:161], v[166:169], v[114:117]
	v_mfma_f32_16x16x32_bf16 v[114:117], v[154:157], v[162:165], v[114:117]
	v_mfma_f32_16x16x32_bf16 v[98:101], v[154:157], v[170:173], v[98:101]
	v_mfma_f32_16x16x32_bf16 v[98:101], v[158:161], v[174:177], v[98:101]
	v_mfma_f32_16x16x32_bf16 v[102:105], v[150:153], v[174:177], v[102:105]
	v_mfma_f32_16x16x32_bf16 v[102:105], v[146:149], v[170:173], v[102:105]
	v_mfma_f32_16x16x32_bf16 v[86:89], v[146:149], v[198:201], v[86:89]
	v_mfma_f32_16x16x32_bf16 v[86:89], v[150:153], v[202:205], v[86:89]
	v_mfma_f32_16x16x32_bf16 v[82:85], v[158:161], v[202:205], v[82:85]
	v_mfma_f32_16x16x32_bf16 v[82:85], v[154:157], v[198:201], v[82:85]
	v_mfma_f32_16x16x32_bf16 v[66:69], v[154:157], v[206:209], v[66:69]
	v_mfma_f32_16x16x32_bf16 v[66:69], v[158:161], v[216:219], v[66:69]
	v_mfma_f32_16x16x32_bf16 v[70:73], v[150:153], v[216:219], v[70:73]
	v_mfma_f32_16x16x32_bf16 v[70:73], v[146:149], v[206:209], v[70:73]
	s_setprio 0
	s_barrier
	s_add_i32 s35, s21, s7
	v_lshl_add_u64 v[220:221], s[58:59], 0, v[184:185]
	s_mov_b32 m0, s35
	ds_read_b128 v[162:165], v215 offset:16384
	ds_read_b128 v[166:169], v215 offset:17408
	ds_read_b128 v[170:173], v215 offset:18432
	ds_read_b128 v[174:177], v215 offset:19456
	ds_read_b128 v[198:201], v215 offset:20480
	ds_read_b128 v[202:205], v215 offset:21504
	ds_read_b128 v[206:209], v215 offset:22528
	ds_read_b128 v[216:219], v215 offset:23552
	global_load_lds_dwordx4 v[220:221], off
	s_add_i32 m0, s35, 0x2000
	s_add_u32 s36, s58, 0x100000
	v_lshl_add_u64 v[222:223], s[58:59], 0, v[188:189]
	s_addc_u32 s37, s59, 0
	s_add_i32 s35, s22, s7
	global_load_lds_dwordx4 v[222:223], off
	v_lshl_add_u64 v[224:225], s[36:37], 0, v[184:185]
	s_mov_b32 m0, s35
	v_lshl_add_u64 v[226:227], s[60:61], 0, v[186:187]
	global_load_lds_dwordx4 v[224:225], off
	v_lshl_add_u64 v[224:225], s[36:37], 0, v[188:189]
	s_add_i32 m0, s35, 0x2000
	s_nop 0
	global_load_lds_dwordx4 v[224:225], off
	v_lshl_add_u64 v[224:225], s[60:61], 0, v[182:183]
	s_mov_b32 m0, s8
	s_nop 0
	global_load_lds_dwordx4 v[224:225], off
	s_mov_b32 m0, s11
	s_nop 0
	global_load_lds_dwordx4 v[226:227], off
	s_waitcnt vmcnt(8)
	s_waitcnt lgkmcnt(0)
	s_barrier
; #define PG8_STAGE(bufoff, gbase, voff) do { _Pragma("unroll") for (int _i = 0; _i < 2; ++_i) \
;         __builtin_amdgcn_global_load_lds((const unsigned*)((const char*)(gbase) + (voff)[_i]), (PG8_LAS unsigned*)(lds + (bufoff) + ldsw + _i * 8192), 16, 0, 0); } while (0)
; #define PG8_LDA(dst, b, h) do { _Pragma("unroll") for (int m = 0; m < 4; ++m) _Pragma("unroll") for (int k = 0; k < 2; ++k) dst[m][k] = *(const PG8_LAS bf16x8*)(lds + PG8_SA(b, h) + aoff + m * 2048 + k * 1024); } while (0)
; #define PG8_LDB(dst, b, h) do { _Pragma("unroll") for (int n = 0; n < 2; ++n) _Pragma("unroll") for (int k = 0; k < 2; ++k) dst[n][k] = *(const PG8_LAS bf16x8*)(lds + PG8_SB(b, h) + boff + n * 2048 + k * 1024); } while (0)
; #define PG8_MMA(ai, bj, At, Bt) do { __builtin_amdgcn_s_setprio(1); _Pragma("unroll") for (int m = 0; m < 4; ++m) _Pragma("unroll") for (int n = 0; n < 2; ++n) _Pragma("unroll") for (int k = 0; k < 2; ++k) \
;         acc[ai][bj][m][n] = mma16(Bt[n][k], At[m][k], acc[ai][bj][m][n]); __builtin_amdgcn_s_setprio(0); } while (0)
; #define PG8_WAIT_V(n) asm volatile("s_waitcnt vmcnt(" #n ")" ::: "memory")
; #define PG8_WAIT_L(n) asm volatile("s_waitcnt lgkmcnt(" #n ")" ::: "memory")
; #define PG8_BAR __builtin_amdgcn_s_barrier()
; #define PG8_SCHED __builtin_amdgcn_sched_barrier(0)
; template <class Epi, class Sched, bool ALIGN_EPI = false, bool SP2 = false>
; __device__ __forceinline__ void gemm_phase(PG8_LAS unsigned char* lds, const Gemm g, const Sched& S, const Epi& E) {
;     ...
;             PG8_WAIT_V(8); PG8_WAIT_L(0); PG8_BAR; PG8_MMA(1, 0, At, B0); PG8_MMA(1, 1, At, B1); PG8_BAR; PG8_SCHED;
;             PG8_LDB(B0, 1, 0); PG8_LDB(B1, 1, 1); PG8_SCHED; PG8_LDA(At, 1, 0); PG8_STAGE(PG8_SA(0, 1), a2 + hstepA, voffA);
;             PG8_WAIT_V(8); PG8_WAIT_L(0); PG8_BAR; PG8_MMA(0, 0, At, B0); PG8_MMA(0, 1, At, B1); PG8_BAR; PG8_SCHED;
	s_setprio 1
	s_waitcnt lgkmcnt(0)
	v_mfma_f32_16x16x32_bf16 v[62:65], v[130:133], v[162:165], v[62:65]
	v_mfma_f32_16x16x32_bf16 v[62:65], v[134:137], v[166:169], v[62:65]
	v_mfma_f32_16x16x32_bf16 v[58:61], v[142:145], v[166:169], v[58:61]
	v_mfma_f32_16x16x32_bf16 v[58:61], v[138:141], v[162:165], v[58:61]
	v_mfma_f32_16x16x32_bf16 v[42:45], v[138:141], v[170:173], v[42:45]
	v_mfma_f32_16x16x32_bf16 v[42:45], v[142:145], v[174:177], v[42:45]
	v_mfma_f32_16x16x32_bf16 v[46:49], v[134:137], v[174:177], v[46:49]
	v_mfma_f32_16x16x32_bf16 v[46:49], v[130:133], v[170:173], v[46:49]
	v_mfma_f32_16x16x32_bf16 v[30:33], v[130:133], v[198:201], v[30:33]
	v_mfma_f32_16x16x32_bf16 v[30:33], v[134:137], v[202:205], v[30:33]
	v_mfma_f32_16x16x32_bf16 v[26:29], v[142:145], v[202:205], v[26:29]
	v_mfma_f32_16x16x32_bf16 v[26:29], v[138:141], v[198:201], v[26:29]
	v_mfma_f32_16x16x32_bf16 v[10:13], v[138:141], v[206:209], v[10:13]
	v_mfma_f32_16x16x32_bf16 v[10:13], v[142:145], v[216:219], v[10:13]
	v_mfma_f32_16x16x32_bf16 v[14:17], v[134:137], v[216:219], v[14:17]
	v_mfma_f32_16x16x32_bf16 v[14:17], v[130:133], v[206:209], v[14:17]
	s_setprio 0
	s_setprio 1
	v_mfma_f32_16x16x32_bf16 v[54:57], v[146:149], v[162:165], v[54:57]
	v_mfma_f32_16x16x32_bf16 v[54:57], v[150:153], v[166:169], v[54:57]
	v_mfma_f32_16x16x32_bf16 v[50:53], v[158:161], v[166:169], v[50:53]
	v_mfma_f32_16x16x32_bf16 v[50:53], v[154:157], v[162:165], v[50:53]
	v_mfma_f32_16x16x32_bf16 v[34:37], v[154:157], v[170:173], v[34:37]
	v_mfma_f32_16x16x32_bf16 v[34:37], v[158:161], v[174:177], v[34:37]
	v_mfma_f32_16x16x32_bf16 v[38:41], v[150:153], v[174:177], v[38:41]
	v_mfma_f32_16x16x32_bf16 v[38:41], v[146:149], v[170:173], v[38:41]
	v_mfma_f32_16x16x32_bf16 v[22:25], v[146:149], v[198:201], v[22:25]
	v_mfma_f32_16x16x32_bf16 v[22:25], v[150:153], v[202:205], v[22:25]
	v_mfma_f32_16x16x32_bf16 v[18:21], v[158:161], v[202:205], v[18:21]
	v_mfma_f32_16x16x32_bf16 v[18:21], v[154:157], v[198:201], v[18:21]
	v_mfma_f32_16x16x32_bf16 v[2:5], v[154:157], v[206:209], v[2:5]
	v_mfma_f32_16x16x32_bf16 v[2:5], v[158:161], v[216:219], v[2:5]
	v_mfma_f32_16x16x32_bf16 v[6:9], v[150:153], v[216:219], v[6:9]
	v_mfma_f32_16x16x32_bf16 v[6:9], v[146:149], v[206:209], v[6:9]
	s_setprio 0
	s_barrier
	s_add_i32 s35, 0, 0x18000
	s_add_i32 s43, 0, 0x1c000
	v_add_u32_e32 v142, s35, v212
	v_add_u32_e32 v158, s43, v212
	ds_read_b128 v[130:133], v142
	ds_read_b128 v[134:137], v142 offset:1024
	ds_read_b128 v[138:141], v142 offset:2048
	ds_read_b128 v[142:145], v142 offset:3072
	ds_read_b128 v[146:149], v158
	ds_read_b128 v[150:153], v158 offset:1024
	ds_read_b128 v[154:157], v158 offset:2048
	ds_read_b128 v[158:161], v158 offset:3072
	s_add_u32 s36, s60, 0x100000
	s_addc_u32 s37, s61, 0
	s_mov_b32 m0, s12
	v_lshl_add_u64 v[228:229], s[36:37], 0, v[182:183]
	ds_read_b128 v[162:165], v215 offset:32768
	ds_read_b128 v[166:169], v215 offset:33792
	ds_read_b128 v[170:173], v215 offset:34816
	ds_read_b128 v[174:177], v215 offset:35840
	ds_read_b128 v[198:201], v215 offset:36864
	ds_read_b128 v[202:205], v215 offset:37888
	ds_read_b128 v[206:209], v215 offset:38912
	ds_read_b128 v[216:219], v215 offset:39936
	global_load_lds_dwordx4 v[228:229], off
	v_lshl_add_u64 v[228:229], s[36:37], 0, v[186:187]
	s_mov_b32 m0, s13
	s_nop 0
	global_load_lds_dwordx4 v[228:229], off
	s_waitcnt vmcnt(8)
	s_waitcnt lgkmcnt(0)
	s_barrier
	s_setprio 1
	s_waitcnt lgkmcnt(0)
	v_mfma_f32_16x16x32_bf16 v[126:129], v[130:133], v[162:165], v[126:129]
	v_mfma_f32_16x16x32_bf16 v[126:129], v[134:137], v[166:169], v[126:129]
	v_mfma_f32_16x16x32_bf16 v[122:125], v[142:145], v[166:169], v[122:125]
	v_mfma_f32_16x16x32_bf16 v[122:125], v[138:141], v[162:165], v[122:125]
	v_mfma_f32_16x16x32_bf16 v[106:109], v[138:141], v[170:173], v[106:109]
	v_mfma_f32_16x16x32_bf16 v[106:109], v[142:145], v[174:177], v[106:109]
	v_mfma_f32_16x16x32_bf16 v[110:113], v[134:137], v[174:177], v[110:113]
	v_mfma_f32_16x16x32_bf16 v[110:113], v[130:133], v[170:173], v[110:113]
	v_mfma_f32_16x16x32_bf16 v[94:97], v[130:133], v[198:201], v[94:97]
	v_mfma_f32_16x16x32_bf16 v[94:97], v[134:137], v[202:205], v[94:97]
	v_mfma_f32_16x16x32_bf16 v[90:93], v[142:145], v[202:205], v[90:93]
	v_mfma_f32_16x16x32_bf16 v[90:93], v[138:141], v[198:201], v[90:93]
	v_mfma_f32_16x16x32_bf16 v[74:77], v[138:141], v[206:209], v[74:77]
	v_mfma_f32_16x16x32_bf16 v[74:77], v[142:145], v[216:219], v[74:77]
	v_mfma_f32_16x16x32_bf16 v[78:81], v[134:137], v[216:219], v[78:81]
	v_mfma_f32_16x16x32_bf16 v[78:81], v[130:133], v[206:209], v[78:81]
	s_setprio 0
	s_setprio 1
	v_mfma_f32_16x16x32_bf16 v[118:121], v[146:149], v[162:165], v[118:121]
	v_mfma_f32_16x16x32_bf16 v[118:121], v[150:153], v[166:169], v[118:121]
	v_mfma_f32_16x16x32_bf16 v[114:117], v[158:161], v[166:169], v[114:117]
	v_mfma_f32_16x16x32_bf16 v[114:117], v[154:157], v[162:165], v[114:117]
	v_mfma_f32_16x16x32_bf16 v[98:101], v[154:157], v[170:173], v[98:101]
	v_mfma_f32_16x16x32_bf16 v[98:101], v[158:161], v[174:177], v[98:101]
	v_mfma_f32_16x16x32_bf16 v[102:105], v[150:153], v[174:177], v[102:105]
	v_mfma_f32_16x16x32_bf16 v[102:105], v[146:149], v[170:173], v[102:105]
	v_mfma_f32_16x16x32_bf16 v[86:89], v[146:149], v[198:201], v[86:89]
	v_mfma_f32_16x16x32_bf16 v[86:89], v[150:153], v[202:205], v[86:89]
	v_mfma_f32_16x16x32_bf16 v[82:85], v[158:161], v[202:205], v[82:85]
	v_mfma_f32_16x16x32_bf16 v[82:85], v[154:157], v[198:201], v[82:85]
	v_mfma_f32_16x16x32_bf16 v[66:69], v[154:157], v[206:209], v[66:69]
	v_mfma_f32_16x16x32_bf16 v[66:69], v[158:161], v[216:219], v[66:69]
	v_mfma_f32_16x16x32_bf16 v[70:73], v[150:153], v[216:219], v[70:73]
	v_mfma_f32_16x16x32_bf16 v[70:73], v[146:149], v[206:209], v[70:73]
	s_setprio 0
	s_barrier
; #define PG8_STAGE(bufoff, gbase, voff) do { _Pragma("unroll") for (int _i = 0; _i < 2; ++_i) \
;         __builtin_amdgcn_global_load_lds((const unsigned*)((const char*)(gbase) + (voff)[_i]), (PG8_LAS unsigned*)(lds + (bufoff) + ldsw + _i * 8192), 16, 0, 0); } while (0)
; #define PG8_LDA(dst, b, h) do { _Pragma("unroll") for (int m = 0; m < 4; ++m) _Pragma("unroll") for (int k = 0; k < 2; ++k) dst[m][k] = *(const PG8_LAS bf16x8*)(lds + PG8_SA(b, h) + aoff + m * 2048 + k * 1024); } while (0)
; #define PG8_MMA(ai, bj, At, Bt) do { __builtin_amdgcn_s_setprio(1); _Pragma("unroll") for (int m = 0; m < 4; ++m) _Pragma("unroll") for (int n = 0; n < 2; ++n) _Pragma("unroll") for (int k = 0; k < 2; ++k) \
;         acc[ai][bj][m][n] = mma16(Bt[n][k], At[m][k], acc[ai][bj][m][n]); __builtin_amdgcn_s_setprio(0); } while (0)
; #define PG8_WAIT_V(n) asm volatile("s_waitcnt vmcnt(" #n ")" ::: "memory")
; #define PG8_WAIT_L(n) asm volatile("s_waitcnt lgkmcnt(" #n ")" ::: "memory")
; #define PG8_BAR __builtin_amdgcn_s_barrier()
; #define PG8_SCHED __builtin_amdgcn_sched_barrier(0)
; template <class Epi, class Sched, bool ALIGN_EPI = false, bool SP2 = false>
; __device__ __forceinline__ void gemm_phase(PG8_LAS unsigned char* lds, const Gemm g, const Sched& S, const Epi& E) {
;     ...
;         for (int t = 0; t < nt; t += 2) {
;     ...
;             PG8_LDA(At, 1, 1); PG8_STAGE(PG8_SB(1, 0), b3, voffB); PG8_STAGE(PG8_SB(1, 1), b3 + hstepB, voffB); PG8_STAGE(PG8_SA(1, 0), a3, voffA);
;             PG8_WAIT_V(8); PG8_WAIT_L(0); PG8_BAR; PG8_MMA(1, 0, At, B0); PG8_MMA(1, 1, At, B1); PG8_BAR; PG8_SCHED;
;     ...
;         if constexpr (ALIGN_EPI) { if (wr == 0) PG8_BAR; }
	s_add_i32 s35, s35, s7
	v_lshl_add_u64 v[220:221], v[220:221], 0, s[38:39]
	s_mov_b32 m0, s35
	ds_read_b128 v[162:165], v215 offset:49152
	ds_read_b128 v[166:169], v215 offset:50176
	ds_read_b128 v[170:173], v215 offset:51200
	ds_read_b128 v[174:177], v215 offset:52224
	ds_read_b128 v[198:201], v215 offset:53248
	ds_read_b128 v[202:205], v215 offset:54272
	ds_read_b128 v[206:209], v215 offset:55296
	ds_read_b128 v[216:219], v215 offset:56320
	global_load_lds_dwordx4 v[220:221], off
	s_add_i32 m0, s35, 0x2000
	s_add_u32 s36, s58, 0x100080
	v_lshl_add_u64 v[220:221], v[222:223], 0, s[38:39]
	s_addc_u32 s37, s59, 0
	s_add_i32 s35, s43, s7
	global_load_lds_dwordx4 v[220:221], off
	v_lshl_add_u64 v[220:221], s[36:37], 0, v[184:185]
	s_mov_b32 m0, s35
	s_nop 0
	global_load_lds_dwordx4 v[220:221], off
	v_lshl_add_u64 v[220:221], s[36:37], 0, v[188:189]
	s_add_i32 m0, s35, 0x2000
	s_nop 0
	global_load_lds_dwordx4 v[220:221], off
	v_lshl_add_u64 v[220:221], v[224:225], 0, s[38:39]
	s_mov_b32 m0, s17
	s_nop 0
	global_load_lds_dwordx4 v[220:221], off
	v_lshl_add_u64 v[220:221], v[226:227], 0, s[38:39]
	s_mov_b32 m0, s18
	s_nop 0
	global_load_lds_dwordx4 v[220:221], off
	s_waitcnt vmcnt(8)
	s_waitcnt lgkmcnt(0)
	s_barrier
	s_setprio 1
	s_waitcnt lgkmcnt(0)
	v_mfma_f32_16x16x32_bf16 v[62:65], v[130:133], v[162:165], v[62:65]
	v_mfma_f32_16x16x32_bf16 v[62:65], v[134:137], v[166:169], v[62:65]
	v_mfma_f32_16x16x32_bf16 v[58:61], v[142:145], v[166:169], v[58:61]
	v_mfma_f32_16x16x32_bf16 v[58:61], v[138:141], v[162:165], v[58:61]
	v_mfma_f32_16x16x32_bf16 v[42:45], v[138:141], v[170:173], v[42:45]
	v_mfma_f32_16x16x32_bf16 v[42:45], v[142:145], v[174:177], v[42:45]
	v_mfma_f32_16x16x32_bf16 v[46:49], v[134:137], v[174:177], v[46:49]
	v_mfma_f32_16x16x32_bf16 v[46:49], v[130:133], v[170:173], v[46:49]
	v_mfma_f32_16x16x32_bf16 v[30:33], v[130:133], v[198:201], v[30:33]
	v_mfma_f32_16x16x32_bf16 v[30:33], v[134:137], v[202:205], v[30:33]
	v_mfma_f32_16x16x32_bf16 v[26:29], v[142:145], v[202:205], v[26:29]
	v_mfma_f32_16x16x32_bf16 v[26:29], v[138:141], v[198:201], v[26:29]
	v_mfma_f32_16x16x32_bf16 v[10:13], v[138:141], v[206:209], v[10:13]
	v_mfma_f32_16x16x32_bf16 v[10:13], v[142:145], v[216:219], v[10:13]
	v_mfma_f32_16x16x32_bf16 v[14:17], v[134:137], v[216:219], v[14:17]
	v_mfma_f32_16x16x32_bf16 v[14:17], v[130:133], v[206:209], v[14:17]
	s_setprio 0
	s_setprio 1
	v_mfma_f32_16x16x32_bf16 v[54:57], v[146:149], v[162:165], v[54:57]
	v_mfma_f32_16x16x32_bf16 v[54:57], v[150:153], v[166:169], v[54:57]
	v_mfma_f32_16x16x32_bf16 v[50:53], v[158:161], v[166:169], v[50:53]
	v_mfma_f32_16x16x32_bf16 v[50:53], v[154:157], v[162:165], v[50:53]
	v_mfma_f32_16x16x32_bf16 v[34:37], v[154:157], v[170:173], v[34:37]
	v_mfma_f32_16x16x32_bf16 v[34:37], v[158:161], v[174:177], v[34:37]
	v_mfma_f32_16x16x32_bf16 v[38:41], v[150:153], v[174:177], v[38:41]
	v_mfma_f32_16x16x32_bf16 v[38:41], v[146:149], v[170:173], v[38:41]
	v_mfma_f32_16x16x32_bf16 v[22:25], v[146:149], v[198:201], v[22:25]
	v_mfma_f32_16x16x32_bf16 v[22:25], v[150:153], v[202:205], v[22:25]
	v_mfma_f32_16x16x32_bf16 v[18:21], v[158:161], v[202:205], v[18:21]
	v_mfma_f32_16x16x32_bf16 v[18:21], v[154:157], v[198:201], v[18:21]
	v_mfma_f32_16x16x32_bf16 v[2:5], v[154:157], v[206:209], v[2:5]
	v_mfma_f32_16x16x32_bf16 v[2:5], v[158:161], v[216:219], v[2:5]
	v_mfma_f32_16x16x32_bf16 v[6:9], v[150:153], v[216:219], v[6:9]
	v_mfma_f32_16x16x32_bf16 v[6:9], v[146:149], v[206:209], v[6:9]
	s_setprio 0
	s_barrier
	s_add_i32 s33, s33, 2
	s_add_u32 s56, s56, 0x100
	s_addc_u32 s57, s57, 0
	s_add_u32 s28, s28, 0x100
	s_addc_u32 s29, s29, 0
	s_cmp_gt_u32 s33, 61
	s_cbranch_scc0 .LBB0_579
	s_and_b64 vcc, exec, s[40:41]
	s_cbranch_vccz .LBB0_582
	s_barrier

; #define PG8_STAGE(bufoff, gbase, voff) do { _Pragma("unroll") for (int _i = 0; _i < 2; ++_i) \
;         __builtin_amdgcn_global_load_lds((const unsigned*)((const char*)(gbase) + (voff)[_i]), (PG8_LAS unsigned*)(lds + (bufoff) + ldsw + _i * 8192), 16, 0, 0); } while (0)
; #define PG8_LDA(dst, b, h) do { _Pragma("unroll") for (int m = 0; m < 4; ++m) _Pragma("unroll") for (int k = 0; k < 2; ++k) dst[m][k] = *(const PG8_LAS bf16x8*)(lds + PG8_SA(b, h) + aoff + m * 2048 + k * 1024); } while (0)
; #define PG8_LDB(dst, b, h) do { _Pragma("unroll") for (int n = 0; n < 2; ++n) _Pragma("unroll") for (int k = 0; k < 2; ++k) dst[n][k] = *(const PG8_LAS bf16x8*)(lds + PG8_SB(b, h) + boff + n * 2048 + k * 1024); } while (0)
; #define PG8_MMA(ai, bj, At, Bt) do { __builtin_amdgcn_s_setprio(1); _Pragma("unroll") for (int m = 0; m < 4; ++m) _Pragma("unroll") for (int n = 0; n < 2; ++n) _Pragma("unroll") for (int k = 0; k < 2; ++k) \
;         acc[ai][bj][m][n] = mma16(Bt[n][k], At[m][k], acc[ai][bj][m][n]); __builtin_amdgcn_s_setprio(0); } while (0)
; #define PG8_WAIT_V(n) asm volatile("s_waitcnt vmcnt(" #n ")" ::: "memory")
; #define PG8_WAIT_L(n) asm volatile("s_waitcnt lgkmcnt(" #n ")" ::: "memory")
; template <class Epi, class Sched, bool ALIGN_EPI = false, bool SP2 = false>
; __device__ __forceinline__ void gemm_phase(PG8_LAS unsigned char* lds, const Gemm g, const Sched& S, const Epi& E) {
;     ...
;         for (int t = 0; t < nt; t += 2) {
;             const bool last = (t == nt - 2);
;             const char* a1 = cA + (size_t)(t + 1) * kstep;
;             const char* a2 = last ? nA : cA + (size_t)(t + 2) * kstep; const char* b2 = last ? nB : cB + (size_t)(t + 2) * kstep;
;             const char* a3 = a2 + kstep; const char* b3 = b2 + kstep;
;             if (last && has_next) S.a_ready(nxt);
;             if constexpr (SP2) {
;             PG8_LDB(B0, 0, 0); PG8_LDB(B1, 0, 1); PG8_SCHED; PG8_LDA(At, 0, 0); PG8_STAGE(PG8_SA(1, 1), a1 + hstepA, voffA);
;             PG8_WAIT_V(8); PG8_WAIT_L(0); PG8_BAR; PG8_MMA(0, 0, At, B0); PG8_MMA(0, 1, At, B1); PG8_BAR; PG8_SCHED;
;             PG8_LDA(At, 0, 1); PG8_STAGE(PG8_SB(0, 0), b2, voffB); PG8_STAGE(PG8_SB(0, 1), b2 + hstepB, voffB); PG8_STAGE(PG8_SA(0, 0), a2, voffA);
;             PG8_WAIT_V(8); PG8_WAIT_L(0); PG8_BAR; PG8_MMA(1, 0, At, B0); PG8_MMA(1, 1, At, B1); PG8_BAR; PG8_SCHED;
.LBB0_660:
	ds_read_b128 v[154:157], v150
	ds_read_b128 v[158:161], v150 offset:1024
	ds_read_b128 v[162:165], v150 offset:2048
	ds_read_b128 v[166:169], v150 offset:3072
	ds_read_b128 v[170:173], v151
	ds_read_b128 v[174:177], v151 offset:1024
	ds_read_b128 v[182:185], v151 offset:2048
	ds_read_b128 v[186:189], v151 offset:3072
	s_add_u32 s36, s0, 0xfff00080
	s_addc_u32 s37, s1, -1
	s_cmp_eq_u32 s35, 60
	s_cselect_b32 s67, s59, s37
	s_cselect_b32 s66, s58, s36
	s_cselect_b32 s65, s27, s33
	s_cselect_b32 s64, s28, s29
	v_lshl_add_u64 v[146:147], s[0:1], 0, v[138:139]
	s_add_i32 m0, s8, 0xc000
	ds_read_b128 v[190:193], v152
	ds_read_b128 v[194:197], v152 offset:1024
	ds_read_b128 v[198:201], v152 offset:2048
	ds_read_b128 v[202:205], v152 offset:3072
	ds_read_b128 v[206:209], v152 offset:4096
	ds_read_b128 v[212:215], v152 offset:5120
	ds_read_b128 v[216:219], v152 offset:6144
	ds_read_b128 v[220:223], v152 offset:7168
	global_load_lds_dwordx4 v[146:147], off
	v_lshl_add_u64 v[146:147], s[0:1], 0, v[140:141]
	s_add_i32 m0, s8, 0xe000
	s_nop 0
	global_load_lds_dwordx4 v[146:147], off
	s_waitcnt vmcnt(8)
	s_waitcnt lgkmcnt(0)
	s_barrier
	s_setprio 1
	s_waitcnt lgkmcnt(0)
	v_mfma_f32_16x16x32_bf16 v[126:129], v[154:157], v[190:193], v[126:129]
	v_mfma_f32_16x16x32_bf16 v[126:129], v[158:161], v[194:197], v[126:129]
	v_mfma_f32_16x16x32_bf16 v[122:125], v[166:169], v[194:197], v[122:125]
	v_mfma_f32_16x16x32_bf16 v[122:125], v[162:165], v[190:193], v[122:125]
	v_mfma_f32_16x16x32_bf16 v[110:113], v[162:165], v[198:201], v[110:113]
	v_mfma_f32_16x16x32_bf16 v[110:113], v[166:169], v[202:205], v[110:113]
	v_mfma_f32_16x16x32_bf16 v[118:121], v[158:161], v[202:205], v[118:121]
	v_mfma_f32_16x16x32_bf16 v[118:121], v[154:157], v[198:201], v[118:121]
	v_mfma_f32_16x16x32_bf16 v[102:105], v[154:157], v[206:209], v[102:105]
	v_mfma_f32_16x16x32_bf16 v[102:105], v[158:161], v[212:215], v[102:105]
	v_mfma_f32_16x16x32_bf16 v[94:97], v[166:169], v[212:215], v[94:97]
	v_mfma_f32_16x16x32_bf16 v[94:97], v[162:165], v[206:209], v[94:97]
	v_mfma_f32_16x16x32_bf16 v[78:81], v[162:165], v[216:219], v[78:81]
	v_mfma_f32_16x16x32_bf16 v[78:81], v[166:169], v[220:223], v[78:81]
	v_mfma_f32_16x16x32_bf16 v[86:89], v[158:161], v[220:223], v[86:89]
	v_mfma_f32_16x16x32_bf16 v[86:89], v[154:157], v[216:219], v[86:89]
	s_setprio 0
	s_setprio 1
	v_mfma_f32_16x16x32_bf16 v[114:117], v[170:173], v[190:193], v[114:117]
	v_mfma_f32_16x16x32_bf16 v[114:117], v[174:177], v[194:197], v[114:117]
	v_mfma_f32_16x16x32_bf16 v[106:109], v[186:189], v[194:197], v[106:109]
	v_mfma_f32_16x16x32_bf16 v[106:109], v[182:185], v[190:193], v[106:109]
	v_mfma_f32_16x16x32_bf16 v[90:93], v[182:185], v[198:201], v[90:93]
	v_mfma_f32_16x16x32_bf16 v[90:93], v[186:189], v[202:205], v[90:93]
	v_mfma_f32_16x16x32_bf16 v[98:101], v[174:177], v[202:205], v[98:101]
	v_mfma_f32_16x16x32_bf16 v[98:101], v[170:173], v[198:201], v[98:101]
	v_mfma_f32_16x16x32_bf16 v[82:85], v[170:173], v[206:209], v[82:85]
	v_mfma_f32_16x16x32_bf16 v[82:85], v[174:177], v[212:215], v[82:85]
	v_mfma_f32_16x16x32_bf16 v[74:77], v[186:189], v[212:215], v[74:77]
	v_mfma_f32_16x16x32_bf16 v[74:77], v[182:185], v[206:209], v[74:77]
	v_mfma_f32_16x16x32_bf16 v[66:69], v[182:185], v[216:219], v[66:69]
	v_mfma_f32_16x16x32_bf16 v[66:69], v[186:189], v[220:223], v[66:69]
	v_mfma_f32_16x16x32_bf16 v[70:73], v[174:177], v[220:223], v[70:73]
	v_mfma_f32_16x16x32_bf16 v[70:73], v[170:173], v[216:219], v[70:73]
	s_setprio 0
	s_barrier
	s_add_i32 s36, s20, s7
	v_lshl_add_u64 v[146:147], s[64:65], 0, v[132:133]
	s_mov_b32 m0, s36
	ds_read_b128 v[190:193], v152 offset:16384
	ds_read_b128 v[194:197], v152 offset:17408
	ds_read_b128 v[198:201], v152 offset:18432
	ds_read_b128 v[202:205], v152 offset:19456
	ds_read_b128 v[206:209], v152 offset:20480
	ds_read_b128 v[212:215], v152 offset:21504
	ds_read_b128 v[216:219], v152 offset:22528
	ds_read_b128 v[220:223], v152 offset:23552
	global_load_lds_dwordx4 v[146:147], off
	s_add_i32 m0, s36, 0x2000
	s_add_u32 s36, s64, 0x100000
	v_lshl_add_u64 v[224:225], s[64:65], 0, v[136:137]
	s_addc_u32 s37, s65, 0
	s_add_i32 s46, s21, s7
	global_load_lds_dwordx4 v[224:225], off
	v_lshl_add_u64 v[226:227], s[36:37], 0, v[132:133]
	s_mov_b32 m0, s46
	v_lshl_add_u64 v[228:229], s[66:67], 0, v[134:135]
	global_load_lds_dwordx4 v[226:227], off
	v_lshl_add_u64 v[226:227], s[36:37], 0, v[136:137]
	s_add_i32 m0, s46, 0x2000
	s_nop 0
	global_load_lds_dwordx4 v[226:227], off
	v_lshl_add_u64 v[226:227], s[66:67], 0, v[130:131]
	s_mov_b32 m0, s8
	s_nop 0
	global_load_lds_dwordx4 v[226:227], off
	s_mov_b32 m0, s11
	s_nop 0
	global_load_lds_dwordx4 v[228:229], off
	s_waitcnt vmcnt(8)
	s_waitcnt lgkmcnt(0)
	s_barrier
; #define PG8_STAGE(bufoff, gbase, voff) do { _Pragma("unroll") for (int _i = 0; _i < 2; ++_i) \
;         __builtin_amdgcn_global_load_lds((const unsigned*)((const char*)(gbase) + (voff)[_i]), (PG8_LAS unsigned*)(lds + (bufoff) + ldsw + _i * 8192), 16, 0, 0); } while (0)
; #define PG8_LDA(dst, b, h) do { _Pragma("unroll") for (int m = 0; m < 4; ++m) _Pragma("unroll") for (int k = 0; k < 2; ++k) dst[m][k] = *(const PG8_LAS bf16x8*)(lds + PG8_SA(b, h) + aoff + m * 2048 + k * 1024); } while (0)
; #define PG8_LDB(dst, b, h) do { _Pragma("unroll") for (int n = 0; n < 2; ++n) _Pragma("unroll") for (int k = 0; k < 2; ++k) dst[n][k] = *(const PG8_LAS bf16x8*)(lds + PG8_SB(b, h) + boff + n * 2048 + k * 1024); } while (0)
; #define PG8_MMA(ai, bj, At, Bt) do { __builtin_amdgcn_s_setprio(1); _Pragma("unroll") for (int m = 0; m < 4; ++m) _Pragma("unroll") for (int n = 0; n < 2; ++n) _Pragma("unroll") for (int k = 0; k < 2; ++k) \
;         acc[ai][bj][m][n] = mma16(Bt[n][k], At[m][k], acc[ai][bj][m][n]); __builtin_amdgcn_s_setprio(0); } while (0)
; #define PG8_WAIT_V(n) asm volatile("s_waitcnt vmcnt(" #n ")" ::: "memory")
; #define PG8_WAIT_L(n) asm volatile("s_waitcnt lgkmcnt(" #n ")" ::: "memory")
; #define PG8_BAR __builtin_amdgcn_s_barrier()
; #define PG8_SCHED __builtin_amdgcn_sched_barrier(0)
; template <class Epi, class Sched, bool ALIGN_EPI = false, bool SP2 = false>
; __device__ __forceinline__ void gemm_phase(PG8_LAS unsigned char* lds, const Gemm g, const Sched& S, const Epi& E) {
;     ...
;             PG8_WAIT_V(8); PG8_WAIT_L(0); PG8_BAR; PG8_MMA(1, 0, At, B0); PG8_MMA(1, 1, At, B1); PG8_BAR; PG8_SCHED;
;             PG8_LDB(B0, 1, 0); PG8_LDB(B1, 1, 1); PG8_SCHED; PG8_LDA(At, 1, 0); PG8_STAGE(PG8_SA(0, 1), a2 + hstepA, voffA);
;             PG8_WAIT_V(8); PG8_WAIT_L(0); PG8_BAR; PG8_MMA(0, 0, At, B0); PG8_MMA(0, 1, At, B1); PG8_BAR; PG8_SCHED;
	s_setprio 1
	s_waitcnt lgkmcnt(0)
	v_mfma_f32_16x16x32_bf16 v[62:65], v[154:157], v[190:193], v[62:65]
	v_mfma_f32_16x16x32_bf16 v[62:65], v[158:161], v[194:197], v[62:65]
	v_mfma_f32_16x16x32_bf16 v[58:61], v[166:169], v[194:197], v[58:61]
	v_mfma_f32_16x16x32_bf16 v[58:61], v[162:165], v[190:193], v[58:61]
	v_mfma_f32_16x16x32_bf16 v[46:49], v[162:165], v[198:201], v[46:49]
	v_mfma_f32_16x16x32_bf16 v[46:49], v[166:169], v[202:205], v[46:49]
	v_mfma_f32_16x16x32_bf16 v[54:57], v[158:161], v[202:205], v[54:57]
	v_mfma_f32_16x16x32_bf16 v[54:57], v[154:157], v[198:201], v[54:57]
	v_mfma_f32_16x16x32_bf16 v[38:41], v[154:157], v[206:209], v[38:41]
	v_mfma_f32_16x16x32_bf16 v[38:41], v[158:161], v[212:215], v[38:41]
	v_mfma_f32_16x16x32_bf16 v[30:33], v[166:169], v[212:215], v[30:33]
	v_mfma_f32_16x16x32_bf16 v[30:33], v[162:165], v[206:209], v[30:33]
	v_mfma_f32_16x16x32_bf16 v[14:17], v[162:165], v[216:219], v[14:17]
	v_mfma_f32_16x16x32_bf16 v[14:17], v[166:169], v[220:223], v[14:17]
	v_mfma_f32_16x16x32_bf16 v[22:25], v[158:161], v[220:223], v[22:25]
	v_mfma_f32_16x16x32_bf16 v[22:25], v[154:157], v[216:219], v[22:25]
	s_setprio 0
	s_setprio 1
	v_mfma_f32_16x16x32_bf16 v[50:53], v[170:173], v[190:193], v[50:53]
	v_mfma_f32_16x16x32_bf16 v[50:53], v[174:177], v[194:197], v[50:53]
	v_mfma_f32_16x16x32_bf16 v[42:45], v[186:189], v[194:197], v[42:45]
	v_mfma_f32_16x16x32_bf16 v[42:45], v[182:185], v[190:193], v[42:45]
	v_mfma_f32_16x16x32_bf16 v[26:29], v[182:185], v[198:201], v[26:29]
	v_mfma_f32_16x16x32_bf16 v[26:29], v[186:189], v[202:205], v[26:29]
	v_mfma_f32_16x16x32_bf16 v[34:37], v[174:177], v[202:205], v[34:37]
	v_mfma_f32_16x16x32_bf16 v[34:37], v[170:173], v[198:201], v[34:37]
	v_mfma_f32_16x16x32_bf16 v[18:21], v[170:173], v[206:209], v[18:21]
	v_mfma_f32_16x16x32_bf16 v[18:21], v[174:177], v[212:215], v[18:21]
	v_mfma_f32_16x16x32_bf16 v[10:13], v[186:189], v[212:215], v[10:13]
	v_mfma_f32_16x16x32_bf16 v[10:13], v[182:185], v[206:209], v[10:13]
	v_mfma_f32_16x16x32_bf16 v[2:5], v[182:185], v[216:219], v[2:5]
	v_mfma_f32_16x16x32_bf16 v[2:5], v[186:189], v[220:223], v[2:5]
	v_mfma_f32_16x16x32_bf16 v[6:9], v[174:177], v[220:223], v[6:9]
	v_mfma_f32_16x16x32_bf16 v[6:9], v[170:173], v[216:219], v[6:9]
	s_setprio 0
	s_barrier
	s_add_i32 s46, 0, 0x18000
	v_add_u32_e32 v153, s46, v148
	s_add_i32 s47, 0, 0x1c000
	ds_read_b128 v[154:157], v153
	ds_read_b128 v[158:161], v153 offset:1024
	ds_read_b128 v[162:165], v153 offset:2048
	ds_read_b128 v[166:169], v153 offset:3072
	v_add_u32_e32 v153, s47, v148
	ds_read_b128 v[170:173], v153
	ds_read_b128 v[174:177], v153 offset:1024
	ds_read_b128 v[182:185], v153 offset:2048
	ds_read_b128 v[186:189], v153 offset:3072
	s_add_u32 s36, s66, 0x100000
	s_addc_u32 s37, s67, 0
	s_mov_b32 m0, s12
	v_lshl_add_u64 v[230:231], s[36:37], 0, v[130:131]
	ds_read_b128 v[190:193], v152 offset:32768
	ds_read_b128 v[194:197], v152 offset:33792
	ds_read_b128 v[198:201], v152 offset:34816
	ds_read_b128 v[202:205], v152 offset:35840
	ds_read_b128 v[206:209], v152 offset:36864
	ds_read_b128 v[212:215], v152 offset:37888
	ds_read_b128 v[216:219], v152 offset:38912
	ds_read_b128 v[220:223], v152 offset:39936
	global_load_lds_dwordx4 v[230:231], off
	v_lshl_add_u64 v[230:231], s[36:37], 0, v[134:135]
	s_mov_b32 m0, s13
	s_nop 0
	global_load_lds_dwordx4 v[230:231], off
	s_waitcnt vmcnt(8)
	s_waitcnt lgkmcnt(0)
	s_barrier
	s_setprio 1
	s_waitcnt lgkmcnt(0)
	v_mfma_f32_16x16x32_bf16 v[126:129], v[154:157], v[190:193], v[126:129]
	v_mfma_f32_16x16x32_bf16 v[126:129], v[158:161], v[194:197], v[126:129]
	v_mfma_f32_16x16x32_bf16 v[122:125], v[166:169], v[194:197], v[122:125]
	v_mfma_f32_16x16x32_bf16 v[122:125], v[162:165], v[190:193], v[122:125]
	v_mfma_f32_16x16x32_bf16 v[110:113], v[162:165], v[198:201], v[110:113]
	v_mfma_f32_16x16x32_bf16 v[110:113], v[166:169], v[202:205], v[110:113]
	v_mfma_f32_16x16x32_bf16 v[118:121], v[158:161], v[202:205], v[118:121]
	v_mfma_f32_16x16x32_bf16 v[118:121], v[154:157], v[198:201], v[118:121]
	v_mfma_f32_16x16x32_bf16 v[102:105], v[154:157], v[206:209], v[102:105]
	v_mfma_f32_16x16x32_bf16 v[102:105], v[158:161], v[212:215], v[102:105]
	v_mfma_f32_16x16x32_bf16 v[94:97], v[166:169], v[212:215], v[94:97]
	v_mfma_f32_16x16x32_bf16 v[94:97], v[162:165], v[206:209], v[94:97]
	v_mfma_f32_16x16x32_bf16 v[78:81], v[162:165], v[216:219], v[78:81]
	v_mfma_f32_16x16x32_bf16 v[78:81], v[166:169], v[220:223], v[78:81]
	v_mfma_f32_16x16x32_bf16 v[86:89], v[158:161], v[220:223], v[86:89]
	v_mfma_f32_16x16x32_bf16 v[86:89], v[154:157], v[216:219], v[86:89]
	s_setprio 0
	s_setprio 1
	v_mfma_f32_16x16x32_bf16 v[114:117], v[170:173], v[190:193], v[114:117]
	v_mfma_f32_16x16x32_bf16 v[114:117], v[174:177], v[194:197], v[114:117]
	v_mfma_f32_16x16x32_bf16 v[106:109], v[186:189], v[194:197], v[106:109]
	v_mfma_f32_16x16x32_bf16 v[106:109], v[182:185], v[190:193], v[106:109]
	v_mfma_f32_16x16x32_bf16 v[90:93], v[182:185], v[198:201], v[90:93]
	v_mfma_f32_16x16x32_bf16 v[90:93], v[186:189], v[202:205], v[90:93]
	v_mfma_f32_16x16x32_bf16 v[98:101], v[174:177], v[202:205], v[98:101]
	v_mfma_f32_16x16x32_bf16 v[98:101], v[170:173], v[198:201], v[98:101]
	v_mfma_f32_16x16x32_bf16 v[82:85], v[170:173], v[206:209], v[82:85]
	v_mfma_f32_16x16x32_bf16 v[82:85], v[174:177], v[212:215], v[82:85]
	v_mfma_f32_16x16x32_bf16 v[74:77], v[186:189], v[212:215], v[74:77]
	v_mfma_f32_16x16x32_bf16 v[74:77], v[182:185], v[206:209], v[74:77]
	v_mfma_f32_16x16x32_bf16 v[66:69], v[182:185], v[216:219], v[66:69]
	v_mfma_f32_16x16x32_bf16 v[66:69], v[186:189], v[220:223], v[66:69]
	v_mfma_f32_16x16x32_bf16 v[70:73], v[174:177], v[220:223], v[70:73]
	v_mfma_f32_16x16x32_bf16 v[70:73], v[170:173], v[216:219], v[70:73]
	s_setprio 0
	s_barrier
; #define PG8_STAGE(bufoff, gbase, voff) do { _Pragma("unroll") for (int _i = 0; _i < 2; ++_i) \
;         __builtin_amdgcn_global_load_lds((const unsigned*)((const char*)(gbase) + (voff)[_i]), (PG8_LAS unsigned*)(lds + (bufoff) + ldsw + _i * 8192), 16, 0, 0); } while (0)
; #define PG8_LDA(dst, b, h) do { _Pragma("unroll") for (int m = 0; m < 4; ++m) _Pragma("unroll") for (int k = 0; k < 2; ++k) dst[m][k] = *(const PG8_LAS bf16x8*)(lds + PG8_SA(b, h) + aoff + m * 2048 + k * 1024); } while (0)
; #define PG8_MMA(ai, bj, At, Bt) do { __builtin_amdgcn_s_setprio(1); _Pragma("unroll") for (int m = 0; m < 4; ++m) _Pragma("unroll") for (int n = 0; n < 2; ++n) _Pragma("unroll") for (int k = 0; k < 2; ++k) \
;         acc[ai][bj][m][n] = mma16(Bt[n][k], At[m][k], acc[ai][bj][m][n]); __builtin_amdgcn_s_setprio(0); } while (0)
; #define PG8_WAIT_V(n) asm volatile("s_waitcnt vmcnt(" #n ")" ::: "memory")
; #define PG8_WAIT_L(n) asm volatile("s_waitcnt lgkmcnt(" #n ")" ::: "memory")
; #define PG8_BAR __builtin_amdgcn_s_barrier()
; #define PG8_SCHED __builtin_amdgcn_sched_barrier(0)
; template <class Epi, class Sched, bool ALIGN_EPI = false, bool SP2 = false>
; __device__ __forceinline__ void gemm_phase(PG8_LAS unsigned char* lds, const Gemm g, const Sched& S, const Epi& E) {
;     ...
;         for (int t = 0; t < nt; t += 2) {
;     ...
;             PG8_LDA(At, 1, 1); PG8_STAGE(PG8_SB(1, 0), b3, voffB); PG8_STAGE(PG8_SB(1, 1), b3 + hstepB, voffB); PG8_STAGE(PG8_SA(1, 0), a3, voffA);
;             PG8_WAIT_V(8); PG8_WAIT_L(0); PG8_BAR; PG8_MMA(1, 0, At, B0); PG8_MMA(1, 1, At, B1); PG8_BAR; PG8_SCHED;
;     ...
;         if constexpr (ALIGN_EPI) { if (wr == 0) PG8_BAR; }
	s_add_i32 s36, s46, s7
	v_lshl_add_u64 v[146:147], v[146:147], 0, s[40:41]
	s_mov_b32 m0, s36
	ds_read_b128 v[190:193], v152 offset:49152
	ds_read_b128 v[194:197], v152 offset:50176
	ds_read_b128 v[198:201], v152 offset:51200
	ds_read_b128 v[202:205], v152 offset:52224
	ds_read_b128 v[206:209], v152 offset:53248
	ds_read_b128 v[212:215], v152 offset:54272
	ds_read_b128 v[216:219], v152 offset:55296
	ds_read_b128 v[220:223], v152 offset:56320
	global_load_lds_dwordx4 v[146:147], off
	s_add_i32 m0, s36, 0x2000
	s_add_u32 s36, s64, 0x100080
	v_lshl_add_u64 v[146:147], v[224:225], 0, s[40:41]
	s_addc_u32 s37, s65, 0
	s_add_i32 s46, s47, s7
	global_load_lds_dwordx4 v[146:147], off
	v_lshl_add_u64 v[146:147], s[36:37], 0, v[132:133]
	s_mov_b32 m0, s46
	s_nop 0
	global_load_lds_dwordx4 v[146:147], off
	v_lshl_add_u64 v[146:147], s[36:37], 0, v[136:137]
	s_add_i32 m0, s46, 0x2000
	s_nop 0
	global_load_lds_dwordx4 v[146:147], off
	v_lshl_add_u64 v[146:147], v[226:227], 0, s[40:41]
	s_mov_b32 m0, s17
	s_nop 0
	global_load_lds_dwordx4 v[146:147], off
	v_lshl_add_u64 v[146:147], v[228:229], 0, s[40:41]
	s_mov_b32 m0, s18
	s_nop 0
	global_load_lds_dwordx4 v[146:147], off
	s_waitcnt vmcnt(8)
	s_waitcnt lgkmcnt(0)
	s_barrier
	s_setprio 1
	s_waitcnt lgkmcnt(0)
	v_mfma_f32_16x16x32_bf16 v[62:65], v[154:157], v[190:193], v[62:65]
	v_mfma_f32_16x16x32_bf16 v[62:65], v[158:161], v[194:197], v[62:65]
	v_mfma_f32_16x16x32_bf16 v[58:61], v[166:169], v[194:197], v[58:61]
	v_mfma_f32_16x16x32_bf16 v[58:61], v[162:165], v[190:193], v[58:61]
	v_mfma_f32_16x16x32_bf16 v[46:49], v[162:165], v[198:201], v[46:49]
	v_mfma_f32_16x16x32_bf16 v[46:49], v[166:169], v[202:205], v[46:49]
	v_mfma_f32_16x16x32_bf16 v[54:57], v[158:161], v[202:205], v[54:57]
	v_mfma_f32_16x16x32_bf16 v[54:57], v[154:157], v[198:201], v[54:57]
	v_mfma_f32_16x16x32_bf16 v[38:41], v[154:157], v[206:209], v[38:41]
	v_mfma_f32_16x16x32_bf16 v[38:41], v[158:161], v[212:215], v[38:41]
	v_mfma_f32_16x16x32_bf16 v[30:33], v[166:169], v[212:215], v[30:33]
	v_mfma_f32_16x16x32_bf16 v[30:33], v[162:165], v[206:209], v[30:33]
	v_mfma_f32_16x16x32_bf16 v[14:17], v[162:165], v[216:219], v[14:17]
	v_mfma_f32_16x16x32_bf16 v[14:17], v[166:169], v[220:223], v[14:17]
	v_mfma_f32_16x16x32_bf16 v[22:25], v[158:161], v[220:223], v[22:25]
	v_mfma_f32_16x16x32_bf16 v[22:25], v[154:157], v[216:219], v[22:25]
	s_setprio 0
	s_setprio 1
	v_mfma_f32_16x16x32_bf16 v[50:53], v[170:173], v[190:193], v[50:53]
	v_mfma_f32_16x16x32_bf16 v[50:53], v[174:177], v[194:197], v[50:53]
	v_mfma_f32_16x16x32_bf16 v[42:45], v[186:189], v[194:197], v[42:45]
	v_mfma_f32_16x16x32_bf16 v[42:45], v[182:185], v[190:193], v[42:45]
	v_mfma_f32_16x16x32_bf16 v[26:29], v[182:185], v[198:201], v[26:29]
	v_mfma_f32_16x16x32_bf16 v[26:29], v[186:189], v[202:205], v[26:29]
	v_mfma_f32_16x16x32_bf16 v[34:37], v[174:177], v[202:205], v[34:37]
	v_mfma_f32_16x16x32_bf16 v[34:37], v[170:173], v[198:201], v[34:37]
	v_mfma_f32_16x16x32_bf16 v[18:21], v[170:173], v[206:209], v[18:21]
	v_mfma_f32_16x16x32_bf16 v[18:21], v[174:177], v[212:215], v[18:21]
	v_mfma_f32_16x16x32_bf16 v[10:13], v[186:189], v[212:215], v[10:13]
	v_mfma_f32_16x16x32_bf16 v[10:13], v[182:185], v[206:209], v[10:13]
	v_mfma_f32_16x16x32_bf16 v[2:5], v[182:185], v[216:219], v[2:5]
	v_mfma_f32_16x16x32_bf16 v[2:5], v[186:189], v[220:223], v[2:5]
	v_mfma_f32_16x16x32_bf16 v[6:9], v[174:177], v[220:223], v[6:9]
	v_mfma_f32_16x16x32_bf16 v[6:9], v[170:173], v[216:219], v[6:9]
	s_setprio 0
	s_barrier
	s_add_i32 s35, s35, 2
	s_add_u32 s0, s0, 0x100
	s_addc_u32 s1, s1, 0
	s_add_u32 s29, s29, 0x100
	s_addc_u32 s33, s33, 0
	s_cmp_gt_u32 s35, 61
	s_cbranch_scc0 .LBB0_660
	s_and_b64 vcc, exec, s[42:43]
	s_cbranch_vccz .LBB0_663
	s_barrier

; #define PG8_STAGE(bufoff, gbase, voff) do { _Pragma("unroll") for (int _i = 0; _i < 2; ++_i) \
;         __builtin_amdgcn_global_load_lds((const unsigned*)((const char*)(gbase) + (voff)[_i]), (PG8_LAS unsigned*)(lds + (bufoff) + ldsw + _i * 8192), 16, 0, 0); } while (0)
; #define PG8_LDA(dst, b, h) do { _Pragma("unroll") for (int m = 0; m < 4; ++m) _Pragma("unroll") for (int k = 0; k < 2; ++k) dst[m][k] = *(const PG8_LAS bf16x8*)(lds + PG8_SA(b, h) + aoff + m * 2048 + k * 1024); } while (0)
; #define PG8_LDB(dst, b, h) do { _Pragma("unroll") for (int n = 0; n < 2; ++n) _Pragma("unroll") for (int k = 0; k < 2; ++k) dst[n][k] = *(const PG8_LAS bf16x8*)(lds + PG8_SB(b, h) + boff + n * 2048 + k * 1024); } while (0)
; #define PG8_MMA(ai, bj, At, Bt) do { __builtin_amdgcn_s_setprio(1); _Pragma("unroll") for (int m = 0; m < 4; ++m) _Pragma("unroll") for (int n = 0; n < 2; ++n) _Pragma("unroll") for (int k = 0; k < 2; ++k) \
;         acc[ai][bj][m][n] = mma16(Bt[n][k], At[m][k], acc[ai][bj][m][n]); __builtin_amdgcn_s_setprio(0); } while (0)
; #define PG8_WAIT_V(n) asm volatile("s_waitcnt vmcnt(" #n ")" ::: "memory")
; #define PG8_WAIT_L(n) asm volatile("s_waitcnt lgkmcnt(" #n ")" ::: "memory")
; template <class Epi, class Sched, bool ALIGN_EPI = false, bool SP2 = false>
; __device__ __forceinline__ void gemm_phase(PG8_LAS unsigned char* lds, const Gemm g, const Sched& S, const Epi& E) {
;     ...
;         for (int t = 0; t < nt; t += 2) {
;             const bool last = (t == nt - 2);
;             const char* a1 = cA + (size_t)(t + 1) * kstep;
;             const char* a2 = last ? nA : cA + (size_t)(t + 2) * kstep; const char* b2 = last ? nB : cB + (size_t)(t + 2) * kstep;
;             const char* a3 = a2 + kstep; const char* b3 = b2 + kstep;
;             if (last && has_next) S.a_ready(nxt);
;             if constexpr (SP2) {
;             PG8_LDB(B0, 0, 0); PG8_LDB(B1, 0, 1); PG8_SCHED; PG8_LDA(At, 0, 0); PG8_STAGE(PG8_SA(1, 1), a1 + hstepA, voffA);
;             PG8_WAIT_V(8); PG8_WAIT_L(0); PG8_BAR; PG8_MMA(0, 0, At, B0); PG8_MMA(0, 1, At, B1); PG8_BAR; PG8_SCHED;
;             PG8_LDA(At, 0, 1); PG8_STAGE(PG8_SB(0, 0), b2, voffB); PG8_STAGE(PG8_SB(0, 1), b2 + hstepB, voffB); PG8_STAGE(PG8_SA(0, 0), a2, voffA);
;             PG8_WAIT_V(8); PG8_WAIT_L(0); PG8_BAR; PG8_MMA(1, 0, At, B0); PG8_MMA(1, 1, At, B1); PG8_BAR; PG8_SCHED;
.LBB0_841:
	ds_read_b128 v[90:93], v173
	ds_read_b128 v[94:97], v173 offset:1024
	ds_read_b128 v[98:101], v173 offset:2048
	ds_read_b128 v[106:109], v173 offset:3072
	ds_read_b128 v[182:185], v174
	ds_read_b128 v[186:189], v174 offset:1024
	ds_read_b128 v[190:193], v174 offset:2048
	ds_read_b128 v[194:197], v174 offset:3072
	s_add_u32 s58, s56, 0xfff80080
	s_addc_u32 s59, s57, -1
	s_cmp_eq_u32 s68, 28
	s_cselect_b32 s61, s62, s59
	s_cselect_b32 s60, s63, s58
	s_cselect_b32 s59, s64, s67
	s_cselect_b32 s58, s65, s66
	v_lshl_add_u64 v[166:167], s[56:57], 0, v[158:159]
	s_add_i32 m0, s12, 0xc000
	ds_read_b128 v[198:201], v175
	ds_read_b128 v[202:205], v175 offset:1024
	ds_read_b128 v[206:209], v175 offset:2048
	ds_read_b128 v[212:215], v175 offset:3072
	ds_read_b128 v[216:219], v175 offset:4096
	ds_read_b128 v[220:223], v175 offset:5120
	ds_read_b128 v[224:227], v175 offset:6144
	ds_read_b128 v[228:231], v175 offset:7168
	global_load_lds_dwordx4 v[166:167], off
	v_lshl_add_u64 v[166:167], s[56:57], 0, v[160:161]
	s_add_i32 m0, s12, 0xe000
	s_nop 0
	global_load_lds_dwordx4 v[166:167], off
	s_waitcnt vmcnt(8)
	s_waitcnt lgkmcnt(0)
	s_barrier
	s_setprio 1
	s_waitcnt lgkmcnt(0)
	v_mfma_i32_16x16x64_i8 v[142:145], v[90:93], v[198:201], v[142:145]
	v_mfma_i32_16x16x64_i8 v[142:145], v[94:97], v[202:205], v[142:145]
	v_mfma_i32_16x16x64_i8 v[138:141], v[106:109], v[202:205], v[138:141]
	v_mfma_i32_16x16x64_i8 v[138:141], v[98:101], v[198:201], v[138:141]
	v_mfma_i32_16x16x64_i8 v[122:125], v[98:101], v[206:209], v[122:125]
	v_mfma_i32_16x16x64_i8 v[122:125], v[106:109], v[212:215], v[122:125]
	v_mfma_i32_16x16x64_i8 v[126:129], v[94:97], v[212:215], v[126:129]
	v_mfma_i32_16x16x64_i8 v[126:129], v[90:93], v[206:209], v[126:129]
	v_mfma_i32_16x16x64_i8 v[110:113], v[90:93], v[216:219], v[110:113]
	v_mfma_i32_16x16x64_i8 v[110:113], v[94:97], v[220:223], v[110:113]
	v_mfma_i32_16x16x64_i8 v[102:105], v[106:109], v[220:223], v[102:105]
	v_mfma_i32_16x16x64_i8 v[102:105], v[98:101], v[216:219], v[102:105]
	v_mfma_i32_16x16x64_i8 v[74:77], v[98:101], v[224:227], v[74:77]
	v_mfma_i32_16x16x64_i8 v[74:77], v[106:109], v[228:231], v[74:77]
	v_mfma_i32_16x16x64_i8 v[78:81], v[94:97], v[228:231], v[78:81]
	v_mfma_i32_16x16x64_i8 v[78:81], v[90:93], v[224:227], v[78:81]
	s_setprio 0
	s_setprio 1
	v_mfma_i32_16x16x64_i8 v[134:137], v[182:185], v[198:201], v[134:137]
	v_mfma_i32_16x16x64_i8 v[134:137], v[186:189], v[202:205], v[134:137]
	v_mfma_i32_16x16x64_i8 v[130:133], v[194:197], v[202:205], v[130:133]
	v_mfma_i32_16x16x64_i8 v[130:133], v[190:193], v[198:201], v[130:133]
	v_mfma_i32_16x16x64_i8 v[114:117], v[190:193], v[206:209], v[114:117]
	v_mfma_i32_16x16x64_i8 v[114:117], v[194:197], v[212:215], v[114:117]
	v_mfma_i32_16x16x64_i8 v[118:121], v[186:189], v[212:215], v[118:121]
	v_mfma_i32_16x16x64_i8 v[118:121], v[182:185], v[206:209], v[118:121]
	v_mfma_i32_16x16x64_i8 v[86:89], v[182:185], v[216:219], v[86:89]
	v_mfma_i32_16x16x64_i8 v[86:89], v[186:189], v[220:223], v[86:89]
	v_mfma_i32_16x16x64_i8 v[82:85], v[194:197], v[220:223], v[82:85]
	v_mfma_i32_16x16x64_i8 v[82:85], v[190:193], v[216:219], v[82:85]
	v_mfma_i32_16x16x64_i8 v[66:69], v[190:193], v[224:227], v[66:69]
	v_mfma_i32_16x16x64_i8 v[66:69], v[194:197], v[228:231], v[66:69]
	v_mfma_i32_16x16x64_i8 v[70:73], v[186:189], v[228:231], v[70:73]
	v_mfma_i32_16x16x64_i8 v[70:73], v[182:185], v[224:227], v[70:73]
	s_setprio 0
	s_barrier
	s_add_i32 s69, s27, s6
	v_lshl_add_u64 v[166:167], s[58:59], 0, v[150:151]
	s_mov_b32 m0, s69
	ds_read_b128 v[198:201], v175 offset:16384
	ds_read_b128 v[202:205], v175 offset:17408
	ds_read_b128 v[206:209], v175 offset:18432
	ds_read_b128 v[212:215], v175 offset:19456
	ds_read_b128 v[216:219], v175 offset:20480
	ds_read_b128 v[220:223], v175 offset:21504
	ds_read_b128 v[224:227], v175 offset:22528
	ds_read_b128 v[228:231], v175 offset:23552
	global_load_lds_dwordx4 v[166:167], off
	s_add_i32 m0, s69, 0x2000
	s_add_u32 s70, s58, 0x80000
	v_lshl_add_u64 v[176:177], s[58:59], 0, v[146:147]
	s_addc_u32 s71, s59, 0
	s_add_i32 s69, s28, s6
	global_load_lds_dwordx4 v[176:177], off
	v_lshl_add_u64 v[232:233], s[70:71], 0, v[150:151]
	s_mov_b32 m0, s69
	v_lshl_add_u64 v[234:235], s[60:61], 0, v[148:149]
	global_load_lds_dwordx4 v[232:233], off
	v_lshl_add_u64 v[232:233], s[70:71], 0, v[146:147]
	s_add_i32 m0, s69, 0x2000
	s_nop 0
	global_load_lds_dwordx4 v[232:233], off
	v_lshl_add_u64 v[232:233], s[60:61], 0, v[152:153]
	s_mov_b32 m0, s12
	s_nop 0
	global_load_lds_dwordx4 v[232:233], off
	s_mov_b32 m0, s13
	s_nop 0
	global_load_lds_dwordx4 v[234:235], off
	s_waitcnt vmcnt(8)
	s_waitcnt lgkmcnt(0)
	s_barrier
; #define PG8_STAGE(bufoff, gbase, voff) do { _Pragma("unroll") for (int _i = 0; _i < 2; ++_i) \
;         __builtin_amdgcn_global_load_lds((const unsigned*)((const char*)(gbase) + (voff)[_i]), (PG8_LAS unsigned*)(lds + (bufoff) + ldsw + _i * 8192), 16, 0, 0); } while (0)
; #define PG8_LDA(dst, b, h) do { _Pragma("unroll") for (int m = 0; m < 4; ++m) _Pragma("unroll") for (int k = 0; k < 2; ++k) dst[m][k] = *(const PG8_LAS bf16x8*)(lds + PG8_SA(b, h) + aoff + m * 2048 + k * 1024); } while (0)
; #define PG8_LDB(dst, b, h) do { _Pragma("unroll") for (int n = 0; n < 2; ++n) _Pragma("unroll") for (int k = 0; k < 2; ++k) dst[n][k] = *(const PG8_LAS bf16x8*)(lds + PG8_SB(b, h) + boff + n * 2048 + k * 1024); } while (0)
; #define PG8_MMA(ai, bj, At, Bt) do { __builtin_amdgcn_s_setprio(1); _Pragma("unroll") for (int m = 0; m < 4; ++m) _Pragma("unroll") for (int n = 0; n < 2; ++n) _Pragma("unroll") for (int k = 0; k < 2; ++k) \
;         acc[ai][bj][m][n] = mma16(Bt[n][k], At[m][k], acc[ai][bj][m][n]); __builtin_amdgcn_s_setprio(0); } while (0)
; #define PG8_WAIT_V(n) asm volatile("s_waitcnt vmcnt(" #n ")" ::: "memory")
; #define PG8_WAIT_L(n) asm volatile("s_waitcnt lgkmcnt(" #n ")" ::: "memory")
; #define PG8_BAR __builtin_amdgcn_s_barrier()
; #define PG8_SCHED __builtin_amdgcn_sched_barrier(0)
; template <class Epi, class Sched, bool ALIGN_EPI = false, bool SP2 = false>
; __device__ __forceinline__ void gemm_phase(PG8_LAS unsigned char* lds, const Gemm g, const Sched& S, const Epi& E) {
;     ...
;             PG8_WAIT_V(8); PG8_WAIT_L(0); PG8_BAR; PG8_MMA(1, 0, At, B0); PG8_MMA(1, 1, At, B1); PG8_BAR; PG8_SCHED;
;             PG8_LDB(B0, 1, 0); PG8_LDB(B1, 1, 1); PG8_SCHED; PG8_LDA(At, 1, 0); PG8_STAGE(PG8_SA(0, 1), a2 + hstepA, voffA);
;             PG8_WAIT_V(8); PG8_WAIT_L(0); PG8_BAR; PG8_MMA(0, 0, At, B0); PG8_MMA(0, 1, At, B1); PG8_BAR; PG8_SCHED;
;             PG8_LDA(At, 1, 1); PG8_STAGE(PG8_SB(1, 0), b3, voffB); PG8_STAGE(PG8_SB(1, 1), b3 + hstepB, voffB); PG8_STAGE(PG8_SA(1, 0), a3, voffA);
	s_setprio 1
	s_waitcnt lgkmcnt(0)
	v_mfma_i32_16x16x64_i8 v[62:65], v[90:93], v[198:201], v[62:65]
	v_mfma_i32_16x16x64_i8 v[62:65], v[94:97], v[202:205], v[62:65]
	v_mfma_i32_16x16x64_i8 v[58:61], v[106:109], v[202:205], v[58:61]
	v_mfma_i32_16x16x64_i8 v[58:61], v[98:101], v[198:201], v[58:61]
	v_mfma_i32_16x16x64_i8 v[42:45], v[98:101], v[206:209], v[42:45]
	v_mfma_i32_16x16x64_i8 v[42:45], v[106:109], v[212:215], v[42:45]
	v_mfma_i32_16x16x64_i8 v[46:49], v[94:97], v[212:215], v[46:49]
	v_mfma_i32_16x16x64_i8 v[46:49], v[90:93], v[206:209], v[46:49]
	v_mfma_i32_16x16x64_i8 v[30:33], v[90:93], v[216:219], v[30:33]
	v_mfma_i32_16x16x64_i8 v[30:33], v[94:97], v[220:223], v[30:33]
	v_mfma_i32_16x16x64_i8 v[26:29], v[106:109], v[220:223], v[26:29]
	v_mfma_i32_16x16x64_i8 v[26:29], v[98:101], v[216:219], v[26:29]
	v_mfma_i32_16x16x64_i8 v[10:13], v[98:101], v[224:227], v[10:13]
	v_mfma_i32_16x16x64_i8 v[10:13], v[106:109], v[228:231], v[10:13]
	v_mfma_i32_16x16x64_i8 v[14:17], v[94:97], v[228:231], v[14:17]
	v_mfma_i32_16x16x64_i8 v[14:17], v[90:93], v[224:227], v[14:17]
	s_setprio 0
	s_setprio 1
	v_mfma_i32_16x16x64_i8 v[54:57], v[182:185], v[198:201], v[54:57]
	v_mfma_i32_16x16x64_i8 v[54:57], v[186:189], v[202:205], v[54:57]
	v_mfma_i32_16x16x64_i8 v[50:53], v[194:197], v[202:205], v[50:53]
	v_mfma_i32_16x16x64_i8 v[50:53], v[190:193], v[198:201], v[50:53]
	v_mfma_i32_16x16x64_i8 v[34:37], v[190:193], v[206:209], v[34:37]
	v_mfma_i32_16x16x64_i8 v[34:37], v[194:197], v[212:215], v[34:37]
	v_mfma_i32_16x16x64_i8 v[38:41], v[186:189], v[212:215], v[38:41]
	v_mfma_i32_16x16x64_i8 v[38:41], v[182:185], v[206:209], v[38:41]
	v_mfma_i32_16x16x64_i8 v[22:25], v[182:185], v[216:219], v[22:25]
	v_mfma_i32_16x16x64_i8 v[22:25], v[186:189], v[220:223], v[22:25]
	v_mfma_i32_16x16x64_i8 v[18:21], v[194:197], v[220:223], v[18:21]
	v_mfma_i32_16x16x64_i8 v[18:21], v[190:193], v[216:219], v[18:21]
	v_mfma_i32_16x16x64_i8 v[2:5], v[190:193], v[224:227], v[2:5]
	v_mfma_i32_16x16x64_i8 v[2:5], v[194:197], v[228:231], v[2:5]
	v_mfma_i32_16x16x64_i8 v[6:9], v[186:189], v[228:231], v[6:9]
	v_mfma_i32_16x16x64_i8 v[6:9], v[182:185], v[224:227], v[6:9]
	s_setprio 0
	s_barrier
	s_add_i32 s69, 0, 0x18000
	s_add_i32 s70, 0, 0x1c000
	v_add_u32_e32 v106, s69, v171
	v_add_u32_e32 v181, s70, v171
	ds_read_b128 v[90:93], v106
	ds_read_b128 v[94:97], v106 offset:1024
	ds_read_b128 v[98:101], v106 offset:2048
	ds_read_b128 v[106:109], v106 offset:3072
	ds_read_b128 v[182:185], v181
	ds_read_b128 v[186:189], v181 offset:1024
	ds_read_b128 v[190:193], v181 offset:2048
	ds_read_b128 v[194:197], v181 offset:3072
	s_add_u32 s60, s60, 0x80000
	s_addc_u32 s61, s61, 0
	s_mov_b32 m0, s16
	v_lshl_add_u64 v[236:237], s[60:61], 0, v[152:153]
	ds_read_b128 v[198:201], v175 offset:32768
	ds_read_b128 v[202:205], v175 offset:33792
	ds_read_b128 v[206:209], v175 offset:34816
	ds_read_b128 v[212:215], v175 offset:35840
	ds_read_b128 v[216:219], v175 offset:36864
	ds_read_b128 v[220:223], v175 offset:37888
	ds_read_b128 v[224:227], v175 offset:38912
	ds_read_b128 v[228:231], v175 offset:39936
	global_load_lds_dwordx4 v[236:237], off
	v_lshl_add_u64 v[236:237], s[60:61], 0, v[148:149]
	s_mov_b32 m0, s17
	s_nop 0
	global_load_lds_dwordx4 v[236:237], off
	s_waitcnt vmcnt(8)
	s_waitcnt lgkmcnt(0)
	s_barrier
	s_setprio 1
	s_waitcnt lgkmcnt(0)
	v_mfma_i32_16x16x64_i8 v[142:145], v[90:93], v[198:201], v[142:145]
	v_mfma_i32_16x16x64_i8 v[142:145], v[94:97], v[202:205], v[142:145]
	v_mfma_i32_16x16x64_i8 v[138:141], v[106:109], v[202:205], v[138:141]
	v_mfma_i32_16x16x64_i8 v[138:141], v[98:101], v[198:201], v[138:141]
	v_mfma_i32_16x16x64_i8 v[122:125], v[98:101], v[206:209], v[122:125]
	v_mfma_i32_16x16x64_i8 v[122:125], v[106:109], v[212:215], v[122:125]
	v_mfma_i32_16x16x64_i8 v[126:129], v[94:97], v[212:215], v[126:129]
	v_mfma_i32_16x16x64_i8 v[126:129], v[90:93], v[206:209], v[126:129]
	v_mfma_i32_16x16x64_i8 v[110:113], v[90:93], v[216:219], v[110:113]
	v_mfma_i32_16x16x64_i8 v[110:113], v[94:97], v[220:223], v[110:113]
	v_mfma_i32_16x16x64_i8 v[102:105], v[106:109], v[220:223], v[102:105]
	v_mfma_i32_16x16x64_i8 v[102:105], v[98:101], v[216:219], v[102:105]
	v_mfma_i32_16x16x64_i8 v[74:77], v[98:101], v[224:227], v[74:77]
	v_mfma_i32_16x16x64_i8 v[74:77], v[106:109], v[228:231], v[74:77]
	v_mfma_i32_16x16x64_i8 v[78:81], v[94:97], v[228:231], v[78:81]
	v_mfma_i32_16x16x64_i8 v[78:81], v[90:93], v[224:227], v[78:81]
	s_setprio 0
	s_setprio 1
	v_mfma_i32_16x16x64_i8 v[134:137], v[182:185], v[198:201], v[134:137]
	v_mfma_i32_16x16x64_i8 v[134:137], v[186:189], v[202:205], v[134:137]
	v_mfma_i32_16x16x64_i8 v[130:133], v[194:197], v[202:205], v[130:133]
	v_mfma_i32_16x16x64_i8 v[130:133], v[190:193], v[198:201], v[130:133]
	v_mfma_i32_16x16x64_i8 v[114:117], v[190:193], v[206:209], v[114:117]
	v_mfma_i32_16x16x64_i8 v[114:117], v[194:197], v[212:215], v[114:117]
	v_mfma_i32_16x16x64_i8 v[118:121], v[186:189], v[212:215], v[118:121]
	v_mfma_i32_16x16x64_i8 v[118:121], v[182:185], v[206:209], v[118:121]
	v_mfma_i32_16x16x64_i8 v[86:89], v[182:185], v[216:219], v[86:89]
	v_mfma_i32_16x16x64_i8 v[86:89], v[186:189], v[220:223], v[86:89]
	v_mfma_i32_16x16x64_i8 v[82:85], v[194:197], v[220:223], v[82:85]
	v_mfma_i32_16x16x64_i8 v[82:85], v[190:193], v[216:219], v[82:85]
	v_mfma_i32_16x16x64_i8 v[66:69], v[190:193], v[224:227], v[66:69]
	v_mfma_i32_16x16x64_i8 v[66:69], v[194:197], v[228:231], v[66:69]
	v_mfma_i32_16x16x64_i8 v[70:73], v[186:189], v[228:231], v[70:73]
	v_mfma_i32_16x16x64_i8 v[70:73], v[182:185], v[224:227], v[70:73]
	s_setprio 0
	s_barrier
; #define PG8_STAGE(bufoff, gbase, voff) do { _Pragma("unroll") for (int _i = 0; _i < 2; ++_i) \
;         __builtin_amdgcn_global_load_lds((const unsigned*)((const char*)(gbase) + (voff)[_i]), (PG8_LAS unsigned*)(lds + (bufoff) + ldsw + _i * 8192), 16, 0, 0); } while (0)
; #define PG8_LDA(dst, b, h) do { _Pragma("unroll") for (int m = 0; m < 4; ++m) _Pragma("unroll") for (int k = 0; k < 2; ++k) dst[m][k] = *(const PG8_LAS bf16x8*)(lds + PG8_SA(b, h) + aoff + m * 2048 + k * 1024); } while (0)
; #define PG8_MMA(ai, bj, At, Bt) do { __builtin_amdgcn_s_setprio(1); _Pragma("unroll") for (int m = 0; m < 4; ++m) _Pragma("unroll") for (int n = 0; n < 2; ++n) _Pragma("unroll") for (int k = 0; k < 2; ++k) \
;         acc[ai][bj][m][n] = mma16(Bt[n][k], At[m][k], acc[ai][bj][m][n]); __builtin_amdgcn_s_setprio(0); } while (0)
; #define PG8_WAIT_V(n) asm volatile("s_waitcnt vmcnt(" #n ")" ::: "memory")
; #define PG8_WAIT_L(n) asm volatile("s_waitcnt lgkmcnt(" #n ")" ::: "memory")
; #define PG8_BAR __builtin_amdgcn_s_barrier()
; #define PG8_SCHED __builtin_amdgcn_sched_barrier(0)
; template <class Epi, class Sched, bool ALIGN_EPI = false, bool SP2 = false>
; __device__ __forceinline__ void gemm_phase(PG8_LAS unsigned char* lds, const Gemm g, const Sched& S, const Epi& E) {
;     ...
;         for (int t = 0; t < nt; t += 2) {
;             const bool last = (t == nt - 2);
;             const char* a1 = cA + (size_t)(t + 1) * kstep;
;             const char* a2 = last ? nA : cA + (size_t)(t + 2) * kstep; const char* b2 = last ? nB : cB + (size_t)(t + 2) * kstep;
;             const char* a3 = a2 + kstep; const char* b3 = b2 + kstep;
;             if (last && has_next) S.a_ready(nxt);
;     ...
;             PG8_LDA(At, 1, 1); PG8_STAGE(PG8_SB(1, 0), b3, voffB); PG8_STAGE(PG8_SB(1, 1), b3 + hstepB, voffB); PG8_STAGE(PG8_SA(1, 0), a3, voffA);
;             PG8_WAIT_V(8); PG8_WAIT_L(0); PG8_BAR; PG8_MMA(1, 0, At, B0); PG8_MMA(1, 1, At, B1); PG8_BAR; PG8_SCHED;
	s_add_i32 s60, s69, s6
	v_lshl_add_u64 v[166:167], v[166:167], 0, s[36:37]
	s_mov_b32 m0, s60
	ds_read_b128 v[198:201], v175 offset:49152
	ds_read_b128 v[202:205], v175 offset:50176
	ds_read_b128 v[206:209], v175 offset:51200
	ds_read_b128 v[212:215], v175 offset:52224
	ds_read_b128 v[216:219], v175 offset:53248
	ds_read_b128 v[220:223], v175 offset:54272
	ds_read_b128 v[224:227], v175 offset:55296
	ds_read_b128 v[228:231], v175 offset:56320
	global_load_lds_dwordx4 v[166:167], off
	s_add_i32 m0, s60, 0x2000
	s_add_u32 s58, s58, 0x80080
	v_lshl_add_u64 v[166:167], v[176:177], 0, s[36:37]
	s_addc_u32 s59, s59, 0
	s_add_i32 s60, s70, s6
	global_load_lds_dwordx4 v[166:167], off
	v_lshl_add_u64 v[166:167], s[58:59], 0, v[150:151]
	s_mov_b32 m0, s60
	s_nop 0
	global_load_lds_dwordx4 v[166:167], off
	v_lshl_add_u64 v[166:167], s[58:59], 0, v[146:147]
	s_add_i32 m0, s60, 0x2000
	s_nop 0
	global_load_lds_dwordx4 v[166:167], off
	v_lshl_add_u64 v[166:167], v[232:233], 0, s[36:37]
	s_mov_b32 m0, s24
	s_nop 0
	global_load_lds_dwordx4 v[166:167], off
	v_lshl_add_u64 v[166:167], v[234:235], 0, s[36:37]
	s_mov_b32 m0, s25
	s_nop 0
	global_load_lds_dwordx4 v[166:167], off
	s_waitcnt vmcnt(8)
	s_waitcnt lgkmcnt(0)
	s_barrier
	s_setprio 1
	s_waitcnt lgkmcnt(0)
	v_mfma_i32_16x16x64_i8 v[62:65], v[90:93], v[198:201], v[62:65]
	v_mfma_i32_16x16x64_i8 v[62:65], v[94:97], v[202:205], v[62:65]
	v_mfma_i32_16x16x64_i8 v[58:61], v[106:109], v[202:205], v[58:61]
	v_mfma_i32_16x16x64_i8 v[58:61], v[98:101], v[198:201], v[58:61]
	v_mfma_i32_16x16x64_i8 v[42:45], v[98:101], v[206:209], v[42:45]
	v_mfma_i32_16x16x64_i8 v[42:45], v[106:109], v[212:215], v[42:45]
	v_mfma_i32_16x16x64_i8 v[46:49], v[94:97], v[212:215], v[46:49]
	v_mfma_i32_16x16x64_i8 v[46:49], v[90:93], v[206:209], v[46:49]
	v_mfma_i32_16x16x64_i8 v[30:33], v[90:93], v[216:219], v[30:33]
	v_mfma_i32_16x16x64_i8 v[30:33], v[94:97], v[220:223], v[30:33]
	v_mfma_i32_16x16x64_i8 v[26:29], v[106:109], v[220:223], v[26:29]
	v_mfma_i32_16x16x64_i8 v[26:29], v[98:101], v[216:219], v[26:29]
	v_mfma_i32_16x16x64_i8 v[10:13], v[98:101], v[224:227], v[10:13]
	v_mfma_i32_16x16x64_i8 v[10:13], v[106:109], v[228:231], v[10:13]
	v_mfma_i32_16x16x64_i8 v[14:17], v[94:97], v[228:231], v[14:17]
	v_mfma_i32_16x16x64_i8 v[14:17], v[90:93], v[224:227], v[14:17]
	s_setprio 0
	s_setprio 1
	v_mfma_i32_16x16x64_i8 v[54:57], v[182:185], v[198:201], v[54:57]
	v_mfma_i32_16x16x64_i8 v[54:57], v[186:189], v[202:205], v[54:57]
	v_mfma_i32_16x16x64_i8 v[50:53], v[194:197], v[202:205], v[50:53]
	v_mfma_i32_16x16x64_i8 v[50:53], v[190:193], v[198:201], v[50:53]
	v_mfma_i32_16x16x64_i8 v[34:37], v[190:193], v[206:209], v[34:37]
	v_mfma_i32_16x16x64_i8 v[34:37], v[194:197], v[212:215], v[34:37]
	v_mfma_i32_16x16x64_i8 v[38:41], v[186:189], v[212:215], v[38:41]
	v_mfma_i32_16x16x64_i8 v[38:41], v[182:185], v[206:209], v[38:41]
	v_mfma_i32_16x16x64_i8 v[22:25], v[182:185], v[216:219], v[22:25]
	v_mfma_i32_16x16x64_i8 v[22:25], v[186:189], v[220:223], v[22:25]
	v_mfma_i32_16x16x64_i8 v[18:21], v[194:197], v[220:223], v[18:21]
	v_mfma_i32_16x16x64_i8 v[18:21], v[190:193], v[216:219], v[18:21]
	v_mfma_i32_16x16x64_i8 v[2:5], v[190:193], v[224:227], v[2:5]
	v_mfma_i32_16x16x64_i8 v[2:5], v[194:197], v[228:231], v[2:5]
	v_mfma_i32_16x16x64_i8 v[6:9], v[186:189], v[228:231], v[6:9]
	v_mfma_i32_16x16x64_i8 v[6:9], v[182:185], v[224:227], v[6:9]
	s_setprio 0
	s_barrier
	s_add_i32 s68, s68, 2
	s_add_u32 s56, s56, 0x100
	s_addc_u32 s57, s57, 0
	s_add_u32 s66, s66, 0x100
	s_addc_u32 s67, s67, 0
	s_cmp_gt_u32 s68, 29
	s_cbranch_scc0 .LBB0_841
	s_and_b64 vcc, exec, s[44:45]
	s_cbranch_vccz .LBB0_844
	s_barrier

; #define PG8_STAGE(bufoff, gbase, voff) do { _Pragma("unroll") for (int _i = 0; _i < 2; ++_i) \
;         __builtin_amdgcn_global_load_lds((const unsigned*)((const char*)(gbase) + (voff)[_i]), (PG8_LAS unsigned*)(lds + (bufoff) + ldsw + _i * 8192), 16, 0, 0); } while (0)
; #define PG8_LDA(dst, b, h) do { _Pragma("unroll") for (int m = 0; m < 4; ++m) _Pragma("unroll") for (int k = 0; k < 2; ++k) dst[m][k] = *(const PG8_LAS bf16x8*)(lds + PG8_SA(b, h) + aoff + m * 2048 + k * 1024); } while (0)
; #define PG8_LDB(dst, b, h) do { _Pragma("unroll") for (int n = 0; n < 2; ++n) _Pragma("unroll") for (int k = 0; k < 2; ++k) dst[n][k] = *(const PG8_LAS bf16x8*)(lds + PG8_SB(b, h) + boff + n * 2048 + k * 1024); } while (0)
; #define PG8_MMA(ai, bj, At, Bt) do { __builtin_amdgcn_s_setprio(1); _Pragma("unroll") for (int m = 0; m < 4; ++m) _Pragma("unroll") for (int n = 0; n < 2; ++n) _Pragma("unroll") for (int k = 0; k < 2; ++k) \
;         acc[ai][bj][m][n] = mma16(Bt[n][k], At[m][k], acc[ai][bj][m][n]); __builtin_amdgcn_s_setprio(0); } while (0)
; #define PG8_WAIT_V(n) asm volatile("s_waitcnt vmcnt(" #n ")" ::: "memory")
; #define PG8_WAIT_L(n) asm volatile("s_waitcnt lgkmcnt(" #n ")" ::: "memory")
; template <class Epi, class Sched, bool ALIGN_EPI = false, bool SP2 = false>
; __device__ __forceinline__ void gemm_phase(PG8_LAS unsigned char* lds, const Gemm g, const Sched& S, const Epi& E) {
;     ...
;         for (int t = 0; t < nt; t += 2) {
;             const bool last = (t == nt - 2);
;             const char* a1 = cA + (size_t)(t + 1) * kstep;
;             const char* a2 = last ? nA : cA + (size_t)(t + 2) * kstep; const char* b2 = last ? nB : cB + (size_t)(t + 2) * kstep;
;             const char* a3 = a2 + kstep; const char* b3 = b2 + kstep;
;             if (last && has_next) S.a_ready(nxt);
;             if constexpr (SP2) {
;             PG8_LDB(B0, 0, 0); PG8_LDB(B1, 0, 1); PG8_SCHED; PG8_LDA(At, 0, 0); PG8_STAGE(PG8_SA(1, 1), a1 + hstepA, voffA);
;             PG8_WAIT_V(8); PG8_WAIT_L(0); PG8_BAR; PG8_MMA(0, 0, At, B0); PG8_MMA(0, 1, At, B1); PG8_BAR; PG8_SCHED;
;             PG8_LDA(At, 0, 1); PG8_STAGE(PG8_SB(0, 0), b2, voffB); PG8_STAGE(PG8_SB(0, 1), b2 + hstepB, voffB); PG8_STAGE(PG8_SA(0, 0), a2, voffA);
;             PG8_WAIT_V(8); PG8_WAIT_L(0); PG8_BAR; PG8_MMA(1, 0, At, B0); PG8_MMA(1, 1, At, B1); PG8_BAR; PG8_SCHED;
.LBB0_1020:
	ds_read_b128 v[122:125], v172
	ds_read_b128 v[126:129], v172 offset:1024
	ds_read_b128 v[130:133], v172 offset:2048
	ds_read_b128 v[138:141], v172 offset:3072
	ds_read_b128 v[182:185], v173
	ds_read_b128 v[186:189], v173 offset:1024
	ds_read_b128 v[190:193], v173 offset:2048
	ds_read_b128 v[194:197], v173 offset:3072
	s_add_u32 s58, s56, 0xffea8080
	s_addc_u32 s59, s57, -1
	s_cmpk_eq_i32 s67, 0x52
	s_cselect_b32 s61, s1, s59
	s_cselect_b32 s60, s0, s58
	s_cselect_b32 s59, s53, s66
	s_cselect_b32 s58, s52, s65
	v_lshl_add_u64 v[166:167], s[56:57], 0, v[158:159]
	s_add_i32 m0, s9, 0xc000
	ds_read_b128 v[198:201], v174
	ds_read_b128 v[202:205], v174 offset:1024
	ds_read_b128 v[206:209], v174 offset:2048
	ds_read_b128 v[212:215], v174 offset:3072
	ds_read_b128 v[216:219], v174 offset:4096
	ds_read_b128 v[220:223], v174 offset:5120
	ds_read_b128 v[224:227], v174 offset:6144
	ds_read_b128 v[228:231], v174 offset:7168
	global_load_lds_dwordx4 v[166:167], off
	v_lshl_add_u64 v[166:167], s[56:57], 0, v[160:161]
	s_add_i32 m0, s9, 0xe000
	s_nop 0
	global_load_lds_dwordx4 v[166:167], off
	s_waitcnt vmcnt(8)
	s_waitcnt lgkmcnt(0)
	s_barrier
	s_setprio 1
	s_waitcnt lgkmcnt(0)
	v_mfma_i32_16x16x64_i8 v[142:145], v[122:125], v[198:201], v[142:145]
	v_mfma_i32_16x16x64_i8 v[142:145], v[126:129], v[202:205], v[142:145]
	v_mfma_i32_16x16x64_i8 v[134:137], v[138:141], v[202:205], v[134:137]
	v_mfma_i32_16x16x64_i8 v[134:137], v[130:133], v[198:201], v[134:137]
	v_mfma_i32_16x16x64_i8 v[106:109], v[130:133], v[206:209], v[106:109]
	v_mfma_i32_16x16x64_i8 v[106:109], v[138:141], v[212:215], v[106:109]
	v_mfma_i32_16x16x64_i8 v[110:113], v[126:129], v[212:215], v[110:113]
	v_mfma_i32_16x16x64_i8 v[110:113], v[122:125], v[206:209], v[110:113]
	v_mfma_i32_16x16x64_i8 v[94:97], v[122:125], v[216:219], v[94:97]
	v_mfma_i32_16x16x64_i8 v[94:97], v[126:129], v[220:223], v[94:97]
	v_mfma_i32_16x16x64_i8 v[90:93], v[138:141], v[220:223], v[90:93]
	v_mfma_i32_16x16x64_i8 v[90:93], v[130:133], v[216:219], v[90:93]
	v_mfma_i32_16x16x64_i8 v[74:77], v[130:133], v[224:227], v[74:77]
	v_mfma_i32_16x16x64_i8 v[74:77], v[138:141], v[228:231], v[74:77]
	v_mfma_i32_16x16x64_i8 v[78:81], v[126:129], v[228:231], v[78:81]
	v_mfma_i32_16x16x64_i8 v[78:81], v[122:125], v[224:227], v[78:81]
	s_setprio 0
	s_setprio 1
	v_mfma_i32_16x16x64_i8 v[118:121], v[182:185], v[198:201], v[118:121]
	v_mfma_i32_16x16x64_i8 v[118:121], v[186:189], v[202:205], v[118:121]
	v_mfma_i32_16x16x64_i8 v[114:117], v[194:197], v[202:205], v[114:117]
	v_mfma_i32_16x16x64_i8 v[114:117], v[190:193], v[198:201], v[114:117]
	v_mfma_i32_16x16x64_i8 v[98:101], v[190:193], v[206:209], v[98:101]
	v_mfma_i32_16x16x64_i8 v[98:101], v[194:197], v[212:215], v[98:101]
	v_mfma_i32_16x16x64_i8 v[102:105], v[186:189], v[212:215], v[102:105]
	v_mfma_i32_16x16x64_i8 v[102:105], v[182:185], v[206:209], v[102:105]
	v_mfma_i32_16x16x64_i8 v[86:89], v[182:185], v[216:219], v[86:89]
	v_mfma_i32_16x16x64_i8 v[86:89], v[186:189], v[220:223], v[86:89]
	v_mfma_i32_16x16x64_i8 v[82:85], v[194:197], v[220:223], v[82:85]
	v_mfma_i32_16x16x64_i8 v[82:85], v[190:193], v[216:219], v[82:85]
	v_mfma_i32_16x16x64_i8 v[66:69], v[190:193], v[224:227], v[66:69]
	v_mfma_i32_16x16x64_i8 v[66:69], v[194:197], v[228:231], v[66:69]
	v_mfma_i32_16x16x64_i8 v[70:73], v[186:189], v[228:231], v[70:73]
	v_mfma_i32_16x16x64_i8 v[70:73], v[182:185], v[224:227], v[70:73]
	s_setprio 0
	s_barrier
	s_add_i32 s68, s29, s7
	v_lshl_add_u64 v[166:167], s[58:59], 0, v[148:149]
	s_mov_b32 m0, s68
	ds_read_b128 v[198:201], v174 offset:16384
	ds_read_b128 v[202:205], v174 offset:17408
	ds_read_b128 v[206:209], v174 offset:18432
	ds_read_b128 v[212:215], v174 offset:19456
	ds_read_b128 v[216:219], v174 offset:20480
	ds_read_b128 v[220:223], v174 offset:21504
	ds_read_b128 v[224:227], v174 offset:22528
	ds_read_b128 v[228:231], v174 offset:23552
	global_load_lds_dwordx4 v[166:167], off
	s_add_i32 m0, s68, 0x2000
	s_add_u32 s68, s58, 0x158000
	v_lshl_add_u64 v[176:177], s[58:59], 0, v[152:153]
	s_addc_u32 s69, s59, 0
	s_add_i32 s70, s33, s7
	global_load_lds_dwordx4 v[176:177], off
	v_lshl_add_u64 v[232:233], s[68:69], 0, v[148:149]
	s_mov_b32 m0, s70
	v_lshl_add_u64 v[234:235], s[60:61], 0, v[150:151]
	global_load_lds_dwordx4 v[232:233], off
	v_lshl_add_u64 v[232:233], s[68:69], 0, v[152:153]
	s_add_i32 m0, s70, 0x2000
	s_nop 0
	global_load_lds_dwordx4 v[232:233], off
	v_lshl_add_u64 v[232:233], s[60:61], 0, v[146:147]
	s_mov_b32 m0, s9
	s_nop 0
	global_load_lds_dwordx4 v[232:233], off
	s_mov_b32 m0, s11
	s_nop 0
	global_load_lds_dwordx4 v[234:235], off
	s_waitcnt vmcnt(8)
	s_waitcnt lgkmcnt(0)
	s_barrier
; #define PG8_STAGE(bufoff, gbase, voff) do { _Pragma("unroll") for (int _i = 0; _i < 2; ++_i) \
;         __builtin_amdgcn_global_load_lds((const unsigned*)((const char*)(gbase) + (voff)[_i]), (PG8_LAS unsigned*)(lds + (bufoff) + ldsw + _i * 8192), 16, 0, 0); } while (0)
; #define PG8_LDA(dst, b, h) do { _Pragma("unroll") for (int m = 0; m < 4; ++m) _Pragma("unroll") for (int k = 0; k < 2; ++k) dst[m][k] = *(const PG8_LAS bf16x8*)(lds + PG8_SA(b, h) + aoff + m * 2048 + k * 1024); } while (0)
; #define PG8_LDB(dst, b, h) do { _Pragma("unroll") for (int n = 0; n < 2; ++n) _Pragma("unroll") for (int k = 0; k < 2; ++k) dst[n][k] = *(const PG8_LAS bf16x8*)(lds + PG8_SB(b, h) + boff + n * 2048 + k * 1024); } while (0)
; #define PG8_MMA(ai, bj, At, Bt) do { __builtin_amdgcn_s_setprio(1); _Pragma("unroll") for (int m = 0; m < 4; ++m) _Pragma("unroll") for (int n = 0; n < 2; ++n) _Pragma("unroll") for (int k = 0; k < 2; ++k) \
;         acc[ai][bj][m][n] = mma16(Bt[n][k], At[m][k], acc[ai][bj][m][n]); __builtin_amdgcn_s_setprio(0); } while (0)
; #define PG8_WAIT_V(n) asm volatile("s_waitcnt vmcnt(" #n ")" ::: "memory")
; #define PG8_WAIT_L(n) asm volatile("s_waitcnt lgkmcnt(" #n ")" ::: "memory")
; #define PG8_BAR __builtin_amdgcn_s_barrier()
; #define PG8_SCHED __builtin_amdgcn_sched_barrier(0)
; template <class Epi, class Sched, bool ALIGN_EPI = false, bool SP2 = false>
; __device__ __forceinline__ void gemm_phase(PG8_LAS unsigned char* lds, const Gemm g, const Sched& S, const Epi& E) {
;     ...
;             PG8_WAIT_V(8); PG8_WAIT_L(0); PG8_BAR; PG8_MMA(1, 0, At, B0); PG8_MMA(1, 1, At, B1); PG8_BAR; PG8_SCHED;
;             PG8_LDB(B0, 1, 0); PG8_LDB(B1, 1, 1); PG8_SCHED; PG8_LDA(At, 1, 0); PG8_STAGE(PG8_SA(0, 1), a2 + hstepA, voffA);
;             PG8_WAIT_V(8); PG8_WAIT_L(0); PG8_BAR; PG8_MMA(0, 0, At, B0); PG8_MMA(0, 1, At, B1); PG8_BAR; PG8_SCHED;
;             PG8_LDA(At, 1, 1); PG8_STAGE(PG8_SB(1, 0), b3, voffB); PG8_STAGE(PG8_SB(1, 1), b3 + hstepB, voffB); PG8_STAGE(PG8_SA(1, 0), a3, voffA);
	s_setprio 1
	s_waitcnt lgkmcnt(0)
	v_mfma_i32_16x16x64_i8 v[62:65], v[122:125], v[198:201], v[62:65]
	v_mfma_i32_16x16x64_i8 v[62:65], v[126:129], v[202:205], v[62:65]
	v_mfma_i32_16x16x64_i8 v[58:61], v[138:141], v[202:205], v[58:61]
	v_mfma_i32_16x16x64_i8 v[58:61], v[130:133], v[198:201], v[58:61]
	v_mfma_i32_16x16x64_i8 v[42:45], v[130:133], v[206:209], v[42:45]
	v_mfma_i32_16x16x64_i8 v[42:45], v[138:141], v[212:215], v[42:45]
	v_mfma_i32_16x16x64_i8 v[46:49], v[126:129], v[212:215], v[46:49]
	v_mfma_i32_16x16x64_i8 v[46:49], v[122:125], v[206:209], v[46:49]
	v_mfma_i32_16x16x64_i8 v[30:33], v[122:125], v[216:219], v[30:33]
	v_mfma_i32_16x16x64_i8 v[30:33], v[126:129], v[220:223], v[30:33]
	v_mfma_i32_16x16x64_i8 v[26:29], v[138:141], v[220:223], v[26:29]
	v_mfma_i32_16x16x64_i8 v[26:29], v[130:133], v[216:219], v[26:29]
	v_mfma_i32_16x16x64_i8 v[10:13], v[130:133], v[224:227], v[10:13]
	v_mfma_i32_16x16x64_i8 v[10:13], v[138:141], v[228:231], v[10:13]
	v_mfma_i32_16x16x64_i8 v[14:17], v[126:129], v[228:231], v[14:17]
	v_mfma_i32_16x16x64_i8 v[14:17], v[122:125], v[224:227], v[14:17]
	s_setprio 0
	s_setprio 1
	v_mfma_i32_16x16x64_i8 v[54:57], v[182:185], v[198:201], v[54:57]
	v_mfma_i32_16x16x64_i8 v[54:57], v[186:189], v[202:205], v[54:57]
	v_mfma_i32_16x16x64_i8 v[50:53], v[194:197], v[202:205], v[50:53]
	v_mfma_i32_16x16x64_i8 v[50:53], v[190:193], v[198:201], v[50:53]
	v_mfma_i32_16x16x64_i8 v[34:37], v[190:193], v[206:209], v[34:37]
	v_mfma_i32_16x16x64_i8 v[34:37], v[194:197], v[212:215], v[34:37]
	v_mfma_i32_16x16x64_i8 v[38:41], v[186:189], v[212:215], v[38:41]
	v_mfma_i32_16x16x64_i8 v[38:41], v[182:185], v[206:209], v[38:41]
	v_mfma_i32_16x16x64_i8 v[22:25], v[182:185], v[216:219], v[22:25]
	v_mfma_i32_16x16x64_i8 v[22:25], v[186:189], v[220:223], v[22:25]
	v_mfma_i32_16x16x64_i8 v[18:21], v[194:197], v[220:223], v[18:21]
	v_mfma_i32_16x16x64_i8 v[18:21], v[190:193], v[216:219], v[18:21]
	v_mfma_i32_16x16x64_i8 v[2:5], v[190:193], v[224:227], v[2:5]
	v_mfma_i32_16x16x64_i8 v[2:5], v[194:197], v[228:231], v[2:5]
	v_mfma_i32_16x16x64_i8 v[6:9], v[186:189], v[228:231], v[6:9]
	v_mfma_i32_16x16x64_i8 v[6:9], v[182:185], v[224:227], v[6:9]
	s_setprio 0
	s_barrier
	s_add_i32 s68, 0, 0x18000
	s_add_i32 s69, 0, 0x1c000
	v_add_u32_e32 v138, s68, v170
	v_add_u32_e32 v175, s69, v170
	ds_read_b128 v[122:125], v138
	ds_read_b128 v[126:129], v138 offset:1024
	ds_read_b128 v[130:133], v138 offset:2048
	ds_read_b128 v[138:141], v138 offset:3072
	ds_read_b128 v[182:185], v175
	ds_read_b128 v[186:189], v175 offset:1024
	ds_read_b128 v[190:193], v175 offset:2048
	ds_read_b128 v[194:197], v175 offset:3072
	s_add_u32 s60, s60, 0x158000
	s_addc_u32 s61, s61, 0
	s_mov_b32 m0, s12
	v_lshl_add_u64 v[236:237], s[60:61], 0, v[146:147]
	ds_read_b128 v[198:201], v174 offset:32768
	ds_read_b128 v[202:205], v174 offset:33792
	ds_read_b128 v[206:209], v174 offset:34816
	ds_read_b128 v[212:215], v174 offset:35840
	ds_read_b128 v[216:219], v174 offset:36864
	ds_read_b128 v[220:223], v174 offset:37888
	ds_read_b128 v[224:227], v174 offset:38912
	ds_read_b128 v[228:231], v174 offset:39936
	global_load_lds_dwordx4 v[236:237], off
	v_lshl_add_u64 v[236:237], s[60:61], 0, v[150:151]
	s_mov_b32 m0, s13
	s_nop 0
	global_load_lds_dwordx4 v[236:237], off
	s_waitcnt vmcnt(8)
	s_waitcnt lgkmcnt(0)
	s_barrier
	s_setprio 1
	s_waitcnt lgkmcnt(0)
	v_mfma_i32_16x16x64_i8 v[142:145], v[122:125], v[198:201], v[142:145]
	v_mfma_i32_16x16x64_i8 v[142:145], v[126:129], v[202:205], v[142:145]
	v_mfma_i32_16x16x64_i8 v[134:137], v[138:141], v[202:205], v[134:137]
	v_mfma_i32_16x16x64_i8 v[134:137], v[130:133], v[198:201], v[134:137]
	v_mfma_i32_16x16x64_i8 v[106:109], v[130:133], v[206:209], v[106:109]
	v_mfma_i32_16x16x64_i8 v[106:109], v[138:141], v[212:215], v[106:109]
	v_mfma_i32_16x16x64_i8 v[110:113], v[126:129], v[212:215], v[110:113]
	v_mfma_i32_16x16x64_i8 v[110:113], v[122:125], v[206:209], v[110:113]
	v_mfma_i32_16x16x64_i8 v[94:97], v[122:125], v[216:219], v[94:97]
	v_mfma_i32_16x16x64_i8 v[94:97], v[126:129], v[220:223], v[94:97]
	v_mfma_i32_16x16x64_i8 v[90:93], v[138:141], v[220:223], v[90:93]
	v_mfma_i32_16x16x64_i8 v[90:93], v[130:133], v[216:219], v[90:93]
	v_mfma_i32_16x16x64_i8 v[74:77], v[130:133], v[224:227], v[74:77]
	v_mfma_i32_16x16x64_i8 v[74:77], v[138:141], v[228:231], v[74:77]
	v_mfma_i32_16x16x64_i8 v[78:81], v[126:129], v[228:231], v[78:81]
	v_mfma_i32_16x16x64_i8 v[78:81], v[122:125], v[224:227], v[78:81]
	s_setprio 0
	s_setprio 1
	v_mfma_i32_16x16x64_i8 v[118:121], v[182:185], v[198:201], v[118:121]
	v_mfma_i32_16x16x64_i8 v[118:121], v[186:189], v[202:205], v[118:121]
	v_mfma_i32_16x16x64_i8 v[114:117], v[194:197], v[202:205], v[114:117]
	v_mfma_i32_16x16x64_i8 v[114:117], v[190:193], v[198:201], v[114:117]
	v_mfma_i32_16x16x64_i8 v[98:101], v[190:193], v[206:209], v[98:101]
	v_mfma_i32_16x16x64_i8 v[98:101], v[194:197], v[212:215], v[98:101]
	v_mfma_i32_16x16x64_i8 v[102:105], v[186:189], v[212:215], v[102:105]
	v_mfma_i32_16x16x64_i8 v[102:105], v[182:185], v[206:209], v[102:105]
	v_mfma_i32_16x16x64_i8 v[86:89], v[182:185], v[216:219], v[86:89]
	v_mfma_i32_16x16x64_i8 v[86:89], v[186:189], v[220:223], v[86:89]
	v_mfma_i32_16x16x64_i8 v[82:85], v[194:197], v[220:223], v[82:85]
	v_mfma_i32_16x16x64_i8 v[82:85], v[190:193], v[216:219], v[82:85]
	v_mfma_i32_16x16x64_i8 v[66:69], v[190:193], v[224:227], v[66:69]
	v_mfma_i32_16x16x64_i8 v[66:69], v[194:197], v[228:231], v[66:69]
	v_mfma_i32_16x16x64_i8 v[70:73], v[186:189], v[228:231], v[70:73]
	v_mfma_i32_16x16x64_i8 v[70:73], v[182:185], v[224:227], v[70:73]
	s_setprio 0
	s_barrier
; #define PG8_STAGE(bufoff, gbase, voff) do { _Pragma("unroll") for (int _i = 0; _i < 2; ++_i) \
;         __builtin_amdgcn_global_load_lds((const unsigned*)((const char*)(gbase) + (voff)[_i]), (PG8_LAS unsigned*)(lds + (bufoff) + ldsw + _i * 8192), 16, 0, 0); } while (0)
; #define PG8_LDA(dst, b, h) do { _Pragma("unroll") for (int m = 0; m < 4; ++m) _Pragma("unroll") for (int k = 0; k < 2; ++k) dst[m][k] = *(const PG8_LAS bf16x8*)(lds + PG8_SA(b, h) + aoff + m * 2048 + k * 1024); } while (0)
; #define PG8_MMA(ai, bj, At, Bt) do { __builtin_amdgcn_s_setprio(1); _Pragma("unroll") for (int m = 0; m < 4; ++m) _Pragma("unroll") for (int n = 0; n < 2; ++n) _Pragma("unroll") for (int k = 0; k < 2; ++k) \
;         acc[ai][bj][m][n] = mma16(Bt[n][k], At[m][k], acc[ai][bj][m][n]); __builtin_amdgcn_s_setprio(0); } while (0)
; #define PG8_WAIT_V(n) asm volatile("s_waitcnt vmcnt(" #n ")" ::: "memory")
; #define PG8_WAIT_L(n) asm volatile("s_waitcnt lgkmcnt(" #n ")" ::: "memory")
; #define PG8_BAR __builtin_amdgcn_s_barrier()
; #define PG8_SCHED __builtin_amdgcn_sched_barrier(0)
; template <class Epi, class Sched, bool ALIGN_EPI = false, bool SP2 = false>
; __device__ __forceinline__ void gemm_phase(PG8_LAS unsigned char* lds, const Gemm g, const Sched& S, const Epi& E) {
;     ...
;         for (int t = 0; t < nt; t += 2) {
;             const bool last = (t == nt - 2);
;             const char* a1 = cA + (size_t)(t + 1) * kstep;
;             const char* a2 = last ? nA : cA + (size_t)(t + 2) * kstep; const char* b2 = last ? nB : cB + (size_t)(t + 2) * kstep;
;             const char* a3 = a2 + kstep; const char* b3 = b2 + kstep;
;             if (last && has_next) S.a_ready(nxt);
;     ...
;             PG8_LDA(At, 1, 1); PG8_STAGE(PG8_SB(1, 0), b3, voffB); PG8_STAGE(PG8_SB(1, 1), b3 + hstepB, voffB); PG8_STAGE(PG8_SA(1, 0), a3, voffA);
;             PG8_WAIT_V(8); PG8_WAIT_L(0); PG8_BAR; PG8_MMA(1, 0, At, B0); PG8_MMA(1, 1, At, B1); PG8_BAR; PG8_SCHED;
	s_add_i32 s60, s68, s7
	v_lshl_add_u64 v[166:167], v[166:167], 0, s[24:25]
	s_mov_b32 m0, s60
	ds_read_b128 v[198:201], v174 offset:49152
	ds_read_b128 v[202:205], v174 offset:50176
	ds_read_b128 v[206:209], v174 offset:51200
	ds_read_b128 v[212:215], v174 offset:52224
	ds_read_b128 v[216:219], v174 offset:53248
	ds_read_b128 v[220:223], v174 offset:54272
	ds_read_b128 v[224:227], v174 offset:55296
	ds_read_b128 v[228:231], v174 offset:56320
	global_load_lds_dwordx4 v[166:167], off
	s_add_i32 m0, s60, 0x2000
	s_add_u32 s58, s58, 0x158080
	v_lshl_add_u64 v[166:167], v[176:177], 0, s[24:25]
	s_addc_u32 s59, s59, 0
	s_add_i32 s60, s69, s7
	global_load_lds_dwordx4 v[166:167], off
	v_lshl_add_u64 v[166:167], s[58:59], 0, v[148:149]
	s_mov_b32 m0, s60
	s_nop 0
	global_load_lds_dwordx4 v[166:167], off
	v_lshl_add_u64 v[166:167], s[58:59], 0, v[152:153]
	s_add_i32 m0, s60, 0x2000
	s_nop 0
	global_load_lds_dwordx4 v[166:167], off
	v_lshl_add_u64 v[166:167], v[232:233], 0, s[24:25]
	s_mov_b32 m0, s26
	s_nop 0
	global_load_lds_dwordx4 v[166:167], off
	v_lshl_add_u64 v[166:167], v[234:235], 0, s[24:25]
	s_mov_b32 m0, s27
	s_nop 0
	global_load_lds_dwordx4 v[166:167], off
	s_waitcnt vmcnt(8)
	s_waitcnt lgkmcnt(0)
	s_barrier
	s_setprio 1
	s_waitcnt lgkmcnt(0)
	v_mfma_i32_16x16x64_i8 v[62:65], v[122:125], v[198:201], v[62:65]
	v_mfma_i32_16x16x64_i8 v[62:65], v[126:129], v[202:205], v[62:65]
	v_mfma_i32_16x16x64_i8 v[58:61], v[138:141], v[202:205], v[58:61]
	v_mfma_i32_16x16x64_i8 v[58:61], v[130:133], v[198:201], v[58:61]
	v_mfma_i32_16x16x64_i8 v[42:45], v[130:133], v[206:209], v[42:45]
	v_mfma_i32_16x16x64_i8 v[42:45], v[138:141], v[212:215], v[42:45]
	v_mfma_i32_16x16x64_i8 v[46:49], v[126:129], v[212:215], v[46:49]
	v_mfma_i32_16x16x64_i8 v[46:49], v[122:125], v[206:209], v[46:49]
	v_mfma_i32_16x16x64_i8 v[30:33], v[122:125], v[216:219], v[30:33]
	v_mfma_i32_16x16x64_i8 v[30:33], v[126:129], v[220:223], v[30:33]
	v_mfma_i32_16x16x64_i8 v[26:29], v[138:141], v[220:223], v[26:29]
	v_mfma_i32_16x16x64_i8 v[26:29], v[130:133], v[216:219], v[26:29]
	v_mfma_i32_16x16x64_i8 v[10:13], v[130:133], v[224:227], v[10:13]
	v_mfma_i32_16x16x64_i8 v[10:13], v[138:141], v[228:231], v[10:13]
	v_mfma_i32_16x16x64_i8 v[14:17], v[126:129], v[228:231], v[14:17]
	v_mfma_i32_16x16x64_i8 v[14:17], v[122:125], v[224:227], v[14:17]
	s_setprio 0
	s_setprio 1
	v_mfma_i32_16x16x64_i8 v[54:57], v[182:185], v[198:201], v[54:57]
	v_mfma_i32_16x16x64_i8 v[54:57], v[186:189], v[202:205], v[54:57]
	v_mfma_i32_16x16x64_i8 v[50:53], v[194:197], v[202:205], v[50:53]
	v_mfma_i32_16x16x64_i8 v[50:53], v[190:193], v[198:201], v[50:53]
	v_mfma_i32_16x16x64_i8 v[34:37], v[190:193], v[206:209], v[34:37]
	v_mfma_i32_16x16x64_i8 v[34:37], v[194:197], v[212:215], v[34:37]
	v_mfma_i32_16x16x64_i8 v[38:41], v[186:189], v[212:215], v[38:41]
	v_mfma_i32_16x16x64_i8 v[38:41], v[182:185], v[206:209], v[38:41]
	v_mfma_i32_16x16x64_i8 v[22:25], v[182:185], v[216:219], v[22:25]
	v_mfma_i32_16x16x64_i8 v[22:25], v[186:189], v[220:223], v[22:25]
	v_mfma_i32_16x16x64_i8 v[18:21], v[194:197], v[220:223], v[18:21]
	v_mfma_i32_16x16x64_i8 v[18:21], v[190:193], v[216:219], v[18:21]
	v_mfma_i32_16x16x64_i8 v[2:5], v[190:193], v[224:227], v[2:5]
	v_mfma_i32_16x16x64_i8 v[2:5], v[194:197], v[228:231], v[2:5]
	v_mfma_i32_16x16x64_i8 v[6:9], v[186:189], v[228:231], v[6:9]
	v_mfma_i32_16x16x64_i8 v[6:9], v[182:185], v[224:227], v[6:9]
	s_setprio 0
	s_barrier
	s_add_i32 s67, s67, 2
	s_add_u32 s56, s56, 0x100
	s_addc_u32 s57, s57, 0
	s_add_u32 s65, s65, 0x100
	s_addc_u32 s66, s66, 0
	s_cmpk_gt_u32 s67, 0x53
	s_cbranch_scc0 .LBB0_1020
	s_and_b64 vcc, exec, s[36:37]
	s_cbranch_vccz .LBB0_1023
	s_barrier

; #define PG8_STAGE(bufoff, gbase, voff) do { _Pragma("unroll") for (int _i = 0; _i < 2; ++_i) \
;         __builtin_amdgcn_global_load_lds((const unsigned*)((const char*)(gbase) + (voff)[_i]), (PG8_LAS unsigned*)(lds + (bufoff) + ldsw + _i * 8192), 16, 0, 0); } while (0)
; #define PG8_LDA(dst, b, h) do { _Pragma("unroll") for (int m = 0; m < 4; ++m) _Pragma("unroll") for (int k = 0; k < 2; ++k) dst[m][k] = *(const PG8_LAS bf16x8*)(lds + PG8_SA(b, h) + aoff + m * 2048 + k * 1024); } while (0)
; #define PG8_LDB(dst, b, h) do { _Pragma("unroll") for (int n = 0; n < 2; ++n) _Pragma("unroll") for (int k = 0; k < 2; ++k) dst[n][k] = *(const PG8_LAS bf16x8*)(lds + PG8_SB(b, h) + boff + n * 2048 + k * 1024); } while (0)
; #define PG8_MMA(ai, bj, At, Bt) do { __builtin_amdgcn_s_setprio(1); _Pragma("unroll") for (int m = 0; m < 4; ++m) _Pragma("unroll") for (int n = 0; n < 2; ++n) _Pragma("unroll") for (int k = 0; k < 2; ++k) \
;         acc[ai][bj][m][n] = mma16(Bt[n][k], At[m][k], acc[ai][bj][m][n]); __builtin_amdgcn_s_setprio(0); } while (0)
; #define PG8_WAIT_V(n) asm volatile("s_waitcnt vmcnt(" #n ")" ::: "memory")
; #define PG8_WAIT_L(n) asm volatile("s_waitcnt lgkmcnt(" #n ")" ::: "memory")
; template <class Epi, class Sched, bool ALIGN_EPI = false, bool SP2 = false>
; __device__ __forceinline__ void gemm_phase(PG8_LAS unsigned char* lds, const Gemm g, const Sched& S, const Epi& E) {
;     ...
;         for (int t = 0; t < nt; t += 2) {
;             const bool last = (t == nt - 2);
;             const char* a1 = cA + (size_t)(t + 1) * kstep;
;             const char* a2 = last ? nA : cA + (size_t)(t + 2) * kstep; const char* b2 = last ? nB : cB + (size_t)(t + 2) * kstep;
;             const char* a3 = a2 + kstep; const char* b3 = b2 + kstep;
;             if (last && has_next) S.a_ready(nxt);
;             if constexpr (SP2) {
;             PG8_LDB(B0, 0, 0); PG8_LDB(B1, 0, 1); PG8_SCHED; PG8_LDA(At, 0, 0); PG8_STAGE(PG8_SA(1, 1), a1 + hstepA, voffA);
;             PG8_WAIT_V(8); PG8_WAIT_L(0); PG8_BAR; PG8_MMA(0, 0, At, B0); PG8_MMA(0, 1, At, B1); PG8_BAR; PG8_SCHED;
;             PG8_LDA(At, 0, 1); PG8_STAGE(PG8_SB(0, 0), b2, voffB); PG8_STAGE(PG8_SB(0, 1), b2 + hstepB, voffB); PG8_STAGE(PG8_SA(0, 0), a2, voffA);
;             PG8_WAIT_V(8); PG8_WAIT_L(0); PG8_BAR; PG8_MMA(1, 0, At, B0); PG8_MMA(1, 1, At, B1); PG8_BAR; PG8_SCHED;
.LBB0_1037:
	ds_read_b128 v[118:121], v167
	ds_read_b128 v[126:129], v167 offset:1024
	ds_read_b128 v[130:133], v167 offset:2048
	ds_read_b128 v[134:137], v167 offset:3072
	ds_read_b128 v[172:175], v168
	ds_read_b128 v[182:185], v168 offset:1024
	ds_read_b128 v[186:189], v168 offset:2048
	ds_read_b128 v[190:193], v168 offset:3072
	s_add_u32 s52, s50, 0xffea8080
	s_addc_u32 s53, s51, -1
	s_cmpk_eq_i32 s71, 0x52
	s_cselect_b32 s55, s47, s53
	s_cselect_b32 s54, s46, s52
	s_cselect_b32 s53, s9, s70
	s_cselect_b32 s52, s8, s45
	s_mov_b32 m0, s35
	v_lshl_add_u64 v[162:163], s[50:51], 0, v[158:159]
	ds_read_b128 v[194:197], v169
	ds_read_b128 v[198:201], v169 offset:1024
	ds_read_b128 v[202:205], v169 offset:2048
	ds_read_b128 v[206:209], v169 offset:3072
	ds_read_b128 v[212:215], v169 offset:4096
	ds_read_b128 v[216:219], v169 offset:5120
	ds_read_b128 v[220:223], v169 offset:6144
	ds_read_b128 v[224:227], v169 offset:7168
	global_load_lds_dwordx4 v[162:163], off
	v_lshl_add_u64 v[162:163], s[50:51], 0, v[160:161]
	s_mov_b32 m0, s56
	s_nop 0
	global_load_lds_dwordx4 v[162:163], off
	s_waitcnt vmcnt(8)
	s_waitcnt lgkmcnt(0)
	s_barrier
	s_setprio 1
	s_waitcnt lgkmcnt(0)
	v_mfma_i32_16x16x64_i8 v[142:145], v[118:121], v[194:197], v[142:145]
	v_mfma_i32_16x16x64_i8 v[142:145], v[126:129], v[198:201], v[142:145]
	v_mfma_i32_16x16x64_i8 v[138:141], v[134:137], v[198:201], v[138:141]
	v_mfma_i32_16x16x64_i8 v[138:141], v[130:133], v[194:197], v[138:141]
	v_mfma_i32_16x16x64_i8 v[106:109], v[130:133], v[202:205], v[106:109]
	v_mfma_i32_16x16x64_i8 v[106:109], v[134:137], v[206:209], v[106:109]
	v_mfma_i32_16x16x64_i8 v[110:113], v[126:129], v[206:209], v[110:113]
	v_mfma_i32_16x16x64_i8 v[110:113], v[118:121], v[202:205], v[110:113]
	v_mfma_i32_16x16x64_i8 v[94:97], v[118:121], v[212:215], v[94:97]
	v_mfma_i32_16x16x64_i8 v[94:97], v[126:129], v[216:219], v[94:97]
	v_mfma_i32_16x16x64_i8 v[90:93], v[134:137], v[216:219], v[90:93]
	v_mfma_i32_16x16x64_i8 v[90:93], v[130:133], v[212:215], v[90:93]
	v_mfma_i32_16x16x64_i8 v[74:77], v[130:133], v[220:223], v[74:77]
	v_mfma_i32_16x16x64_i8 v[74:77], v[134:137], v[224:227], v[74:77]
	v_mfma_i32_16x16x64_i8 v[78:81], v[126:129], v[224:227], v[78:81]
	v_mfma_i32_16x16x64_i8 v[78:81], v[118:121], v[220:223], v[78:81]
	s_setprio 0
	s_setprio 1
	v_mfma_i32_16x16x64_i8 v[122:125], v[172:175], v[194:197], v[122:125]
	v_mfma_i32_16x16x64_i8 v[122:125], v[182:185], v[198:201], v[122:125]
	v_mfma_i32_16x16x64_i8 v[114:117], v[190:193], v[198:201], v[114:117]
	v_mfma_i32_16x16x64_i8 v[114:117], v[186:189], v[194:197], v[114:117]
	v_mfma_i32_16x16x64_i8 v[98:101], v[186:189], v[202:205], v[98:101]
	v_mfma_i32_16x16x64_i8 v[98:101], v[190:193], v[206:209], v[98:101]
	v_mfma_i32_16x16x64_i8 v[102:105], v[182:185], v[206:209], v[102:105]
	v_mfma_i32_16x16x64_i8 v[102:105], v[172:175], v[202:205], v[102:105]
	v_mfma_i32_16x16x64_i8 v[86:89], v[172:175], v[212:215], v[86:89]
	v_mfma_i32_16x16x64_i8 v[86:89], v[182:185], v[216:219], v[86:89]
	v_mfma_i32_16x16x64_i8 v[82:85], v[190:193], v[216:219], v[82:85]
	v_mfma_i32_16x16x64_i8 v[82:85], v[186:189], v[212:215], v[82:85]
	v_mfma_i32_16x16x64_i8 v[66:69], v[186:189], v[220:223], v[66:69]
	v_mfma_i32_16x16x64_i8 v[66:69], v[190:193], v[224:227], v[66:69]
	v_mfma_i32_16x16x64_i8 v[70:73], v[182:185], v[224:227], v[70:73]
	v_mfma_i32_16x16x64_i8 v[70:73], v[172:175], v[220:223], v[70:73]
	s_setprio 0
	s_barrier
	s_mov_b32 m0, s57
	v_lshl_add_u64 v[162:163], s[52:53], 0, v[150:151]
	s_add_u32 s74, s52, 0x158000
	ds_read_b128 v[194:197], v169 offset:16384
	ds_read_b128 v[198:201], v169 offset:17408
	ds_read_b128 v[202:205], v169 offset:18432
	ds_read_b128 v[206:209], v169 offset:19456
	ds_read_b128 v[212:215], v169 offset:20480
	ds_read_b128 v[216:219], v169 offset:21504
	ds_read_b128 v[220:223], v169 offset:22528
	ds_read_b128 v[224:227], v169 offset:23552
	global_load_lds_dwordx4 v[162:163], off
	v_lshl_add_u64 v[176:177], s[52:53], 0, v[146:147]
	s_mov_b32 m0, s58
	s_addc_u32 s75, s53, 0
	global_load_lds_dwordx4 v[176:177], off
	v_lshl_add_u64 v[228:229], s[74:75], 0, v[150:151]
	s_mov_b32 m0, s63
	v_lshl_add_u64 v[230:231], s[54:55], 0, v[148:149]
	global_load_lds_dwordx4 v[228:229], off
	v_lshl_add_u64 v[228:229], s[74:75], 0, v[146:147]
	s_mov_b32 m0, s64
	s_nop 0
	global_load_lds_dwordx4 v[228:229], off
	v_lshl_add_u64 v[228:229], s[54:55], 0, v[152:153]
	s_mov_b32 m0, s5
	s_nop 0
	global_load_lds_dwordx4 v[228:229], off
	s_mov_b32 m0, s6
	s_nop 0
	global_load_lds_dwordx4 v[230:231], off
	s_waitcnt vmcnt(8)
	s_waitcnt lgkmcnt(0)
	s_barrier
; #define PG8_STAGE(bufoff, gbase, voff) do { _Pragma("unroll") for (int _i = 0; _i < 2; ++_i) \
;         __builtin_amdgcn_global_load_lds((const unsigned*)((const char*)(gbase) + (voff)[_i]), (PG8_LAS unsigned*)(lds + (bufoff) + ldsw + _i * 8192), 16, 0, 0); } while (0)
; #define PG8_LDA(dst, b, h) do { _Pragma("unroll") for (int m = 0; m < 4; ++m) _Pragma("unroll") for (int k = 0; k < 2; ++k) dst[m][k] = *(const PG8_LAS bf16x8*)(lds + PG8_SA(b, h) + aoff + m * 2048 + k * 1024); } while (0)
; #define PG8_LDB(dst, b, h) do { _Pragma("unroll") for (int n = 0; n < 2; ++n) _Pragma("unroll") for (int k = 0; k < 2; ++k) dst[n][k] = *(const PG8_LAS bf16x8*)(lds + PG8_SB(b, h) + boff + n * 2048 + k * 1024); } while (0)
; #define PG8_MMA(ai, bj, At, Bt) do { __builtin_amdgcn_s_setprio(1); _Pragma("unroll") for (int m = 0; m < 4; ++m) _Pragma("unroll") for (int n = 0; n < 2; ++n) _Pragma("unroll") for (int k = 0; k < 2; ++k) \
;         acc[ai][bj][m][n] = mma16(Bt[n][k], At[m][k], acc[ai][bj][m][n]); __builtin_amdgcn_s_setprio(0); } while (0)
; #define PG8_WAIT_V(n) asm volatile("s_waitcnt vmcnt(" #n ")" ::: "memory")
; #define PG8_WAIT_L(n) asm volatile("s_waitcnt lgkmcnt(" #n ")" ::: "memory")
; #define PG8_BAR __builtin_amdgcn_s_barrier()
; #define PG8_SCHED __builtin_amdgcn_sched_barrier(0)
; template <class Epi, class Sched, bool ALIGN_EPI = false, bool SP2 = false>
; __device__ __forceinline__ void gemm_phase(PG8_LAS unsigned char* lds, const Gemm g, const Sched& S, const Epi& E) {
;     ...
;             PG8_WAIT_V(8); PG8_WAIT_L(0); PG8_BAR; PG8_MMA(1, 0, At, B0); PG8_MMA(1, 1, At, B1); PG8_BAR; PG8_SCHED;
;             PG8_LDB(B0, 1, 0); PG8_LDB(B1, 1, 1); PG8_SCHED; PG8_LDA(At, 1, 0); PG8_STAGE(PG8_SA(0, 1), a2 + hstepA, voffA);
;             PG8_WAIT_V(8); PG8_WAIT_L(0); PG8_BAR; PG8_MMA(0, 0, At, B0); PG8_MMA(0, 1, At, B1); PG8_BAR; PG8_SCHED;
;             PG8_LDA(At, 1, 1); PG8_STAGE(PG8_SB(1, 0), b3, voffB); PG8_STAGE(PG8_SB(1, 1), b3 + hstepB, voffB); PG8_STAGE(PG8_SA(1, 0), a3, voffA);
	s_setprio 1
	s_waitcnt lgkmcnt(0)
	v_mfma_i32_16x16x64_i8 v[62:65], v[118:121], v[194:197], v[62:65]
	v_mfma_i32_16x16x64_i8 v[62:65], v[126:129], v[198:201], v[62:65]
	v_mfma_i32_16x16x64_i8 v[58:61], v[134:137], v[198:201], v[58:61]
	v_mfma_i32_16x16x64_i8 v[58:61], v[130:133], v[194:197], v[58:61]
	v_mfma_i32_16x16x64_i8 v[42:45], v[130:133], v[202:205], v[42:45]
	v_mfma_i32_16x16x64_i8 v[42:45], v[134:137], v[206:209], v[42:45]
	v_mfma_i32_16x16x64_i8 v[46:49], v[126:129], v[206:209], v[46:49]
	v_mfma_i32_16x16x64_i8 v[46:49], v[118:121], v[202:205], v[46:49]
	v_mfma_i32_16x16x64_i8 v[30:33], v[118:121], v[212:215], v[30:33]
	v_mfma_i32_16x16x64_i8 v[30:33], v[126:129], v[216:219], v[30:33]
	v_mfma_i32_16x16x64_i8 v[26:29], v[134:137], v[216:219], v[26:29]
	v_mfma_i32_16x16x64_i8 v[26:29], v[130:133], v[212:215], v[26:29]
	v_mfma_i32_16x16x64_i8 v[10:13], v[130:133], v[220:223], v[10:13]
	v_mfma_i32_16x16x64_i8 v[10:13], v[134:137], v[224:227], v[10:13]
	v_mfma_i32_16x16x64_i8 v[14:17], v[126:129], v[224:227], v[14:17]
	v_mfma_i32_16x16x64_i8 v[14:17], v[118:121], v[220:223], v[14:17]
	s_setprio 0
	s_setprio 1
	v_mfma_i32_16x16x64_i8 v[54:57], v[172:175], v[194:197], v[54:57]
	v_mfma_i32_16x16x64_i8 v[54:57], v[182:185], v[198:201], v[54:57]
	v_mfma_i32_16x16x64_i8 v[50:53], v[190:193], v[198:201], v[50:53]
	v_mfma_i32_16x16x64_i8 v[50:53], v[186:189], v[194:197], v[50:53]
	v_mfma_i32_16x16x64_i8 v[34:37], v[186:189], v[202:205], v[34:37]
	v_mfma_i32_16x16x64_i8 v[34:37], v[190:193], v[206:209], v[34:37]
	v_mfma_i32_16x16x64_i8 v[38:41], v[182:185], v[206:209], v[38:41]
	v_mfma_i32_16x16x64_i8 v[38:41], v[172:175], v[202:205], v[38:41]
	v_mfma_i32_16x16x64_i8 v[22:25], v[172:175], v[212:215], v[22:25]
	v_mfma_i32_16x16x64_i8 v[22:25], v[182:185], v[216:219], v[22:25]
	v_mfma_i32_16x16x64_i8 v[18:21], v[190:193], v[216:219], v[18:21]
	v_mfma_i32_16x16x64_i8 v[18:21], v[186:189], v[212:215], v[18:21]
	v_mfma_i32_16x16x64_i8 v[2:5], v[186:189], v[220:223], v[2:5]
	v_mfma_i32_16x16x64_i8 v[2:5], v[190:193], v[224:227], v[2:5]
	v_mfma_i32_16x16x64_i8 v[6:9], v[182:185], v[224:227], v[6:9]
	v_mfma_i32_16x16x64_i8 v[6:9], v[172:175], v[220:223], v[6:9]
	s_setprio 0
	s_barrier
	ds_read_b128 v[118:121], v170
	ds_read_b128 v[126:129], v170 offset:1024
	ds_read_b128 v[130:133], v170 offset:2048
	ds_read_b128 v[134:137], v170 offset:3072
	ds_read_b128 v[172:175], v171
	ds_read_b128 v[182:185], v171 offset:1024
	ds_read_b128 v[186:189], v171 offset:2048
	ds_read_b128 v[190:193], v171 offset:3072
	s_add_u32 s54, s54, 0x158000
	s_addc_u32 s55, s55, 0
	s_mov_b32 m0, s7
	v_lshl_add_u64 v[232:233], s[54:55], 0, v[152:153]
	ds_read_b128 v[194:197], v169 offset:32768
	ds_read_b128 v[198:201], v169 offset:33792
	ds_read_b128 v[202:205], v169 offset:34816
	ds_read_b128 v[206:209], v169 offset:35840
	ds_read_b128 v[212:215], v169 offset:36864
	ds_read_b128 v[216:219], v169 offset:37888
	ds_read_b128 v[220:223], v169 offset:38912
	ds_read_b128 v[224:227], v169 offset:39936
	global_load_lds_dwordx4 v[232:233], off
	v_lshl_add_u64 v[232:233], s[54:55], 0, v[148:149]
	s_mov_b32 m0, s11
	s_nop 0
	global_load_lds_dwordx4 v[232:233], off
	s_waitcnt vmcnt(8)
	s_waitcnt lgkmcnt(0)
	s_barrier
	s_setprio 1
	s_waitcnt lgkmcnt(0)
	v_mfma_i32_16x16x64_i8 v[142:145], v[118:121], v[194:197], v[142:145]
	v_mfma_i32_16x16x64_i8 v[142:145], v[126:129], v[198:201], v[142:145]
	v_mfma_i32_16x16x64_i8 v[138:141], v[134:137], v[198:201], v[138:141]
	v_mfma_i32_16x16x64_i8 v[138:141], v[130:133], v[194:197], v[138:141]
	v_mfma_i32_16x16x64_i8 v[106:109], v[130:133], v[202:205], v[106:109]
	v_mfma_i32_16x16x64_i8 v[106:109], v[134:137], v[206:209], v[106:109]
	v_mfma_i32_16x16x64_i8 v[110:113], v[126:129], v[206:209], v[110:113]
	v_mfma_i32_16x16x64_i8 v[110:113], v[118:121], v[202:205], v[110:113]
	v_mfma_i32_16x16x64_i8 v[94:97], v[118:121], v[212:215], v[94:97]
	v_mfma_i32_16x16x64_i8 v[94:97], v[126:129], v[216:219], v[94:97]
	v_mfma_i32_16x16x64_i8 v[90:93], v[134:137], v[216:219], v[90:93]
	v_mfma_i32_16x16x64_i8 v[90:93], v[130:133], v[212:215], v[90:93]
	v_mfma_i32_16x16x64_i8 v[74:77], v[130:133], v[220:223], v[74:77]
	v_mfma_i32_16x16x64_i8 v[74:77], v[134:137], v[224:227], v[74:77]
	v_mfma_i32_16x16x64_i8 v[78:81], v[126:129], v[224:227], v[78:81]
	v_mfma_i32_16x16x64_i8 v[78:81], v[118:121], v[220:223], v[78:81]
	s_setprio 0
	s_setprio 1
	v_mfma_i32_16x16x64_i8 v[122:125], v[172:175], v[194:197], v[122:125]
	v_mfma_i32_16x16x64_i8 v[122:125], v[182:185], v[198:201], v[122:125]
	v_mfma_i32_16x16x64_i8 v[114:117], v[190:193], v[198:201], v[114:117]
	v_mfma_i32_16x16x64_i8 v[114:117], v[186:189], v[194:197], v[114:117]
	v_mfma_i32_16x16x64_i8 v[98:101], v[186:189], v[202:205], v[98:101]
	v_mfma_i32_16x16x64_i8 v[98:101], v[190:193], v[206:209], v[98:101]
	v_mfma_i32_16x16x64_i8 v[102:105], v[182:185], v[206:209], v[102:105]
	v_mfma_i32_16x16x64_i8 v[102:105], v[172:175], v[202:205], v[102:105]
	v_mfma_i32_16x16x64_i8 v[86:89], v[172:175], v[212:215], v[86:89]
	v_mfma_i32_16x16x64_i8 v[86:89], v[182:185], v[216:219], v[86:89]
	v_mfma_i32_16x16x64_i8 v[82:85], v[190:193], v[216:219], v[82:85]
	v_mfma_i32_16x16x64_i8 v[82:85], v[186:189], v[212:215], v[82:85]
	v_mfma_i32_16x16x64_i8 v[66:69], v[186:189], v[220:223], v[66:69]
	v_mfma_i32_16x16x64_i8 v[66:69], v[190:193], v[224:227], v[66:69]
	v_mfma_i32_16x16x64_i8 v[70:73], v[182:185], v[224:227], v[70:73]
	v_mfma_i32_16x16x64_i8 v[70:73], v[172:175], v[220:223], v[70:73]
	s_setprio 0
	s_barrier
; #define PG8_STAGE(bufoff, gbase, voff) do { _Pragma("unroll") for (int _i = 0; _i < 2; ++_i) \
;         __builtin_amdgcn_global_load_lds((const unsigned*)((const char*)(gbase) + (voff)[_i]), (PG8_LAS unsigned*)(lds + (bufoff) + ldsw + _i * 8192), 16, 0, 0); } while (0)
; #define PG8_LDA(dst, b, h) do { _Pragma("unroll") for (int m = 0; m < 4; ++m) _Pragma("unroll") for (int k = 0; k < 2; ++k) dst[m][k] = *(const PG8_LAS bf16x8*)(lds + PG8_SA(b, h) + aoff + m * 2048 + k * 1024); } while (0)
; #define PG8_MMA(ai, bj, At, Bt) do { __builtin_amdgcn_s_setprio(1); _Pragma("unroll") for (int m = 0; m < 4; ++m) _Pragma("unroll") for (int n = 0; n < 2; ++n) _Pragma("unroll") for (int k = 0; k < 2; ++k) \
;         acc[ai][bj][m][n] = mma16(Bt[n][k], At[m][k], acc[ai][bj][m][n]); __builtin_amdgcn_s_setprio(0); } while (0)
; #define PG8_WAIT_V(n) asm volatile("s_waitcnt vmcnt(" #n ")" ::: "memory")
; #define PG8_WAIT_L(n) asm volatile("s_waitcnt lgkmcnt(" #n ")" ::: "memory")
; #define PG8_BAR __builtin_amdgcn_s_barrier()
; #define PG8_SCHED __builtin_amdgcn_sched_barrier(0)
; template <class Epi, class Sched, bool ALIGN_EPI = false, bool SP2 = false>
; __device__ __forceinline__ void gemm_phase(PG8_LAS unsigned char* lds, const Gemm g, const Sched& S, const Epi& E) {
;     ...
;         for (int t = 0; t < nt; t += 2) {
;             const bool last = (t == nt - 2);
;             const char* a1 = cA + (size_t)(t + 1) * kstep;
;             const char* a2 = last ? nA : cA + (size_t)(t + 2) * kstep; const char* b2 = last ? nB : cB + (size_t)(t + 2) * kstep;
;             const char* a3 = a2 + kstep; const char* b3 = b2 + kstep;
;             if (last && has_next) S.a_ready(nxt);
;     ...
;             PG8_LDA(At, 1, 1); PG8_STAGE(PG8_SB(1, 0), b3, voffB); PG8_STAGE(PG8_SB(1, 1), b3 + hstepB, voffB); PG8_STAGE(PG8_SA(1, 0), a3, voffA);
;             PG8_WAIT_V(8); PG8_WAIT_L(0); PG8_BAR; PG8_MMA(1, 0, At, B0); PG8_MMA(1, 1, At, B1); PG8_BAR; PG8_SCHED;
	s_mov_b32 m0, s65
	v_lshl_add_u64 v[162:163], v[162:163], 0, s[22:23]
	s_add_u32 s52, s52, 0x158080
	ds_read_b128 v[194:197], v169 offset:49152
	ds_read_b128 v[198:201], v169 offset:50176
	ds_read_b128 v[202:205], v169 offset:51200
	ds_read_b128 v[206:209], v169 offset:52224
	ds_read_b128 v[212:215], v169 offset:53248
	ds_read_b128 v[216:219], v169 offset:54272
	ds_read_b128 v[220:223], v169 offset:55296
	ds_read_b128 v[224:227], v169 offset:56320
	global_load_lds_dwordx4 v[162:163], off
	v_lshl_add_u64 v[162:163], v[176:177], 0, s[22:23]
	s_mov_b32 m0, s66
	s_addc_u32 s53, s53, 0
	global_load_lds_dwordx4 v[162:163], off
	v_lshl_add_u64 v[162:163], s[52:53], 0, v[150:151]
	s_mov_b32 m0, s67
	s_nop 0
	global_load_lds_dwordx4 v[162:163], off
	v_lshl_add_u64 v[162:163], s[52:53], 0, v[146:147]
	s_mov_b32 m0, s68
	s_nop 0
	global_load_lds_dwordx4 v[162:163], off
	v_lshl_add_u64 v[162:163], v[228:229], 0, s[22:23]
	s_mov_b32 m0, s26
	s_nop 0
	global_load_lds_dwordx4 v[162:163], off
	v_lshl_add_u64 v[162:163], v[230:231], 0, s[22:23]
	s_mov_b32 m0, s27
	s_nop 0
	global_load_lds_dwordx4 v[162:163], off
	s_waitcnt vmcnt(8)
	s_waitcnt lgkmcnt(0)
	s_barrier
	s_setprio 1
	s_waitcnt lgkmcnt(0)
	v_mfma_i32_16x16x64_i8 v[62:65], v[118:121], v[194:197], v[62:65]
	v_mfma_i32_16x16x64_i8 v[62:65], v[126:129], v[198:201], v[62:65]
	v_mfma_i32_16x16x64_i8 v[58:61], v[134:137], v[198:201], v[58:61]
	v_mfma_i32_16x16x64_i8 v[58:61], v[130:133], v[194:197], v[58:61]
	v_mfma_i32_16x16x64_i8 v[42:45], v[130:133], v[202:205], v[42:45]
	v_mfma_i32_16x16x64_i8 v[42:45], v[134:137], v[206:209], v[42:45]
	v_mfma_i32_16x16x64_i8 v[46:49], v[126:129], v[206:209], v[46:49]
	v_mfma_i32_16x16x64_i8 v[46:49], v[118:121], v[202:205], v[46:49]
	v_mfma_i32_16x16x64_i8 v[30:33], v[118:121], v[212:215], v[30:33]
	v_mfma_i32_16x16x64_i8 v[30:33], v[126:129], v[216:219], v[30:33]
	v_mfma_i32_16x16x64_i8 v[26:29], v[134:137], v[216:219], v[26:29]
	v_mfma_i32_16x16x64_i8 v[26:29], v[130:133], v[212:215], v[26:29]
	v_mfma_i32_16x16x64_i8 v[10:13], v[130:133], v[220:223], v[10:13]
	v_mfma_i32_16x16x64_i8 v[10:13], v[134:137], v[224:227], v[10:13]
	v_mfma_i32_16x16x64_i8 v[14:17], v[126:129], v[224:227], v[14:17]
	v_mfma_i32_16x16x64_i8 v[14:17], v[118:121], v[220:223], v[14:17]
	s_setprio 0
	s_setprio 1
	v_mfma_i32_16x16x64_i8 v[54:57], v[172:175], v[194:197], v[54:57]
	v_mfma_i32_16x16x64_i8 v[54:57], v[182:185], v[198:201], v[54:57]
	v_mfma_i32_16x16x64_i8 v[50:53], v[190:193], v[198:201], v[50:53]
	v_mfma_i32_16x16x64_i8 v[50:53], v[186:189], v[194:197], v[50:53]
	v_mfma_i32_16x16x64_i8 v[34:37], v[186:189], v[202:205], v[34:37]
	v_mfma_i32_16x16x64_i8 v[34:37], v[190:193], v[206:209], v[34:37]
	v_mfma_i32_16x16x64_i8 v[38:41], v[182:185], v[206:209], v[38:41]
	v_mfma_i32_16x16x64_i8 v[38:41], v[172:175], v[202:205], v[38:41]
	v_mfma_i32_16x16x64_i8 v[22:25], v[172:175], v[212:215], v[22:25]
	v_mfma_i32_16x16x64_i8 v[22:25], v[182:185], v[216:219], v[22:25]
	v_mfma_i32_16x16x64_i8 v[18:21], v[190:193], v[216:219], v[18:21]
	v_mfma_i32_16x16x64_i8 v[18:21], v[186:189], v[212:215], v[18:21]
	v_mfma_i32_16x16x64_i8 v[2:5], v[186:189], v[220:223], v[2:5]
	v_mfma_i32_16x16x64_i8 v[2:5], v[190:193], v[224:227], v[2:5]
	v_mfma_i32_16x16x64_i8 v[6:9], v[182:185], v[224:227], v[6:9]
	v_mfma_i32_16x16x64_i8 v[6:9], v[172:175], v[220:223], v[6:9]
	s_setprio 0
	s_barrier
	s_add_i32 s71, s71, 2
	s_add_u32 s50, s50, 0x100
	s_addc_u32 s51, s51, 0
	s_add_u32 s45, s45, 0x100
	s_addc_u32 s70, s70, 0
	s_cmpk_gt_u32 s71, 0x53
	s_cbranch_scc0 .LBB0_1037
	s_and_b64 vcc, exec, s[24:25]
	s_cbranch_vccz .LBB0_1040
	s_barrier
